# GEMM MFMA order: first operand held for 4 MFMAs (k0 over Y0..Y3, k1 over Y3..Y0); accumulator pairs not adjacent
# baseline (speedup 1.0000x reference)
; #define PG8_STAGE(bufoff, gbase, voff) do { if constexpr (!pg8_noload<Epi>::value) { _Pragma("unroll") for (int _i = 0; _i < 2; ++_i) \
;         __builtin_amdgcn_global_load_lds((const unsigned*)((const char*)(gbase) + (size_t)_i * pstep + (voff)[0]), (PG8_LAS unsigned*)(lds + (bufoff) + ldsw + _i * 8192), 16, 0, 0); } } while (0)
; #define PG8_LDA(dst, b, h) do { _Pragma("unroll") for (int m = 0; m < 4; ++m) _Pragma("unroll") for (int k = 0; k < 2; ++k) dst[m][k] = *(const PG8_LAS bf16x8*)(lds + PG8_SA(b, h) + aoff + m * 2048 + k * 1024); } while (0)
; #define PG8_LDB(dst, b, h) do { _Pragma("unroll") for (int n = 0; n < 2; ++n) _Pragma("unroll") for (int k = 0; k < 2; ++k) dst[n][k] = *(const PG8_LAS bf16x8*)(lds + PG8_SB(b, h) + boff + n * 2048 + k * 1024); } while (0)
; #define PG8_MMA(ai, bj, At, Bt) do { __builtin_amdgcn_s_setprio(1); _Pragma("unroll") for (int m = 0; m < 4; ++m) _Pragma("unroll") for (int n = 0; n < 2; ++n) _Pragma("unroll") for (int k = 0; k < 2; ++k) \
;         acc[ai][bj][m][n] = __builtin_amdgcn_mfma_f32_16x16x32_bf16(Bt[n][k], At[m][k], acc[ai][bj][m][n], 0, 0, 0); __builtin_amdgcn_s_setprio(0); } while (0)
; #define PG8_BAR __builtin_amdgcn_s_barrier()
; template <class Epi, class Sched, bool ALIGN_EPI = false, bool SP2 = false, bool ABLK = false>
; __device__ __forceinline__ void gemm_phase(PG8_LAS unsigned char* lds, const Gemm g, const Sched& S, const Epi& E) {
;     ...
;         for (int t = 0; t < nt; t += 2) {
;             const bool last = (t == nt - 2);
;             const char* a1 = cA + (size_t)(t + 1) * kstep;
;             const char* a2 = last ? nA : cA + (size_t)(t + 2) * kstep; const char* b2 = last ? nB : cB + (size_t)(t + 2) * kstepB;
;             const char* a3 = a2 + kstep; const char* b3 = b2 + kstepB;
;             if (last && has_next) S.a_ready(nxt);
;             if constexpr (SP2) {
;             PG8_LDB(B0, 0, 0); PG8_LDB(B1, 0, 1); PG8_SCHED; PG8_LDA(At, 0, 0); PG8_STAGE(PG8_SA(1, 1), a1 + hstep, voffA);
;             PG8_WAIT_V(8); PG8_WAIT_L(0); PG8_BAR; PG8_MMA(0, 0, At, B0); PG8_MMA(0, 1, At, B1); PG8_BAR; PG8_SCHED;
;             PG8_LDA(At, 0, 1); PG8_STAGE(PG8_SB(0, 0), b2, voffB); PG8_STAGE(PG8_SB(0, 1), b2 + hstep, voffB); PG8_STAGE(PG8_SA(0, 0), a2, voffA);
;             PG8_WAIT_V(8); PG8_WAIT_L(0); PG8_BAR; PG8_MMA(1, 0, At, B0); PG8_MMA(1, 1, At, B1); PG8_BAR; PG8_SCHED;
.LBB0_114:
	ds_read_b128 v[144:147], v168
	ds_read_b128 v[184:187], v168 offset:1024
	ds_read_b128 v[188:191], v168 offset:2048
	ds_read_b128 v[192:195], v168 offset:3072
	ds_read_b128 v[196:199], v169
	ds_read_b128 v[200:203], v169 offset:1024
	ds_read_b128 v[204:207], v169 offset:2048
	ds_read_b128 v[208:211], v169 offset:3072
	s_add_u32 s71, vcc_lo, 0xfff80800
	s_addc_u32 s73, vcc_hi, -1
	s_cmp_eq_u32 s70, 28
	s_cselect_b32 s75, s3, s73
	s_cselect_b32 s74, s7, s71
	s_cselect_b32 s77, s21, s17
	s_cselect_b32 s76, s72, s16
	v_lshl_add_u64 v[244:245], vcc, 0, v[136:137]
	s_add_i32 m0, s53, 0xc000
	ds_read_b128 v[212:215], v170
	ds_read_b128 v[216:219], v170 offset:1024
	ds_read_b128 v[220:223], v170 offset:2048
	ds_read_b128 v[224:227], v170 offset:3072
	ds_read_b128 v[228:231], v170 offset:4096
	ds_read_b128 v[232:235], v170 offset:5120
	ds_read_b128 v[236:239], v170 offset:6144
	ds_read_b128 v[240:243], v170 offset:7168
	global_load_lds_dwordx4 v[244:245], off
	v_lshl_add_u64 v[244:245], v[244:245], 0, s[0:1]
	s_add_i32 m0, s53, 0xe000
	s_nop 0
	global_load_lds_dwordx4 v[244:245], off
	s_waitcnt vmcnt(8)
	s_waitcnt lgkmcnt(0)
	s_barrier
	s_setprio 1
	s_waitcnt lgkmcnt(0)
	v_mfma_f32_16x16x32_bf16 v[126:129], v[144:147], v[212:215], v[126:129]
	v_mfma_f32_16x16x32_bf16 v[110:113], v[144:147], v[220:223], v[110:113]
	v_mfma_f32_16x16x32_bf16 v[94:97], v[144:147], v[228:231], v[94:97]
	v_mfma_f32_16x16x32_bf16 v[78:81], v[144:147], v[236:239], v[78:81]
	v_mfma_f32_16x16x32_bf16 v[78:81], v[184:187], v[240:243], v[78:81]
	v_mfma_f32_16x16x32_bf16 v[94:97], v[184:187], v[232:235], v[94:97]
	v_mfma_f32_16x16x32_bf16 v[110:113], v[184:187], v[224:227], v[110:113]
	v_mfma_f32_16x16x32_bf16 v[126:129], v[184:187], v[216:219], v[126:129]
	v_mfma_f32_16x16x32_bf16 v[122:125], v[188:191], v[212:215], v[122:125]
	v_mfma_f32_16x16x32_bf16 v[106:109], v[188:191], v[220:223], v[106:109]
	v_mfma_f32_16x16x32_bf16 v[90:93], v[188:191], v[228:231], v[90:93]
	v_mfma_f32_16x16x32_bf16 v[74:77], v[188:191], v[236:239], v[74:77]
	v_mfma_f32_16x16x32_bf16 v[74:77], v[192:195], v[240:243], v[74:77]
	v_mfma_f32_16x16x32_bf16 v[90:93], v[192:195], v[232:235], v[90:93]
	v_mfma_f32_16x16x32_bf16 v[106:109], v[192:195], v[224:227], v[106:109]
	v_mfma_f32_16x16x32_bf16 v[122:125], v[192:195], v[216:219], v[122:125]
	v_mfma_f32_16x16x32_bf16 v[118:121], v[196:199], v[212:215], v[118:121]
	v_mfma_f32_16x16x32_bf16 v[102:105], v[196:199], v[220:223], v[102:105]
	v_mfma_f32_16x16x32_bf16 v[86:89], v[196:199], v[228:231], v[86:89]
	v_mfma_f32_16x16x32_bf16 v[70:73], v[196:199], v[236:239], v[70:73]
	v_mfma_f32_16x16x32_bf16 v[70:73], v[200:203], v[240:243], v[70:73]
	v_mfma_f32_16x16x32_bf16 v[86:89], v[200:203], v[232:235], v[86:89]
	v_mfma_f32_16x16x32_bf16 v[102:105], v[200:203], v[224:227], v[102:105]
	v_mfma_f32_16x16x32_bf16 v[118:121], v[200:203], v[216:219], v[118:121]
	v_mfma_f32_16x16x32_bf16 v[114:117], v[204:207], v[212:215], v[114:117]
	v_mfma_f32_16x16x32_bf16 v[98:101], v[204:207], v[220:223], v[98:101]
	v_mfma_f32_16x16x32_bf16 v[82:85], v[204:207], v[228:231], v[82:85]
	v_mfma_f32_16x16x32_bf16 v[66:69], v[204:207], v[236:239], v[66:69]
	s_barrier
	s_setprio 2
	v_mfma_f32_16x16x32_bf16 v[66:69], v[208:211], v[240:243], v[66:69]
	v_mfma_f32_16x16x32_bf16 v[82:85], v[208:211], v[232:235], v[82:85]
	v_mfma_f32_16x16x32_bf16 v[98:101], v[208:211], v[224:227], v[98:101]
	v_mfma_f32_16x16x32_bf16 v[114:117], v[208:211], v[216:219], v[114:117]
	s_setprio 0
	s_add_i32 s71, s64, s52
	v_lshl_add_u64 v[244:245], s[76:77], 0, v[130:131]
	s_mov_b32 m0, s71
	ds_read_b128 v[212:215], v170 offset:16384
	ds_read_b128 v[216:219], v170 offset:17408
	ds_read_b128 v[220:223], v170 offset:18432
	ds_read_b128 v[224:227], v170 offset:19456
	ds_read_b128 v[228:231], v170 offset:20480
	ds_read_b128 v[232:235], v170 offset:21504
	ds_read_b128 v[236:239], v170 offset:22528
	ds_read_b128 v[240:243], v170 offset:23552
	global_load_lds_dwordx4 v[244:245], off
	v_lshl_add_u64 v[246:247], v[244:245], 0, s[0:1]
	s_add_i32 m0, s71, 0x2000
	s_add_i32 s71, s65, s52
	global_load_lds_dwordx4 v[246:247], off
	v_lshl_add_u64 v[246:247], v[244:245], 0, s[14:15]
	s_mov_b32 m0, s71
	s_nop 0
	global_load_lds_dwordx4 v[246:247], off
	v_lshl_add_u64 v[246:247], v[244:245], 0, s[18:19]
	s_add_i32 m0, s71, 0x2000
	s_nop 0
	global_load_lds_dwordx4 v[246:247], off
	v_lshl_add_u64 v[246:247], s[74:75], 0, v[130:131]
	s_mov_b32 m0, s53
	v_lshl_add_u64 v[248:249], v[246:247], 0, s[0:1]
	global_load_lds_dwordx4 v[246:247], off
	s_mov_b32 m0, s54
	s_nop 0
	global_load_lds_dwordx4 v[248:249], off
	s_waitcnt vmcnt(8)
	s_waitcnt lgkmcnt(0)
	s_barrier
; #define PG8_STAGE(bufoff, gbase, voff) do { if constexpr (!pg8_noload<Epi>::value) { _Pragma("unroll") for (int _i = 0; _i < 2; ++_i) \
;         __builtin_amdgcn_global_load_lds((const unsigned*)((const char*)(gbase) + (size_t)_i * pstep + (voff)[0]), (PG8_LAS unsigned*)(lds + (bufoff) + ldsw + _i * 8192), 16, 0, 0); } } while (0)
; #define PG8_LDA(dst, b, h) do { _Pragma("unroll") for (int m = 0; m < 4; ++m) _Pragma("unroll") for (int k = 0; k < 2; ++k) dst[m][k] = *(const PG8_LAS bf16x8*)(lds + PG8_SA(b, h) + aoff + m * 2048 + k * 1024); } while (0)
; #define PG8_LDB(dst, b, h) do { _Pragma("unroll") for (int n = 0; n < 2; ++n) _Pragma("unroll") for (int k = 0; k < 2; ++k) dst[n][k] = *(const PG8_LAS bf16x8*)(lds + PG8_SB(b, h) + boff + n * 2048 + k * 1024); } while (0)
; #define PG8_MMA(ai, bj, At, Bt) do { __builtin_amdgcn_s_setprio(1); _Pragma("unroll") for (int m = 0; m < 4; ++m) _Pragma("unroll") for (int n = 0; n < 2; ++n) _Pragma("unroll") for (int k = 0; k < 2; ++k) \
;         acc[ai][bj][m][n] = __builtin_amdgcn_mfma_f32_16x16x32_bf16(Bt[n][k], At[m][k], acc[ai][bj][m][n], 0, 0, 0); __builtin_amdgcn_s_setprio(0); } while (0)
; #define PG8_WAIT_V(n) asm volatile("s_waitcnt vmcnt(" #n ")" ::: "memory")
; #define PG8_WAIT_L(n) asm volatile("s_waitcnt lgkmcnt(" #n ")" ::: "memory")
; #define PG8_BAR __builtin_amdgcn_s_barrier()
; #define PG8_SCHED __builtin_amdgcn_sched_barrier(0)
; template <class Epi, class Sched, bool ALIGN_EPI = false, bool SP2 = false, bool ABLK = false>
; __device__ __forceinline__ void gemm_phase(PG8_LAS unsigned char* lds, const Gemm g, const Sched& S, const Epi& E) {
;     ...
;             PG8_WAIT_V(8); PG8_WAIT_L(0); PG8_BAR; PG8_MMA(1, 0, At, B0); PG8_MMA(1, 1, At, B1); PG8_BAR; PG8_SCHED;
;             PG8_LDB(B0, 1, 0); PG8_LDB(B1, 1, 1); PG8_SCHED; PG8_LDA(At, 1, 0); PG8_STAGE(PG8_SA(0, 1), a2 + hstep, voffA);
;             PG8_WAIT_V(8); PG8_WAIT_L(0); PG8_BAR; PG8_MMA(0, 0, At, B0); PG8_MMA(0, 1, At, B1); PG8_BAR; PG8_SCHED;
;             PG8_LDA(At, 1, 1); PG8_STAGE(PG8_SB(1, 0), b3, voffB); PG8_STAGE(PG8_SB(1, 1), b3 + hstep, voffB); PG8_STAGE(PG8_SA(1, 0), a3, voffA);
	s_setprio 1
	s_waitcnt lgkmcnt(0)
	v_mfma_f32_16x16x32_bf16 v[62:65], v[144:147], v[212:215], v[62:65]
	v_mfma_f32_16x16x32_bf16 v[46:49], v[144:147], v[220:223], v[46:49]
	v_mfma_f32_16x16x32_bf16 v[30:33], v[144:147], v[228:231], v[30:33]
	v_mfma_f32_16x16x32_bf16 v[14:17], v[144:147], v[236:239], v[14:17]
	v_mfma_f32_16x16x32_bf16 v[14:17], v[184:187], v[240:243], v[14:17]
	v_mfma_f32_16x16x32_bf16 v[30:33], v[184:187], v[232:235], v[30:33]
	v_mfma_f32_16x16x32_bf16 v[46:49], v[184:187], v[224:227], v[46:49]
	v_mfma_f32_16x16x32_bf16 v[62:65], v[184:187], v[216:219], v[62:65]
	v_mfma_f32_16x16x32_bf16 v[58:61], v[188:191], v[212:215], v[58:61]
	v_mfma_f32_16x16x32_bf16 v[42:45], v[188:191], v[220:223], v[42:45]
	v_mfma_f32_16x16x32_bf16 v[26:29], v[188:191], v[228:231], v[26:29]
	v_mfma_f32_16x16x32_bf16 v[10:13], v[188:191], v[236:239], v[10:13]
	v_mfma_f32_16x16x32_bf16 v[10:13], v[192:195], v[240:243], v[10:13]
	v_mfma_f32_16x16x32_bf16 v[26:29], v[192:195], v[232:235], v[26:29]
	v_mfma_f32_16x16x32_bf16 v[42:45], v[192:195], v[224:227], v[42:45]
	v_mfma_f32_16x16x32_bf16 v[58:61], v[192:195], v[216:219], v[58:61]
	v_mfma_f32_16x16x32_bf16 v[54:57], v[196:199], v[212:215], v[54:57]
	v_mfma_f32_16x16x32_bf16 v[38:41], v[196:199], v[220:223], v[38:41]
	v_mfma_f32_16x16x32_bf16 v[22:25], v[196:199], v[228:231], v[22:25]
	v_mfma_f32_16x16x32_bf16 v[6:9], v[196:199], v[236:239], v[6:9]
	v_mfma_f32_16x16x32_bf16 v[6:9], v[200:203], v[240:243], v[6:9]
	v_mfma_f32_16x16x32_bf16 v[22:25], v[200:203], v[232:235], v[22:25]
	v_mfma_f32_16x16x32_bf16 v[38:41], v[200:203], v[224:227], v[38:41]
	v_mfma_f32_16x16x32_bf16 v[54:57], v[200:203], v[216:219], v[54:57]
	v_mfma_f32_16x16x32_bf16 v[50:53], v[204:207], v[212:215], v[50:53]
	v_mfma_f32_16x16x32_bf16 v[34:37], v[204:207], v[220:223], v[34:37]
	v_mfma_f32_16x16x32_bf16 v[18:21], v[204:207], v[228:231], v[18:21]
	v_mfma_f32_16x16x32_bf16 v[2:5], v[204:207], v[236:239], v[2:5]
	s_barrier
	s_setprio 2
	v_mfma_f32_16x16x32_bf16 v[2:5], v[208:211], v[240:243], v[2:5]
	v_mfma_f32_16x16x32_bf16 v[18:21], v[208:211], v[232:235], v[18:21]
	v_mfma_f32_16x16x32_bf16 v[34:37], v[208:211], v[224:227], v[34:37]
	v_mfma_f32_16x16x32_bf16 v[50:53], v[208:211], v[216:219], v[50:53]
	s_setprio 0
	s_add_i32 s71, 0, 0x18000
	v_add_u32_e32 v133, s71, v149
	s_add_i32 s73, 0, 0x1c000
	ds_read_b128 v[144:147], v133
	ds_read_b128 v[184:187], v133 offset:1024
	ds_read_b128 v[188:191], v133 offset:2048
	ds_read_b128 v[192:195], v133 offset:3072
	v_add_u32_e32 v133, s73, v149
	ds_read_b128 v[196:199], v133
	ds_read_b128 v[200:203], v133 offset:1024
	ds_read_b128 v[204:207], v133 offset:2048
	ds_read_b128 v[208:211], v133 offset:3072
	s_mov_b32 m0, s55
	v_lshl_add_u64 v[248:249], v[246:247], 0, s[14:15]
	ds_read_b128 v[212:215], v170 offset:32768
	ds_read_b128 v[216:219], v170 offset:33792
	ds_read_b128 v[220:223], v170 offset:34816
	ds_read_b128 v[224:227], v170 offset:35840
	ds_read_b128 v[228:231], v170 offset:36864
	ds_read_b128 v[232:235], v170 offset:37888
	ds_read_b128 v[236:239], v170 offset:38912
	ds_read_b128 v[240:243], v170 offset:39936
	global_load_lds_dwordx4 v[248:249], off
	v_lshl_add_u64 v[248:249], v[246:247], 0, s[18:19]
	s_mov_b32 m0, s56
	s_nop 0
	global_load_lds_dwordx4 v[248:249], off
	s_waitcnt vmcnt(8)
	s_waitcnt lgkmcnt(0)
	s_barrier
	s_setprio 1
	s_waitcnt lgkmcnt(0)
	v_mfma_f32_16x16x32_bf16 v[126:129], v[144:147], v[212:215], v[126:129]
	v_mfma_f32_16x16x32_bf16 v[110:113], v[144:147], v[220:223], v[110:113]
	v_mfma_f32_16x16x32_bf16 v[94:97], v[144:147], v[228:231], v[94:97]
	v_mfma_f32_16x16x32_bf16 v[78:81], v[144:147], v[236:239], v[78:81]
	v_mfma_f32_16x16x32_bf16 v[78:81], v[184:187], v[240:243], v[78:81]
	v_mfma_f32_16x16x32_bf16 v[94:97], v[184:187], v[232:235], v[94:97]
	v_mfma_f32_16x16x32_bf16 v[110:113], v[184:187], v[224:227], v[110:113]
	v_mfma_f32_16x16x32_bf16 v[126:129], v[184:187], v[216:219], v[126:129]
	v_mfma_f32_16x16x32_bf16 v[122:125], v[188:191], v[212:215], v[122:125]
	v_mfma_f32_16x16x32_bf16 v[106:109], v[188:191], v[220:223], v[106:109]
	v_mfma_f32_16x16x32_bf16 v[90:93], v[188:191], v[228:231], v[90:93]
	v_mfma_f32_16x16x32_bf16 v[74:77], v[188:191], v[236:239], v[74:77]
	v_mfma_f32_16x16x32_bf16 v[74:77], v[192:195], v[240:243], v[74:77]
	v_mfma_f32_16x16x32_bf16 v[90:93], v[192:195], v[232:235], v[90:93]
	v_mfma_f32_16x16x32_bf16 v[106:109], v[192:195], v[224:227], v[106:109]
	v_mfma_f32_16x16x32_bf16 v[122:125], v[192:195], v[216:219], v[122:125]
	v_mfma_f32_16x16x32_bf16 v[118:121], v[196:199], v[212:215], v[118:121]
	v_mfma_f32_16x16x32_bf16 v[102:105], v[196:199], v[220:223], v[102:105]
	v_mfma_f32_16x16x32_bf16 v[86:89], v[196:199], v[228:231], v[86:89]
	v_mfma_f32_16x16x32_bf16 v[70:73], v[196:199], v[236:239], v[70:73]
	v_mfma_f32_16x16x32_bf16 v[70:73], v[200:203], v[240:243], v[70:73]
	v_mfma_f32_16x16x32_bf16 v[86:89], v[200:203], v[232:235], v[86:89]
	v_mfma_f32_16x16x32_bf16 v[102:105], v[200:203], v[224:227], v[102:105]
	v_mfma_f32_16x16x32_bf16 v[118:121], v[200:203], v[216:219], v[118:121]
	v_mfma_f32_16x16x32_bf16 v[114:117], v[204:207], v[212:215], v[114:117]
	v_mfma_f32_16x16x32_bf16 v[98:101], v[204:207], v[220:223], v[98:101]
	v_mfma_f32_16x16x32_bf16 v[82:85], v[204:207], v[228:231], v[82:85]
	v_mfma_f32_16x16x32_bf16 v[66:69], v[204:207], v[236:239], v[66:69]
	s_barrier
; #define PG8_STAGE(bufoff, gbase, voff) do { if constexpr (!pg8_noload<Epi>::value) { _Pragma("unroll") for (int _i = 0; _i < 2; ++_i) \
;         __builtin_amdgcn_global_load_lds((const unsigned*)((const char*)(gbase) + (size_t)_i * pstep + (voff)[0]), (PG8_LAS unsigned*)(lds + (bufoff) + ldsw + _i * 8192), 16, 0, 0); } } while (0)
; #define PG8_LDA(dst, b, h) do { _Pragma("unroll") for (int m = 0; m < 4; ++m) _Pragma("unroll") for (int k = 0; k < 2; ++k) dst[m][k] = *(const PG8_LAS bf16x8*)(lds + PG8_SA(b, h) + aoff + m * 2048 + k * 1024); } while (0)
; #define PG8_MMA(ai, bj, At, Bt) do { __builtin_amdgcn_s_setprio(1); _Pragma("unroll") for (int m = 0; m < 4; ++m) _Pragma("unroll") for (int n = 0; n < 2; ++n) _Pragma("unroll") for (int k = 0; k < 2; ++k) \
;         acc[ai][bj][m][n] = __builtin_amdgcn_mfma_f32_16x16x32_bf16(Bt[n][k], At[m][k], acc[ai][bj][m][n], 0, 0, 0); __builtin_amdgcn_s_setprio(0); } while (0)
; #define PG8_WAIT_V(n) asm volatile("s_waitcnt vmcnt(" #n ")" ::: "memory")
; #define PG8_WAIT_L(n) asm volatile("s_waitcnt lgkmcnt(" #n ")" ::: "memory")
; #define PG8_BAR __builtin_amdgcn_s_barrier()
; #define PG8_SCHED __builtin_amdgcn_sched_barrier(0)
; template <class Epi, class Sched, bool ALIGN_EPI = false, bool SP2 = false, bool ABLK = false>
; __device__ __forceinline__ void gemm_phase(PG8_LAS unsigned char* lds, const Gemm g, const Sched& S, const Epi& E) {
;     ...
;             PG8_WAIT_V(8); PG8_WAIT_L(0); PG8_BAR; PG8_MMA(0, 0, At, B0); PG8_MMA(0, 1, At, B1); PG8_BAR; PG8_SCHED;
;             PG8_LDA(At, 1, 1); PG8_STAGE(PG8_SB(1, 0), b3, voffB); PG8_STAGE(PG8_SB(1, 1), b3 + hstep, voffB); PG8_STAGE(PG8_SA(1, 0), a3, voffA);
;             PG8_WAIT_V(8); PG8_WAIT_L(0); PG8_BAR; PG8_MMA(1, 0, At, B0); PG8_MMA(1, 1, At, B1); PG8_BAR; PG8_SCHED;
	s_setprio 2
	v_mfma_f32_16x16x32_bf16 v[66:69], v[208:211], v[240:243], v[66:69]
	v_mfma_f32_16x16x32_bf16 v[82:85], v[208:211], v[232:235], v[82:85]
	v_mfma_f32_16x16x32_bf16 v[98:101], v[208:211], v[224:227], v[98:101]
	v_mfma_f32_16x16x32_bf16 v[114:117], v[208:211], v[216:219], v[114:117]
	s_setprio 0
	s_add_i32 s71, s71, s52
	v_lshl_add_u64 v[248:249], v[244:245], 0, s[28:29]
	s_mov_b32 m0, s71
	ds_read_b128 v[212:215], v170 offset:49152
	ds_read_b128 v[216:219], v170 offset:50176
	ds_read_b128 v[220:223], v170 offset:51200
	ds_read_b128 v[224:227], v170 offset:52224
	ds_read_b128 v[228:231], v170 offset:53248
	ds_read_b128 v[232:235], v170 offset:54272
	ds_read_b128 v[236:239], v170 offset:55296
	ds_read_b128 v[240:243], v170 offset:56320
	global_load_lds_dwordx4 v[248:249], off
	v_lshl_add_u64 v[248:249], v[244:245], 0, s[30:31]
	s_add_i32 m0, s71, 0x2000
	s_add_i32 s71, s73, s52
	global_load_lds_dwordx4 v[248:249], off
	v_lshl_add_u64 v[248:249], v[244:245], 0, s[34:35]
	s_mov_b32 m0, s71
	v_lshl_add_u64 v[244:245], v[244:245], 0, s[36:37]
	global_load_lds_dwordx4 v[248:249], off
	s_add_i32 m0, s71, 0x2000
	s_nop 0
	global_load_lds_dwordx4 v[244:245], off
	v_lshl_add_u64 v[244:245], v[246:247], 0, s[28:29]
	s_mov_b32 m0, s59
	s_nop 0
	global_load_lds_dwordx4 v[244:245], off
	v_lshl_add_u64 v[244:245], v[246:247], 0, s[30:31]
	s_mov_b32 m0, s60
	s_nop 0
	global_load_lds_dwordx4 v[244:245], off
	s_waitcnt vmcnt(8)
	s_waitcnt lgkmcnt(0)
	s_barrier
	s_setprio 1
	s_waitcnt lgkmcnt(0)
	v_mfma_f32_16x16x32_bf16 v[62:65], v[144:147], v[212:215], v[62:65]
	v_mfma_f32_16x16x32_bf16 v[46:49], v[144:147], v[220:223], v[46:49]
	v_mfma_f32_16x16x32_bf16 v[30:33], v[144:147], v[228:231], v[30:33]
	v_mfma_f32_16x16x32_bf16 v[14:17], v[144:147], v[236:239], v[14:17]
	v_mfma_f32_16x16x32_bf16 v[14:17], v[184:187], v[240:243], v[14:17]
	v_mfma_f32_16x16x32_bf16 v[30:33], v[184:187], v[232:235], v[30:33]
	v_mfma_f32_16x16x32_bf16 v[46:49], v[184:187], v[224:227], v[46:49]
	v_mfma_f32_16x16x32_bf16 v[62:65], v[184:187], v[216:219], v[62:65]
	v_mfma_f32_16x16x32_bf16 v[58:61], v[188:191], v[212:215], v[58:61]
	v_mfma_f32_16x16x32_bf16 v[42:45], v[188:191], v[220:223], v[42:45]
	v_mfma_f32_16x16x32_bf16 v[26:29], v[188:191], v[228:231], v[26:29]
	v_mfma_f32_16x16x32_bf16 v[10:13], v[188:191], v[236:239], v[10:13]
	v_mfma_f32_16x16x32_bf16 v[10:13], v[192:195], v[240:243], v[10:13]
	v_mfma_f32_16x16x32_bf16 v[26:29], v[192:195], v[232:235], v[26:29]
	v_mfma_f32_16x16x32_bf16 v[42:45], v[192:195], v[224:227], v[42:45]
	v_mfma_f32_16x16x32_bf16 v[58:61], v[192:195], v[216:219], v[58:61]
	v_mfma_f32_16x16x32_bf16 v[54:57], v[196:199], v[212:215], v[54:57]
	v_mfma_f32_16x16x32_bf16 v[38:41], v[196:199], v[220:223], v[38:41]
	v_mfma_f32_16x16x32_bf16 v[22:25], v[196:199], v[228:231], v[22:25]
	v_mfma_f32_16x16x32_bf16 v[6:9], v[196:199], v[236:239], v[6:9]
	v_mfma_f32_16x16x32_bf16 v[6:9], v[200:203], v[240:243], v[6:9]
	v_mfma_f32_16x16x32_bf16 v[22:25], v[200:203], v[232:235], v[22:25]
	v_mfma_f32_16x16x32_bf16 v[38:41], v[200:203], v[224:227], v[38:41]
	v_mfma_f32_16x16x32_bf16 v[54:57], v[200:203], v[216:219], v[54:57]
	v_mfma_f32_16x16x32_bf16 v[50:53], v[204:207], v[212:215], v[50:53]
	v_mfma_f32_16x16x32_bf16 v[34:37], v[204:207], v[220:223], v[34:37]
	v_mfma_f32_16x16x32_bf16 v[18:21], v[204:207], v[228:231], v[18:21]
	v_mfma_f32_16x16x32_bf16 v[2:5], v[204:207], v[236:239], v[2:5]
	s_barrier
	s_setprio 2
	v_mfma_f32_16x16x32_bf16 v[2:5], v[208:211], v[240:243], v[2:5]
	v_mfma_f32_16x16x32_bf16 v[18:21], v[208:211], v[232:235], v[18:21]
	v_mfma_f32_16x16x32_bf16 v[34:37], v[208:211], v[224:227], v[34:37]
	v_mfma_f32_16x16x32_bf16 v[50:53], v[208:211], v[216:219], v[50:53]
	s_setprio 0
	s_add_i32 s70, s70, 2
	s_add_u32 vcc_lo, vcc_lo, 0x1000
	s_addc_u32 vcc_hi, vcc_hi, 0
	s_add_u32 s16, s16, 0x1000
	s_addc_u32 s17, s17, 0
	s_cmp_gt_u32 s70, 29
	s_cbranch_scc0 .LBB0_114
	s_and_b64 vcc, exec, s[38:39]
	s_cbranch_vccz .LBB0_117
	s_barrier

; #define PG8_STAGE(bufoff, gbase, voff) do { if constexpr (!pg8_noload<Epi>::value) { _Pragma("unroll") for (int _i = 0; _i < 2; ++_i) \
;         __builtin_amdgcn_global_load_lds((const unsigned*)((const char*)(gbase) + (size_t)_i * pstep + (voff)[0]), (PG8_LAS unsigned*)(lds + (bufoff) + ldsw + _i * 8192), 16, 0, 0); } } while (0)
; #define PG8_LDA(dst, b, h) do { _Pragma("unroll") for (int m = 0; m < 4; ++m) _Pragma("unroll") for (int k = 0; k < 2; ++k) dst[m][k] = *(const PG8_LAS bf16x8*)(lds + PG8_SA(b, h) + aoff + m * 2048 + k * 1024); } while (0)
; #define PG8_LDB(dst, b, h) do { _Pragma("unroll") for (int n = 0; n < 2; ++n) _Pragma("unroll") for (int k = 0; k < 2; ++k) dst[n][k] = *(const PG8_LAS bf16x8*)(lds + PG8_SB(b, h) + boff + n * 2048 + k * 1024); } while (0)
; #define PG8_MMA(ai, bj, At, Bt) do { __builtin_amdgcn_s_setprio(1); _Pragma("unroll") for (int m = 0; m < 4; ++m) _Pragma("unroll") for (int n = 0; n < 2; ++n) _Pragma("unroll") for (int k = 0; k < 2; ++k) \
;         acc[ai][bj][m][n] = __builtin_amdgcn_mfma_f32_16x16x32_bf16(Bt[n][k], At[m][k], acc[ai][bj][m][n], 0, 0, 0); __builtin_amdgcn_s_setprio(0); } while (0)
; #define PG8_BAR __builtin_amdgcn_s_barrier()
; template <class Epi, class Sched, bool ALIGN_EPI = false, bool SP2 = false, bool ABLK = false>
; __device__ __forceinline__ void gemm_phase(PG8_LAS unsigned char* lds, const Gemm g, const Sched& S, const Epi& E) {
;     ...
;         for (int t = 0; t < nt; t += 2) {
;             const bool last = (t == nt - 2);
;             const char* a1 = cA + (size_t)(t + 1) * kstep;
;             const char* a2 = last ? nA : cA + (size_t)(t + 2) * kstep; const char* b2 = last ? nB : cB + (size_t)(t + 2) * kstepB;
;             const char* a3 = a2 + kstep; const char* b3 = b2 + kstepB;
;             if (last && has_next) S.a_ready(nxt);
;             if constexpr (SP2) {
;             PG8_LDB(B0, 0, 0); PG8_LDB(B1, 0, 1); PG8_SCHED; PG8_LDA(At, 0, 0); PG8_STAGE(PG8_SA(1, 1), a1 + hstep, voffA);
;             PG8_WAIT_V(8); PG8_WAIT_L(0); PG8_BAR; PG8_MMA(0, 0, At, B0); PG8_MMA(0, 1, At, B1); PG8_BAR; PG8_SCHED;
;             PG8_LDA(At, 0, 1); PG8_STAGE(PG8_SB(0, 0), b2, voffB); PG8_STAGE(PG8_SB(0, 1), b2 + hstep, voffB); PG8_STAGE(PG8_SA(0, 0), a2, voffA);
;             PG8_WAIT_V(8); PG8_WAIT_L(0); PG8_BAR; PG8_MMA(1, 0, At, B0); PG8_MMA(1, 1, At, B1); PG8_BAR; PG8_SCHED;
.LBB0_487:
	ds_read_b128 v[114:117], v167
	ds_read_b128 v[126:129], v167 offset:1024
	ds_read_b128 v[130:133], v167 offset:2048
	ds_read_b128 v[142:145], v167 offset:3072
	ds_read_b128 v[146:149], v168
	ds_read_b128 v[150:153], v168 offset:1024
	ds_read_b128 v[174:177], v168 offset:2048
	ds_read_b128 v[178:181], v168 offset:3072
	s_add_i32 s65, s39, 2
	s_add_u32 s68, s92, 0xfff00800
	s_addc_u32 s69, s93, -1
	s_cmp_eq_u32 s3, s39
	s_cselect_b32 s69, s79, s69
	s_cselect_b32 s68, s78, s68
	s_cselect_b32 s71, s89, s37
	s_cselect_b32 s70, s88, s11
	v_lshl_add_u64 v[162:163], s[92:93], 0, v[158:159]
	s_add_i32 m0, s56, 0xc000
	ds_read_b128 v[184:187], v169
	ds_read_b128 v[188:191], v169 offset:1024
	ds_read_b128 v[192:195], v169 offset:2048
	ds_read_b128 v[196:199], v169 offset:3072
	ds_read_b128 v[200:203], v169 offset:4096
	ds_read_b128 v[204:207], v169 offset:5120
	ds_read_b128 v[208:211], v169 offset:6144
	ds_read_b128 v[212:215], v169 offset:7168
	global_load_lds_dwordx4 v[162:163], off
	v_lshl_add_u64 v[162:163], v[162:163], 0, s[12:13]
	s_add_i32 m0, s56, 0xe000
	s_nop 0
	global_load_lds_dwordx4 v[162:163], off
	s_waitcnt vmcnt(8)
	s_waitcnt lgkmcnt(0)
	s_barrier
	s_setprio 1
	s_waitcnt lgkmcnt(0)
	v_mfma_f32_16x16x32_bf16 v[138:141], v[114:117], v[184:187], v[138:141]
	v_mfma_f32_16x16x32_bf16 v[110:113], v[114:117], v[192:195], v[110:113]
	v_mfma_f32_16x16x32_bf16 v[94:97], v[114:117], v[200:203], v[94:97]
	v_mfma_f32_16x16x32_bf16 v[78:81], v[114:117], v[208:211], v[78:81]
	v_mfma_f32_16x16x32_bf16 v[78:81], v[126:129], v[212:215], v[78:81]
	v_mfma_f32_16x16x32_bf16 v[94:97], v[126:129], v[204:207], v[94:97]
	v_mfma_f32_16x16x32_bf16 v[110:113], v[126:129], v[196:199], v[110:113]
	v_mfma_f32_16x16x32_bf16 v[138:141], v[126:129], v[188:191], v[138:141]
	v_mfma_f32_16x16x32_bf16 v[134:137], v[130:133], v[184:187], v[134:137]
	v_mfma_f32_16x16x32_bf16 v[106:109], v[130:133], v[192:195], v[106:109]
	v_mfma_f32_16x16x32_bf16 v[90:93], v[130:133], v[200:203], v[90:93]
	v_mfma_f32_16x16x32_bf16 v[74:77], v[130:133], v[208:211], v[74:77]
	v_mfma_f32_16x16x32_bf16 v[74:77], v[142:145], v[212:215], v[74:77]
	v_mfma_f32_16x16x32_bf16 v[90:93], v[142:145], v[204:207], v[90:93]
	v_mfma_f32_16x16x32_bf16 v[106:109], v[142:145], v[196:199], v[106:109]
	v_mfma_f32_16x16x32_bf16 v[134:137], v[142:145], v[188:191], v[134:137]
	v_mfma_f32_16x16x32_bf16 v[122:125], v[146:149], v[184:187], v[122:125]
	v_mfma_f32_16x16x32_bf16 v[102:105], v[146:149], v[192:195], v[102:105]
	v_mfma_f32_16x16x32_bf16 v[86:89], v[146:149], v[200:203], v[86:89]
	v_mfma_f32_16x16x32_bf16 v[70:73], v[146:149], v[208:211], v[70:73]
	v_mfma_f32_16x16x32_bf16 v[70:73], v[150:153], v[212:215], v[70:73]
	v_mfma_f32_16x16x32_bf16 v[86:89], v[150:153], v[204:207], v[86:89]
	v_mfma_f32_16x16x32_bf16 v[102:105], v[150:153], v[196:199], v[102:105]
	v_mfma_f32_16x16x32_bf16 v[122:125], v[150:153], v[188:191], v[122:125]
	v_mfma_f32_16x16x32_bf16 v[118:121], v[174:177], v[184:187], v[118:121]
	v_mfma_f32_16x16x32_bf16 v[98:101], v[174:177], v[192:195], v[98:101]
	v_mfma_f32_16x16x32_bf16 v[82:85], v[174:177], v[200:203], v[82:85]
	v_mfma_f32_16x16x32_bf16 v[66:69], v[174:177], v[208:211], v[66:69]
	s_barrier
	s_setprio 2
	v_mfma_f32_16x16x32_bf16 v[66:69], v[178:181], v[212:215], v[66:69]
	v_mfma_f32_16x16x32_bf16 v[82:85], v[178:181], v[204:207], v[82:85]
	v_mfma_f32_16x16x32_bf16 v[98:101], v[178:181], v[196:199], v[98:101]
	v_mfma_f32_16x16x32_bf16 v[118:121], v[178:181], v[188:191], v[118:121]
	s_setprio 0
	s_add_i32 s39, s73, s55
	v_lshl_add_u64 v[162:163], s[70:71], 0, v[154:155]
	s_mov_b32 m0, s39
	ds_read_b128 v[184:187], v169 offset:16384
	ds_read_b128 v[188:191], v169 offset:17408
	ds_read_b128 v[192:195], v169 offset:18432
	ds_read_b128 v[196:199], v169 offset:19456
	ds_read_b128 v[200:203], v169 offset:20480
	ds_read_b128 v[204:207], v169 offset:21504
	ds_read_b128 v[208:211], v169 offset:22528
	ds_read_b128 v[212:215], v169 offset:23552
	global_load_lds_dwordx4 v[162:163], off
	v_lshl_add_u64 v[216:217], v[162:163], 0, s[12:13]
	s_add_i32 m0, s39, 0x2000
	s_add_i32 s39, s74, s55
	global_load_lds_dwordx4 v[216:217], off
	v_lshl_add_u64 v[216:217], v[162:163], 0, s[14:15]
	s_mov_b32 m0, s39
	s_nop 0
	global_load_lds_dwordx4 v[216:217], off
	v_lshl_add_u64 v[216:217], v[162:163], 0, s[16:17]
	s_add_i32 m0, s39, 0x2000
	s_nop 0
	global_load_lds_dwordx4 v[216:217], off
	v_lshl_add_u64 v[216:217], s[68:69], 0, v[154:155]
	s_mov_b32 m0, s56
	v_lshl_add_u64 v[218:219], v[216:217], 0, s[12:13]
	global_load_lds_dwordx4 v[216:217], off
	s_mov_b32 m0, s57
	s_nop 0
	global_load_lds_dwordx4 v[218:219], off
	s_waitcnt vmcnt(8)
	s_waitcnt lgkmcnt(0)
	s_barrier
; #define PG8_STAGE(bufoff, gbase, voff) do { if constexpr (!pg8_noload<Epi>::value) { _Pragma("unroll") for (int _i = 0; _i < 2; ++_i) \
;         __builtin_amdgcn_global_load_lds((const unsigned*)((const char*)(gbase) + (size_t)_i * pstep + (voff)[0]), (PG8_LAS unsigned*)(lds + (bufoff) + ldsw + _i * 8192), 16, 0, 0); } } while (0)
; #define PG8_LDA(dst, b, h) do { _Pragma("unroll") for (int m = 0; m < 4; ++m) _Pragma("unroll") for (int k = 0; k < 2; ++k) dst[m][k] = *(const PG8_LAS bf16x8*)(lds + PG8_SA(b, h) + aoff + m * 2048 + k * 1024); } while (0)
; #define PG8_LDB(dst, b, h) do { _Pragma("unroll") for (int n = 0; n < 2; ++n) _Pragma("unroll") for (int k = 0; k < 2; ++k) dst[n][k] = *(const PG8_LAS bf16x8*)(lds + PG8_SB(b, h) + boff + n * 2048 + k * 1024); } while (0)
; #define PG8_MMA(ai, bj, At, Bt) do { __builtin_amdgcn_s_setprio(1); _Pragma("unroll") for (int m = 0; m < 4; ++m) _Pragma("unroll") for (int n = 0; n < 2; ++n) _Pragma("unroll") for (int k = 0; k < 2; ++k) \
;         acc[ai][bj][m][n] = __builtin_amdgcn_mfma_f32_16x16x32_bf16(Bt[n][k], At[m][k], acc[ai][bj][m][n], 0, 0, 0); __builtin_amdgcn_s_setprio(0); } while (0)
; #define PG8_WAIT_V(n) asm volatile("s_waitcnt vmcnt(" #n ")" ::: "memory")
; #define PG8_WAIT_L(n) asm volatile("s_waitcnt lgkmcnt(" #n ")" ::: "memory")
; #define PG8_BAR __builtin_amdgcn_s_barrier()
; #define PG8_SCHED __builtin_amdgcn_sched_barrier(0)
; template <class Epi, class Sched, bool ALIGN_EPI = false, bool SP2 = false, bool ABLK = false>
; __device__ __forceinline__ void gemm_phase(PG8_LAS unsigned char* lds, const Gemm g, const Sched& S, const Epi& E) {
;     ...
;             PG8_WAIT_V(8); PG8_WAIT_L(0); PG8_BAR; PG8_MMA(1, 0, At, B0); PG8_MMA(1, 1, At, B1); PG8_BAR; PG8_SCHED;
;             PG8_LDB(B0, 1, 0); PG8_LDB(B1, 1, 1); PG8_SCHED; PG8_LDA(At, 1, 0); PG8_STAGE(PG8_SA(0, 1), a2 + hstep, voffA);
;             PG8_WAIT_V(8); PG8_WAIT_L(0); PG8_BAR; PG8_MMA(0, 0, At, B0); PG8_MMA(0, 1, At, B1); PG8_BAR; PG8_SCHED;
;             PG8_LDA(At, 1, 1); PG8_STAGE(PG8_SB(1, 0), b3, voffB); PG8_STAGE(PG8_SB(1, 1), b3 + hstep, voffB); PG8_STAGE(PG8_SA(1, 0), a3, voffA);
	s_setprio 1
	s_waitcnt lgkmcnt(0)
	v_mfma_f32_16x16x32_bf16 v[62:65], v[114:117], v[184:187], v[62:65]
	v_mfma_f32_16x16x32_bf16 v[46:49], v[114:117], v[192:195], v[46:49]
	v_mfma_f32_16x16x32_bf16 v[30:33], v[114:117], v[200:203], v[30:33]
	v_mfma_f32_16x16x32_bf16 v[14:17], v[114:117], v[208:211], v[14:17]
	v_mfma_f32_16x16x32_bf16 v[14:17], v[126:129], v[212:215], v[14:17]
	v_mfma_f32_16x16x32_bf16 v[30:33], v[126:129], v[204:207], v[30:33]
	v_mfma_f32_16x16x32_bf16 v[46:49], v[126:129], v[196:199], v[46:49]
	v_mfma_f32_16x16x32_bf16 v[62:65], v[126:129], v[188:191], v[62:65]
	v_mfma_f32_16x16x32_bf16 v[58:61], v[130:133], v[184:187], v[58:61]
	v_mfma_f32_16x16x32_bf16 v[42:45], v[130:133], v[192:195], v[42:45]
	v_mfma_f32_16x16x32_bf16 v[26:29], v[130:133], v[200:203], v[26:29]
	v_mfma_f32_16x16x32_bf16 v[10:13], v[130:133], v[208:211], v[10:13]
	v_mfma_f32_16x16x32_bf16 v[10:13], v[142:145], v[212:215], v[10:13]
	v_mfma_f32_16x16x32_bf16 v[26:29], v[142:145], v[204:207], v[26:29]
	v_mfma_f32_16x16x32_bf16 v[42:45], v[142:145], v[196:199], v[42:45]
	v_mfma_f32_16x16x32_bf16 v[58:61], v[142:145], v[188:191], v[58:61]
	v_mfma_f32_16x16x32_bf16 v[54:57], v[146:149], v[184:187], v[54:57]
	v_mfma_f32_16x16x32_bf16 v[38:41], v[146:149], v[192:195], v[38:41]
	v_mfma_f32_16x16x32_bf16 v[22:25], v[146:149], v[200:203], v[22:25]
	v_mfma_f32_16x16x32_bf16 v[6:9], v[146:149], v[208:211], v[6:9]
	v_mfma_f32_16x16x32_bf16 v[6:9], v[150:153], v[212:215], v[6:9]
	v_mfma_f32_16x16x32_bf16 v[22:25], v[150:153], v[204:207], v[22:25]
	v_mfma_f32_16x16x32_bf16 v[38:41], v[150:153], v[196:199], v[38:41]
	v_mfma_f32_16x16x32_bf16 v[54:57], v[150:153], v[188:191], v[54:57]
	v_mfma_f32_16x16x32_bf16 v[50:53], v[174:177], v[184:187], v[50:53]
	v_mfma_f32_16x16x32_bf16 v[34:37], v[174:177], v[192:195], v[34:37]
	v_mfma_f32_16x16x32_bf16 v[18:21], v[174:177], v[200:203], v[18:21]
	v_mfma_f32_16x16x32_bf16 v[2:5], v[174:177], v[208:211], v[2:5]
	s_barrier
	s_setprio 2
	v_mfma_f32_16x16x32_bf16 v[2:5], v[178:181], v[212:215], v[2:5]
	v_mfma_f32_16x16x32_bf16 v[18:21], v[178:181], v[204:207], v[18:21]
	v_mfma_f32_16x16x32_bf16 v[34:37], v[178:181], v[196:199], v[34:37]
	v_mfma_f32_16x16x32_bf16 v[50:53], v[178:181], v[188:191], v[50:53]
	s_setprio 0
	s_add_i32 s39, 0, 0x18000
	s_add_i32 s68, 0, 0x1c000
	v_add_u32_e32 v142, s39, v1
	v_add_u32_e32 v173, s68, v1
	ds_read_b128 v[114:117], v142
	ds_read_b128 v[126:129], v142 offset:1024
	ds_read_b128 v[130:133], v142 offset:2048
	ds_read_b128 v[142:145], v142 offset:3072
	ds_read_b128 v[146:149], v173
	ds_read_b128 v[150:153], v173 offset:1024
	ds_read_b128 v[174:177], v173 offset:2048
	ds_read_b128 v[178:181], v173 offset:3072
	s_mov_b32 m0, s58
	v_lshl_add_u64 v[218:219], v[216:217], 0, s[14:15]
	ds_read_b128 v[184:187], v169 offset:32768
	ds_read_b128 v[188:191], v169 offset:33792
	ds_read_b128 v[192:195], v169 offset:34816
	ds_read_b128 v[196:199], v169 offset:35840
	ds_read_b128 v[200:203], v169 offset:36864
	ds_read_b128 v[204:207], v169 offset:37888
	ds_read_b128 v[208:211], v169 offset:38912
	ds_read_b128 v[212:215], v169 offset:39936
	global_load_lds_dwordx4 v[218:219], off
	v_lshl_add_u64 v[218:219], v[216:217], 0, s[16:17]
	s_mov_b32 m0, s59
	s_nop 0
	global_load_lds_dwordx4 v[218:219], off
	s_waitcnt vmcnt(8)
	s_waitcnt lgkmcnt(0)
	s_barrier
	s_setprio 1
	s_waitcnt lgkmcnt(0)
	v_mfma_f32_16x16x32_bf16 v[138:141], v[114:117], v[184:187], v[138:141]
	v_mfma_f32_16x16x32_bf16 v[110:113], v[114:117], v[192:195], v[110:113]
	v_mfma_f32_16x16x32_bf16 v[94:97], v[114:117], v[200:203], v[94:97]
	v_mfma_f32_16x16x32_bf16 v[78:81], v[114:117], v[208:211], v[78:81]
	v_mfma_f32_16x16x32_bf16 v[78:81], v[126:129], v[212:215], v[78:81]
	v_mfma_f32_16x16x32_bf16 v[94:97], v[126:129], v[204:207], v[94:97]
	v_mfma_f32_16x16x32_bf16 v[110:113], v[126:129], v[196:199], v[110:113]
	v_mfma_f32_16x16x32_bf16 v[138:141], v[126:129], v[188:191], v[138:141]
	v_mfma_f32_16x16x32_bf16 v[134:137], v[130:133], v[184:187], v[134:137]
	v_mfma_f32_16x16x32_bf16 v[106:109], v[130:133], v[192:195], v[106:109]
	v_mfma_f32_16x16x32_bf16 v[90:93], v[130:133], v[200:203], v[90:93]
	v_mfma_f32_16x16x32_bf16 v[74:77], v[130:133], v[208:211], v[74:77]
	v_mfma_f32_16x16x32_bf16 v[74:77], v[142:145], v[212:215], v[74:77]
	v_mfma_f32_16x16x32_bf16 v[90:93], v[142:145], v[204:207], v[90:93]
	v_mfma_f32_16x16x32_bf16 v[106:109], v[142:145], v[196:199], v[106:109]
	v_mfma_f32_16x16x32_bf16 v[134:137], v[142:145], v[188:191], v[134:137]
	v_mfma_f32_16x16x32_bf16 v[122:125], v[146:149], v[184:187], v[122:125]
	v_mfma_f32_16x16x32_bf16 v[102:105], v[146:149], v[192:195], v[102:105]
	v_mfma_f32_16x16x32_bf16 v[86:89], v[146:149], v[200:203], v[86:89]
	v_mfma_f32_16x16x32_bf16 v[70:73], v[146:149], v[208:211], v[70:73]
	v_mfma_f32_16x16x32_bf16 v[70:73], v[150:153], v[212:215], v[70:73]
	v_mfma_f32_16x16x32_bf16 v[86:89], v[150:153], v[204:207], v[86:89]
	v_mfma_f32_16x16x32_bf16 v[102:105], v[150:153], v[196:199], v[102:105]
	v_mfma_f32_16x16x32_bf16 v[122:125], v[150:153], v[188:191], v[122:125]
	v_mfma_f32_16x16x32_bf16 v[118:121], v[174:177], v[184:187], v[118:121]
	v_mfma_f32_16x16x32_bf16 v[98:101], v[174:177], v[192:195], v[98:101]
	v_mfma_f32_16x16x32_bf16 v[82:85], v[174:177], v[200:203], v[82:85]
	v_mfma_f32_16x16x32_bf16 v[66:69], v[174:177], v[208:211], v[66:69]
	s_barrier
; #define PG8_STAGE(bufoff, gbase, voff) do { if constexpr (!pg8_noload<Epi>::value) { _Pragma("unroll") for (int _i = 0; _i < 2; ++_i) \
;         __builtin_amdgcn_global_load_lds((const unsigned*)((const char*)(gbase) + (size_t)_i * pstep + (voff)[0]), (PG8_LAS unsigned*)(lds + (bufoff) + ldsw + _i * 8192), 16, 0, 0); } } while (0)
; #define PG8_LDA(dst, b, h) do { _Pragma("unroll") for (int m = 0; m < 4; ++m) _Pragma("unroll") for (int k = 0; k < 2; ++k) dst[m][k] = *(const PG8_LAS bf16x8*)(lds + PG8_SA(b, h) + aoff + m * 2048 + k * 1024); } while (0)
; #define PG8_MMA(ai, bj, At, Bt) do { __builtin_amdgcn_s_setprio(1); _Pragma("unroll") for (int m = 0; m < 4; ++m) _Pragma("unroll") for (int n = 0; n < 2; ++n) _Pragma("unroll") for (int k = 0; k < 2; ++k) \
;         acc[ai][bj][m][n] = __builtin_amdgcn_mfma_f32_16x16x32_bf16(Bt[n][k], At[m][k], acc[ai][bj][m][n], 0, 0, 0); __builtin_amdgcn_s_setprio(0); } while (0)
; #define PG8_WAIT_V(n) asm volatile("s_waitcnt vmcnt(" #n ")" ::: "memory")
; #define PG8_WAIT_L(n) asm volatile("s_waitcnt lgkmcnt(" #n ")" ::: "memory")
; #define PG8_BAR __builtin_amdgcn_s_barrier()
; #define PG8_SCHED __builtin_amdgcn_sched_barrier(0)
; template <class Epi, class Sched, bool ALIGN_EPI = false, bool SP2 = false, bool ABLK = false>
; __device__ __forceinline__ void gemm_phase(PG8_LAS unsigned char* lds, const Gemm g, const Sched& S, const Epi& E) {
;     ...
;             PG8_WAIT_V(8); PG8_WAIT_L(0); PG8_BAR; PG8_MMA(0, 0, At, B0); PG8_MMA(0, 1, At, B1); PG8_BAR; PG8_SCHED;
;             PG8_LDA(At, 1, 1); PG8_STAGE(PG8_SB(1, 0), b3, voffB); PG8_STAGE(PG8_SB(1, 1), b3 + hstep, voffB); PG8_STAGE(PG8_SA(1, 0), a3, voffA);
;             PG8_WAIT_V(8); PG8_WAIT_L(0); PG8_BAR; PG8_MMA(1, 0, At, B0); PG8_MMA(1, 1, At, B1); PG8_BAR; PG8_SCHED;
	s_setprio 2
	v_mfma_f32_16x16x32_bf16 v[66:69], v[178:181], v[212:215], v[66:69]
	v_mfma_f32_16x16x32_bf16 v[82:85], v[178:181], v[204:207], v[82:85]
	v_mfma_f32_16x16x32_bf16 v[98:101], v[178:181], v[196:199], v[98:101]
	v_mfma_f32_16x16x32_bf16 v[118:121], v[178:181], v[188:191], v[118:121]
	s_setprio 0
	s_add_i32 s39, s39, s55
	v_lshl_add_u64 v[218:219], v[162:163], 0, s[24:25]
	s_mov_b32 m0, s39
	ds_read_b128 v[184:187], v169 offset:49152
	ds_read_b128 v[188:191], v169 offset:50176
	ds_read_b128 v[192:195], v169 offset:51200
	ds_read_b128 v[196:199], v169 offset:52224
	ds_read_b128 v[200:203], v169 offset:53248
	ds_read_b128 v[204:207], v169 offset:54272
	ds_read_b128 v[208:211], v169 offset:55296
	ds_read_b128 v[212:215], v169 offset:56320
	global_load_lds_dwordx4 v[218:219], off
	v_lshl_add_u64 v[218:219], v[162:163], 0, s[26:27]
	s_add_i32 m0, s39, 0x2000
	s_add_i32 s39, s68, s55
	global_load_lds_dwordx4 v[218:219], off
	v_lshl_add_u64 v[218:219], v[162:163], 0, s[28:29]
	s_mov_b32 m0, s39
	v_lshl_add_u64 v[162:163], v[162:163], 0, s[30:31]
	global_load_lds_dwordx4 v[218:219], off
	s_add_i32 m0, s39, 0x2000
	s_nop 0
	global_load_lds_dwordx4 v[162:163], off
	v_lshl_add_u64 v[162:163], v[216:217], 0, s[24:25]
	s_mov_b32 m0, s62
	s_nop 0
	global_load_lds_dwordx4 v[162:163], off
	v_lshl_add_u64 v[162:163], v[216:217], 0, s[26:27]
	s_mov_b32 m0, s63
	s_nop 0
	global_load_lds_dwordx4 v[162:163], off
	s_waitcnt vmcnt(8)
	s_waitcnt lgkmcnt(0)
	s_barrier
	s_setprio 1
	s_waitcnt lgkmcnt(0)
	v_mfma_f32_16x16x32_bf16 v[62:65], v[114:117], v[184:187], v[62:65]
	v_mfma_f32_16x16x32_bf16 v[46:49], v[114:117], v[192:195], v[46:49]
	v_mfma_f32_16x16x32_bf16 v[30:33], v[114:117], v[200:203], v[30:33]
	v_mfma_f32_16x16x32_bf16 v[14:17], v[114:117], v[208:211], v[14:17]
	v_mfma_f32_16x16x32_bf16 v[14:17], v[126:129], v[212:215], v[14:17]
	v_mfma_f32_16x16x32_bf16 v[30:33], v[126:129], v[204:207], v[30:33]
	v_mfma_f32_16x16x32_bf16 v[46:49], v[126:129], v[196:199], v[46:49]
	v_mfma_f32_16x16x32_bf16 v[62:65], v[126:129], v[188:191], v[62:65]
	v_mfma_f32_16x16x32_bf16 v[58:61], v[130:133], v[184:187], v[58:61]
	v_mfma_f32_16x16x32_bf16 v[42:45], v[130:133], v[192:195], v[42:45]
	v_mfma_f32_16x16x32_bf16 v[26:29], v[130:133], v[200:203], v[26:29]
	v_mfma_f32_16x16x32_bf16 v[10:13], v[130:133], v[208:211], v[10:13]
	v_mfma_f32_16x16x32_bf16 v[10:13], v[142:145], v[212:215], v[10:13]
	v_mfma_f32_16x16x32_bf16 v[26:29], v[142:145], v[204:207], v[26:29]
	v_mfma_f32_16x16x32_bf16 v[42:45], v[142:145], v[196:199], v[42:45]
	v_mfma_f32_16x16x32_bf16 v[58:61], v[142:145], v[188:191], v[58:61]
	v_mfma_f32_16x16x32_bf16 v[54:57], v[146:149], v[184:187], v[54:57]
	v_mfma_f32_16x16x32_bf16 v[38:41], v[146:149], v[192:195], v[38:41]
	v_mfma_f32_16x16x32_bf16 v[22:25], v[146:149], v[200:203], v[22:25]
	v_mfma_f32_16x16x32_bf16 v[6:9], v[146:149], v[208:211], v[6:9]
	v_mfma_f32_16x16x32_bf16 v[6:9], v[150:153], v[212:215], v[6:9]
	v_mfma_f32_16x16x32_bf16 v[22:25], v[150:153], v[204:207], v[22:25]
	v_mfma_f32_16x16x32_bf16 v[38:41], v[150:153], v[196:199], v[38:41]
	v_mfma_f32_16x16x32_bf16 v[54:57], v[150:153], v[188:191], v[54:57]
	v_mfma_f32_16x16x32_bf16 v[50:53], v[174:177], v[184:187], v[50:53]
	v_mfma_f32_16x16x32_bf16 v[34:37], v[174:177], v[192:195], v[34:37]
	v_mfma_f32_16x16x32_bf16 v[18:21], v[174:177], v[200:203], v[18:21]
	v_mfma_f32_16x16x32_bf16 v[2:5], v[174:177], v[208:211], v[2:5]
	s_barrier
	s_setprio 2
	v_mfma_f32_16x16x32_bf16 v[2:5], v[178:181], v[212:215], v[2:5]
	v_mfma_f32_16x16x32_bf16 v[18:21], v[178:181], v[204:207], v[18:21]
	v_mfma_f32_16x16x32_bf16 v[34:37], v[178:181], v[196:199], v[34:37]
	v_mfma_f32_16x16x32_bf16 v[50:53], v[178:181], v[188:191], v[50:53]
	s_setprio 0
	s_add_u32 s92, s92, 0x1000
	s_addc_u32 s93, s93, 0
	s_add_u32 s11, s11, 0x1000
	s_addc_u32 s37, s37, 0
	s_cmp_ge_i32 s65, s80
	s_mov_b32 s39, s65
	s_cbranch_scc0 .LBB0_487
	s_and_b64 vcc, exec, s[34:35]
	s_cbranch_vccnz .LBB0_492
	s_lshl_b32 s11, s2, 8
	s_cmp_gt_i32 s2, 63
	s_mov_b64 s[68:69], -1
	s_cbranch_scc1 .LBB0_493

; #define PG8_STAGE(bufoff, gbase, voff) do { if constexpr (!pg8_noload<Epi>::value) { _Pragma("unroll") for (int _i = 0; _i < 2; ++_i) \
;         __builtin_amdgcn_global_load_lds((const unsigned*)((const char*)(gbase) + (size_t)_i * pstep + (voff)[0]), (PG8_LAS unsigned*)(lds + (bufoff) + ldsw + _i * 8192), 16, 0, 0); } } while (0)
; #define PG8_LDA(dst, b, h) do { _Pragma("unroll") for (int m = 0; m < 4; ++m) _Pragma("unroll") for (int k = 0; k < 2; ++k) dst[m][k] = *(const PG8_LAS bf16x8*)(lds + PG8_SA(b, h) + aoff + m * 2048 + k * 1024); } while (0)
; #define PG8_LDB(dst, b, h) do { _Pragma("unroll") for (int n = 0; n < 2; ++n) _Pragma("unroll") for (int k = 0; k < 2; ++k) dst[n][k] = *(const PG8_LAS bf16x8*)(lds + PG8_SB(b, h) + boff + n * 2048 + k * 1024); } while (0)
; #define PG8_MMA(ai, bj, At, Bt) do { __builtin_amdgcn_s_setprio(1); _Pragma("unroll") for (int m = 0; m < 4; ++m) _Pragma("unroll") for (int n = 0; n < 2; ++n) _Pragma("unroll") for (int k = 0; k < 2; ++k) \
;         acc[ai][bj][m][n] = __builtin_amdgcn_mfma_f32_16x16x32_bf16(Bt[n][k], At[m][k], acc[ai][bj][m][n], 0, 0, 0); __builtin_amdgcn_s_setprio(0); } while (0)
; #define PG8_BAR __builtin_amdgcn_s_barrier()
; template <class Epi, class Sched, bool ALIGN_EPI = false, bool SP2 = false, bool ABLK = false>
; __device__ __forceinline__ void gemm_phase(PG8_LAS unsigned char* lds, const Gemm g, const Sched& S, const Epi& E) {
;     ...
;         for (int t = 0; t < nt; t += 2) {
;             const bool last = (t == nt - 2);
;             const char* a1 = cA + (size_t)(t + 1) * kstep;
;             const char* a2 = last ? nA : cA + (size_t)(t + 2) * kstep; const char* b2 = last ? nB : cB + (size_t)(t + 2) * kstepB;
;             const char* a3 = a2 + kstep; const char* b3 = b2 + kstepB;
;             if (last && has_next) S.a_ready(nxt);
;             if constexpr (SP2) {
;             PG8_LDB(B0, 0, 0); PG8_LDB(B1, 0, 1); PG8_SCHED; PG8_LDA(At, 0, 0); PG8_STAGE(PG8_SA(1, 1), a1 + hstep, voffA);
;             PG8_WAIT_V(8); PG8_WAIT_L(0); PG8_BAR; PG8_MMA(0, 0, At, B0); PG8_MMA(0, 1, At, B1); PG8_BAR; PG8_SCHED;
;             PG8_LDA(At, 0, 1); PG8_STAGE(PG8_SB(0, 0), b2, voffB); PG8_STAGE(PG8_SB(0, 1), b2 + hstep, voffB); PG8_STAGE(PG8_SA(0, 0), a2, voffA);
;             PG8_WAIT_V(8); PG8_WAIT_L(0); PG8_BAR; PG8_MMA(1, 0, At, B0); PG8_MMA(1, 1, At, B1); PG8_BAR; PG8_SCHED;
.LBB0_619:
	s_or_b32 s28, s57, 1
	s_lshl_b64 s[58:59], s[28:29], 11
	s_add_u32 s58, s2, s58
	s_addc_u32 s59, s3, s59
	s_add_i32 s28, s57, 2
	v_add_u32_e32 v160, s78, v168
	v_add_u32_e32 v180, s79, v168
	s_lshl_b64 s[60:61], s[28:29], 11
	ds_read_b128 v[130:133], v160
	ds_read_b128 v[134:137], v160 offset:1024
	ds_read_b128 v[156:159], v160 offset:2048
	ds_read_b128 v[160:163], v160 offset:3072
	ds_read_b128 v[164:167], v180
	ds_read_b128 v[176:179], v180 offset:1024
	ds_read_b128 v[184:187], v180 offset:2048
	ds_read_b128 v[188:191], v180 offset:3072
	s_add_u32 s66, s2, s60
	s_addc_u32 s67, s3, s61
	s_and_b64 s[62:63], s[68:69], exec
	s_cselect_b32 s73, s67, s7
	s_cselect_b32 s72, s66, s15
	s_add_u32 s62, s16, s60
	s_addc_u32 s63, s17, s61
	s_and_b64 s[60:61], s[68:69], exec
	s_cselect_b32 s61, s63, s9
	s_cselect_b32 s60, s62, s56
	v_lshl_add_u64 v[180:181], s[58:59], 0, v[138:139]
	v_lshl_add_u64 v[224:225], v[180:181], 0, s[24:25]
	s_add_i32 m0, s70, 0xc000
	ds_read_b128 v[192:195], v173
	ds_read_b128 v[196:199], v173 offset:1024
	ds_read_b128 v[200:203], v173 offset:2048
	ds_read_b128 v[204:207], v173 offset:3072
	ds_read_b128 v[208:211], v173 offset:4096
	ds_read_b128 v[212:215], v173 offset:5120
	ds_read_b128 v[216:219], v173 offset:6144
	ds_read_b128 v[220:223], v173 offset:7168
	global_load_lds_dwordx4 v[224:225], off
	v_lshl_add_u64 v[180:181], v[180:181], 0, s[26:27]
	s_add_i32 m0, s70, 0xe000
	s_nop 0
	global_load_lds_dwordx4 v[180:181], off
	s_waitcnt vmcnt(8)
	s_waitcnt lgkmcnt(0)
	s_barrier
	s_setprio 1
	s_waitcnt lgkmcnt(0)
	v_mfma_f32_16x16x32_bf16 v[126:129], v[130:133], v[192:195], v[126:129]
	v_mfma_f32_16x16x32_bf16 v[110:113], v[130:133], v[200:203], v[110:113]
	v_mfma_f32_16x16x32_bf16 v[94:97], v[130:133], v[208:211], v[94:97]
	v_mfma_f32_16x16x32_bf16 v[78:81], v[130:133], v[216:219], v[78:81]
	v_mfma_f32_16x16x32_bf16 v[78:81], v[134:137], v[220:223], v[78:81]
	v_mfma_f32_16x16x32_bf16 v[94:97], v[134:137], v[212:215], v[94:97]
	v_mfma_f32_16x16x32_bf16 v[110:113], v[134:137], v[204:207], v[110:113]
	v_mfma_f32_16x16x32_bf16 v[126:129], v[134:137], v[196:199], v[126:129]
	v_mfma_f32_16x16x32_bf16 v[122:125], v[156:159], v[192:195], v[122:125]
	v_mfma_f32_16x16x32_bf16 v[106:109], v[156:159], v[200:203], v[106:109]
	v_mfma_f32_16x16x32_bf16 v[90:93], v[156:159], v[208:211], v[90:93]
	v_mfma_f32_16x16x32_bf16 v[74:77], v[156:159], v[216:219], v[74:77]
	v_mfma_f32_16x16x32_bf16 v[74:77], v[160:163], v[220:223], v[74:77]
	v_mfma_f32_16x16x32_bf16 v[90:93], v[160:163], v[212:215], v[90:93]
	v_mfma_f32_16x16x32_bf16 v[106:109], v[160:163], v[204:207], v[106:109]
	v_mfma_f32_16x16x32_bf16 v[122:125], v[160:163], v[196:199], v[122:125]
	v_mfma_f32_16x16x32_bf16 v[118:121], v[164:167], v[192:195], v[118:121]
	v_mfma_f32_16x16x32_bf16 v[102:105], v[164:167], v[200:203], v[102:105]
	v_mfma_f32_16x16x32_bf16 v[86:89], v[164:167], v[208:211], v[86:89]
	v_mfma_f32_16x16x32_bf16 v[70:73], v[164:167], v[216:219], v[70:73]
	v_mfma_f32_16x16x32_bf16 v[70:73], v[176:179], v[220:223], v[70:73]
	v_mfma_f32_16x16x32_bf16 v[86:89], v[176:179], v[212:215], v[86:89]
	v_mfma_f32_16x16x32_bf16 v[102:105], v[176:179], v[204:207], v[102:105]
	v_mfma_f32_16x16x32_bf16 v[118:121], v[176:179], v[196:199], v[118:121]
	v_mfma_f32_16x16x32_bf16 v[114:117], v[184:187], v[192:195], v[114:117]
	v_mfma_f32_16x16x32_bf16 v[98:101], v[184:187], v[200:203], v[98:101]
	v_mfma_f32_16x16x32_bf16 v[82:85], v[184:187], v[208:211], v[82:85]
	v_mfma_f32_16x16x32_bf16 v[66:69], v[184:187], v[216:219], v[66:69]
	s_barrier
	s_setprio 2
	v_mfma_f32_16x16x32_bf16 v[66:69], v[188:191], v[220:223], v[66:69]
	v_mfma_f32_16x16x32_bf16 v[82:85], v[188:191], v[212:215], v[82:85]
	v_mfma_f32_16x16x32_bf16 v[98:101], v[188:191], v[204:207], v[98:101]
	v_mfma_f32_16x16x32_bf16 v[114:117], v[188:191], v[196:199], v[114:117]
	s_setprio 0
	s_add_i32 s58, s78, s91
	v_lshl_add_u64 v[180:181], s[60:61], 0, v[138:139]
	s_mov_b32 m0, s58
	ds_read_b128 v[192:195], v173 offset:16384
	ds_read_b128 v[196:199], v173 offset:17408
	ds_read_b128 v[200:203], v173 offset:18432
	ds_read_b128 v[204:207], v173 offset:19456
	ds_read_b128 v[208:211], v173 offset:20480
	ds_read_b128 v[212:215], v173 offset:21504
	ds_read_b128 v[216:219], v173 offset:22528
	ds_read_b128 v[220:223], v173 offset:23552
	global_load_lds_dwordx4 v[180:181], off
	v_lshl_add_u64 v[224:225], v[180:181], 0, s[22:23]
	s_add_i32 m0, s58, 0x2000
	s_add_i32 s58, s79, s91
	global_load_lds_dwordx4 v[224:225], off
	v_lshl_add_u64 v[224:225], v[180:181], 0, s[24:25]
	s_mov_b32 m0, s58
	s_nop 0
	global_load_lds_dwordx4 v[224:225], off
	v_lshl_add_u64 v[224:225], v[180:181], 0, s[26:27]
	s_add_i32 m0, s58, 0x2000
	s_nop 0
	global_load_lds_dwordx4 v[224:225], off
	v_lshl_add_u64 v[224:225], s[72:73], 0, v[138:139]
	s_mov_b32 m0, s70
	v_lshl_add_u64 v[226:227], v[224:225], 0, s[22:23]
	global_load_lds_dwordx4 v[224:225], off
	s_mov_b32 m0, s71
	s_nop 0
	global_load_lds_dwordx4 v[226:227], off
	s_waitcnt vmcnt(8)
	s_waitcnt lgkmcnt(0)
	s_barrier
; #define PG8_STAGE(bufoff, gbase, voff) do { if constexpr (!pg8_noload<Epi>::value) { _Pragma("unroll") for (int _i = 0; _i < 2; ++_i) \
;         __builtin_amdgcn_global_load_lds((const unsigned*)((const char*)(gbase) + (size_t)_i * pstep + (voff)[0]), (PG8_LAS unsigned*)(lds + (bufoff) + ldsw + _i * 8192), 16, 0, 0); } } while (0)
; #define PG8_LDA(dst, b, h) do { _Pragma("unroll") for (int m = 0; m < 4; ++m) _Pragma("unroll") for (int k = 0; k < 2; ++k) dst[m][k] = *(const PG8_LAS bf16x8*)(lds + PG8_SA(b, h) + aoff + m * 2048 + k * 1024); } while (0)
; #define PG8_LDB(dst, b, h) do { _Pragma("unroll") for (int n = 0; n < 2; ++n) _Pragma("unroll") for (int k = 0; k < 2; ++k) dst[n][k] = *(const PG8_LAS bf16x8*)(lds + PG8_SB(b, h) + boff + n * 2048 + k * 1024); } while (0)
; #define PG8_MMA(ai, bj, At, Bt) do { __builtin_amdgcn_s_setprio(1); _Pragma("unroll") for (int m = 0; m < 4; ++m) _Pragma("unroll") for (int n = 0; n < 2; ++n) _Pragma("unroll") for (int k = 0; k < 2; ++k) \
;         acc[ai][bj][m][n] = __builtin_amdgcn_mfma_f32_16x16x32_bf16(Bt[n][k], At[m][k], acc[ai][bj][m][n], 0, 0, 0); __builtin_amdgcn_s_setprio(0); } while (0)
; #define PG8_WAIT_V(n) asm volatile("s_waitcnt vmcnt(" #n ")" ::: "memory")
; #define PG8_WAIT_L(n) asm volatile("s_waitcnt lgkmcnt(" #n ")" ::: "memory")
; #define PG8_BAR __builtin_amdgcn_s_barrier()
; #define PG8_SCHED __builtin_amdgcn_sched_barrier(0)
; template <class Epi, class Sched, bool ALIGN_EPI = false, bool SP2 = false, bool ABLK = false>
; __device__ __forceinline__ void gemm_phase(PG8_LAS unsigned char* lds, const Gemm g, const Sched& S, const Epi& E) {
;     ...
;             PG8_WAIT_V(8); PG8_WAIT_L(0); PG8_BAR; PG8_MMA(1, 0, At, B0); PG8_MMA(1, 1, At, B1); PG8_BAR; PG8_SCHED;
;             PG8_LDB(B0, 1, 0); PG8_LDB(B1, 1, 1); PG8_SCHED; PG8_LDA(At, 1, 0); PG8_STAGE(PG8_SA(0, 1), a2 + hstep, voffA);
;             PG8_WAIT_V(8); PG8_WAIT_L(0); PG8_BAR; PG8_MMA(0, 0, At, B0); PG8_MMA(0, 1, At, B1); PG8_BAR; PG8_SCHED;
;             PG8_LDA(At, 1, 1); PG8_STAGE(PG8_SB(1, 0), b3, voffB); PG8_STAGE(PG8_SB(1, 1), b3 + hstep, voffB); PG8_STAGE(PG8_SA(1, 0), a3, voffA);
	s_setprio 1
	s_waitcnt lgkmcnt(0)
	v_mfma_f32_16x16x32_bf16 v[62:65], v[130:133], v[192:195], v[62:65]
	v_mfma_f32_16x16x32_bf16 v[46:49], v[130:133], v[200:203], v[46:49]
	v_mfma_f32_16x16x32_bf16 v[30:33], v[130:133], v[208:211], v[30:33]
	v_mfma_f32_16x16x32_bf16 v[14:17], v[130:133], v[216:219], v[14:17]
	v_mfma_f32_16x16x32_bf16 v[14:17], v[134:137], v[220:223], v[14:17]
	v_mfma_f32_16x16x32_bf16 v[30:33], v[134:137], v[212:215], v[30:33]
	v_mfma_f32_16x16x32_bf16 v[46:49], v[134:137], v[204:207], v[46:49]
	v_mfma_f32_16x16x32_bf16 v[62:65], v[134:137], v[196:199], v[62:65]
	v_mfma_f32_16x16x32_bf16 v[58:61], v[156:159], v[192:195], v[58:61]
	v_mfma_f32_16x16x32_bf16 v[42:45], v[156:159], v[200:203], v[42:45]
	v_mfma_f32_16x16x32_bf16 v[26:29], v[156:159], v[208:211], v[26:29]
	v_mfma_f32_16x16x32_bf16 v[10:13], v[156:159], v[216:219], v[10:13]
	v_mfma_f32_16x16x32_bf16 v[10:13], v[160:163], v[220:223], v[10:13]
	v_mfma_f32_16x16x32_bf16 v[26:29], v[160:163], v[212:215], v[26:29]
	v_mfma_f32_16x16x32_bf16 v[42:45], v[160:163], v[204:207], v[42:45]
	v_mfma_f32_16x16x32_bf16 v[58:61], v[160:163], v[196:199], v[58:61]
	v_mfma_f32_16x16x32_bf16 v[54:57], v[164:167], v[192:195], v[54:57]
	v_mfma_f32_16x16x32_bf16 v[38:41], v[164:167], v[200:203], v[38:41]
	v_mfma_f32_16x16x32_bf16 v[22:25], v[164:167], v[208:211], v[22:25]
	v_mfma_f32_16x16x32_bf16 v[6:9], v[164:167], v[216:219], v[6:9]
	v_mfma_f32_16x16x32_bf16 v[6:9], v[176:179], v[220:223], v[6:9]
	v_mfma_f32_16x16x32_bf16 v[22:25], v[176:179], v[212:215], v[22:25]
	v_mfma_f32_16x16x32_bf16 v[38:41], v[176:179], v[204:207], v[38:41]
	v_mfma_f32_16x16x32_bf16 v[54:57], v[176:179], v[196:199], v[54:57]
	v_mfma_f32_16x16x32_bf16 v[50:53], v[184:187], v[192:195], v[50:53]
	v_mfma_f32_16x16x32_bf16 v[34:37], v[184:187], v[200:203], v[34:37]
	v_mfma_f32_16x16x32_bf16 v[18:21], v[184:187], v[208:211], v[18:21]
	v_mfma_f32_16x16x32_bf16 v[2:5], v[184:187], v[216:219], v[2:5]
	s_barrier
	s_setprio 2
	v_mfma_f32_16x16x32_bf16 v[2:5], v[188:191], v[220:223], v[2:5]
	v_mfma_f32_16x16x32_bf16 v[18:21], v[188:191], v[212:215], v[18:21]
	v_mfma_f32_16x16x32_bf16 v[34:37], v[188:191], v[204:207], v[34:37]
	v_mfma_f32_16x16x32_bf16 v[50:53], v[188:191], v[196:199], v[50:53]
	s_setprio 0
	s_add_i32 s58, 0, 0x18000
	s_add_i32 s59, 0, 0x1c000
	v_add_u32_e32 v160, s58, v168
	v_add_u32_e32 v188, s59, v168
	ds_read_b128 v[130:133], v160
	ds_read_b128 v[134:137], v160 offset:1024
	ds_read_b128 v[156:159], v160 offset:2048
	ds_read_b128 v[160:163], v160 offset:3072
	ds_read_b128 v[164:167], v188
	ds_read_b128 v[176:179], v188 offset:1024
	ds_read_b128 v[184:187], v188 offset:2048
	ds_read_b128 v[188:191], v188 offset:3072
	s_mov_b32 m0, s34
	v_lshl_add_u64 v[226:227], v[224:225], 0, s[24:25]
	ds_read_b128 v[192:195], v173 offset:32768
	ds_read_b128 v[196:199], v173 offset:33792
	ds_read_b128 v[200:203], v173 offset:34816
	ds_read_b128 v[204:207], v173 offset:35840
	ds_read_b128 v[208:211], v173 offset:36864
	ds_read_b128 v[212:215], v173 offset:37888
	ds_read_b128 v[216:219], v173 offset:38912
	ds_read_b128 v[220:223], v173 offset:39936
	global_load_lds_dwordx4 v[226:227], off
	v_lshl_add_u64 v[226:227], v[224:225], 0, s[26:27]
	s_mov_b32 m0, s35
	s_nop 0
	global_load_lds_dwordx4 v[226:227], off
	s_waitcnt vmcnt(8)
	s_waitcnt lgkmcnt(0)
	s_barrier
	s_setprio 1
	s_waitcnt lgkmcnt(0)
	v_mfma_f32_16x16x32_bf16 v[126:129], v[130:133], v[192:195], v[126:129]
	v_mfma_f32_16x16x32_bf16 v[110:113], v[130:133], v[200:203], v[110:113]
	v_mfma_f32_16x16x32_bf16 v[94:97], v[130:133], v[208:211], v[94:97]
	v_mfma_f32_16x16x32_bf16 v[78:81], v[130:133], v[216:219], v[78:81]
	v_mfma_f32_16x16x32_bf16 v[78:81], v[134:137], v[220:223], v[78:81]
	v_mfma_f32_16x16x32_bf16 v[94:97], v[134:137], v[212:215], v[94:97]
	v_mfma_f32_16x16x32_bf16 v[110:113], v[134:137], v[204:207], v[110:113]
	v_mfma_f32_16x16x32_bf16 v[126:129], v[134:137], v[196:199], v[126:129]
	v_mfma_f32_16x16x32_bf16 v[122:125], v[156:159], v[192:195], v[122:125]
	v_mfma_f32_16x16x32_bf16 v[106:109], v[156:159], v[200:203], v[106:109]
	v_mfma_f32_16x16x32_bf16 v[90:93], v[156:159], v[208:211], v[90:93]
	v_mfma_f32_16x16x32_bf16 v[74:77], v[156:159], v[216:219], v[74:77]
	v_mfma_f32_16x16x32_bf16 v[74:77], v[160:163], v[220:223], v[74:77]
	v_mfma_f32_16x16x32_bf16 v[90:93], v[160:163], v[212:215], v[90:93]
	v_mfma_f32_16x16x32_bf16 v[106:109], v[160:163], v[204:207], v[106:109]
	v_mfma_f32_16x16x32_bf16 v[122:125], v[160:163], v[196:199], v[122:125]
	v_mfma_f32_16x16x32_bf16 v[118:121], v[164:167], v[192:195], v[118:121]
	v_mfma_f32_16x16x32_bf16 v[102:105], v[164:167], v[200:203], v[102:105]
	v_mfma_f32_16x16x32_bf16 v[86:89], v[164:167], v[208:211], v[86:89]
	v_mfma_f32_16x16x32_bf16 v[70:73], v[164:167], v[216:219], v[70:73]
	v_mfma_f32_16x16x32_bf16 v[70:73], v[176:179], v[220:223], v[70:73]
	v_mfma_f32_16x16x32_bf16 v[86:89], v[176:179], v[212:215], v[86:89]
	v_mfma_f32_16x16x32_bf16 v[102:105], v[176:179], v[204:207], v[102:105]
	v_mfma_f32_16x16x32_bf16 v[118:121], v[176:179], v[196:199], v[118:121]
	v_mfma_f32_16x16x32_bf16 v[114:117], v[184:187], v[192:195], v[114:117]
	v_mfma_f32_16x16x32_bf16 v[98:101], v[184:187], v[200:203], v[98:101]
	v_mfma_f32_16x16x32_bf16 v[82:85], v[184:187], v[208:211], v[82:85]
	v_mfma_f32_16x16x32_bf16 v[66:69], v[184:187], v[216:219], v[66:69]
	s_barrier
; #define PG8_STAGE(bufoff, gbase, voff) do { if constexpr (!pg8_noload<Epi>::value) { _Pragma("unroll") for (int _i = 0; _i < 2; ++_i) \
;         __builtin_amdgcn_global_load_lds((const unsigned*)((const char*)(gbase) + (size_t)_i * pstep + (voff)[0]), (PG8_LAS unsigned*)(lds + (bufoff) + ldsw + _i * 8192), 16, 0, 0); } } while (0)
; #define PG8_LDA(dst, b, h) do { _Pragma("unroll") for (int m = 0; m < 4; ++m) _Pragma("unroll") for (int k = 0; k < 2; ++k) dst[m][k] = *(const PG8_LAS bf16x8*)(lds + PG8_SA(b, h) + aoff + m * 2048 + k * 1024); } while (0)
; #define PG8_MMA(ai, bj, At, Bt) do { __builtin_amdgcn_s_setprio(1); _Pragma("unroll") for (int m = 0; m < 4; ++m) _Pragma("unroll") for (int n = 0; n < 2; ++n) _Pragma("unroll") for (int k = 0; k < 2; ++k) \
;         acc[ai][bj][m][n] = __builtin_amdgcn_mfma_f32_16x16x32_bf16(Bt[n][k], At[m][k], acc[ai][bj][m][n], 0, 0, 0); __builtin_amdgcn_s_setprio(0); } while (0)
; #define PG8_WAIT_V(n) asm volatile("s_waitcnt vmcnt(" #n ")" ::: "memory")
; #define PG8_WAIT_L(n) asm volatile("s_waitcnt lgkmcnt(" #n ")" ::: "memory")
; #define PG8_BAR __builtin_amdgcn_s_barrier()
; #define PG8_SCHED __builtin_amdgcn_sched_barrier(0)
; template <class Epi, class Sched, bool ALIGN_EPI = false, bool SP2 = false, bool ABLK = false>
; __device__ __forceinline__ void gemm_phase(PG8_LAS unsigned char* lds, const Gemm g, const Sched& S, const Epi& E) {
;     ...
;             PG8_WAIT_V(8); PG8_WAIT_L(0); PG8_BAR; PG8_MMA(0, 0, At, B0); PG8_MMA(0, 1, At, B1); PG8_BAR; PG8_SCHED;
;             PG8_LDA(At, 1, 1); PG8_STAGE(PG8_SB(1, 0), b3, voffB); PG8_STAGE(PG8_SB(1, 1), b3 + hstep, voffB); PG8_STAGE(PG8_SA(1, 0), a3, voffA);
;             PG8_WAIT_V(8); PG8_WAIT_L(0); PG8_BAR; PG8_MMA(1, 0, At, B0); PG8_MMA(1, 1, At, B1); PG8_BAR; PG8_SCHED;
	s_setprio 2
	v_mfma_f32_16x16x32_bf16 v[66:69], v[188:191], v[220:223], v[66:69]
	v_mfma_f32_16x16x32_bf16 v[82:85], v[188:191], v[212:215], v[82:85]
	v_mfma_f32_16x16x32_bf16 v[98:101], v[188:191], v[204:207], v[98:101]
	v_mfma_f32_16x16x32_bf16 v[114:117], v[188:191], v[196:199], v[114:117]
	s_setprio 0
	s_add_i32 s58, s58, s91
	v_lshl_add_u64 v[226:227], v[180:181], 0, s[92:93]
	s_mov_b32 m0, s58
	ds_read_b128 v[192:195], v173 offset:49152
	ds_read_b128 v[196:199], v173 offset:50176
	ds_read_b128 v[200:203], v173 offset:51200
	ds_read_b128 v[204:207], v173 offset:52224
	ds_read_b128 v[208:211], v173 offset:53248
	ds_read_b128 v[212:215], v173 offset:54272
	ds_read_b128 v[216:219], v173 offset:55296
	ds_read_b128 v[220:223], v173 offset:56320
	global_load_lds_dwordx4 v[226:227], off
	v_lshl_add_u64 v[226:227], v[180:181], 0, s[94:95]
	s_add_i32 m0, s58, 0x2000
	s_add_i32 s58, s59, s91
	global_load_lds_dwordx4 v[226:227], off
	v_lshl_add_u64 v[226:227], v[180:181], 0, s[96:97]
	s_mov_b32 m0, s58
	v_lshl_add_u64 v[180:181], v[180:181], 0, s[88:89]
	global_load_lds_dwordx4 v[226:227], off
	s_add_i32 m0, s58, 0x2000
	s_nop 0
	global_load_lds_dwordx4 v[180:181], off
	v_lshl_add_u64 v[180:181], v[224:225], 0, s[92:93]
	s_mov_b32 m0, s10
	s_nop 0
	global_load_lds_dwordx4 v[180:181], off
	v_lshl_add_u64 v[180:181], v[224:225], 0, s[94:95]
	s_mov_b32 m0, s11
	s_nop 0
	global_load_lds_dwordx4 v[180:181], off
	s_waitcnt vmcnt(8)
	s_waitcnt lgkmcnt(0)
	s_barrier
	s_setprio 1
	s_waitcnt lgkmcnt(0)
	v_mfma_f32_16x16x32_bf16 v[62:65], v[130:133], v[192:195], v[62:65]
	v_mfma_f32_16x16x32_bf16 v[46:49], v[130:133], v[200:203], v[46:49]
	v_mfma_f32_16x16x32_bf16 v[30:33], v[130:133], v[208:211], v[30:33]
	v_mfma_f32_16x16x32_bf16 v[14:17], v[130:133], v[216:219], v[14:17]
	v_mfma_f32_16x16x32_bf16 v[14:17], v[134:137], v[220:223], v[14:17]
	v_mfma_f32_16x16x32_bf16 v[30:33], v[134:137], v[212:215], v[30:33]
	v_mfma_f32_16x16x32_bf16 v[46:49], v[134:137], v[204:207], v[46:49]
	v_mfma_f32_16x16x32_bf16 v[62:65], v[134:137], v[196:199], v[62:65]
	v_mfma_f32_16x16x32_bf16 v[58:61], v[156:159], v[192:195], v[58:61]
	v_mfma_f32_16x16x32_bf16 v[42:45], v[156:159], v[200:203], v[42:45]
	v_mfma_f32_16x16x32_bf16 v[26:29], v[156:159], v[208:211], v[26:29]
	v_mfma_f32_16x16x32_bf16 v[10:13], v[156:159], v[216:219], v[10:13]
	v_mfma_f32_16x16x32_bf16 v[10:13], v[160:163], v[220:223], v[10:13]
	v_mfma_f32_16x16x32_bf16 v[26:29], v[160:163], v[212:215], v[26:29]
	v_mfma_f32_16x16x32_bf16 v[42:45], v[160:163], v[204:207], v[42:45]
	v_mfma_f32_16x16x32_bf16 v[58:61], v[160:163], v[196:199], v[58:61]
	v_mfma_f32_16x16x32_bf16 v[54:57], v[164:167], v[192:195], v[54:57]
	v_mfma_f32_16x16x32_bf16 v[38:41], v[164:167], v[200:203], v[38:41]
	v_mfma_f32_16x16x32_bf16 v[22:25], v[164:167], v[208:211], v[22:25]
	v_mfma_f32_16x16x32_bf16 v[6:9], v[164:167], v[216:219], v[6:9]
	v_mfma_f32_16x16x32_bf16 v[6:9], v[176:179], v[220:223], v[6:9]
	v_mfma_f32_16x16x32_bf16 v[22:25], v[176:179], v[212:215], v[22:25]
	v_mfma_f32_16x16x32_bf16 v[38:41], v[176:179], v[204:207], v[38:41]
	v_mfma_f32_16x16x32_bf16 v[54:57], v[176:179], v[196:199], v[54:57]
	v_mfma_f32_16x16x32_bf16 v[50:53], v[184:187], v[192:195], v[50:53]
	v_mfma_f32_16x16x32_bf16 v[34:37], v[184:187], v[200:203], v[34:37]
	v_mfma_f32_16x16x32_bf16 v[18:21], v[184:187], v[208:211], v[18:21]
	v_mfma_f32_16x16x32_bf16 v[2:5], v[184:187], v[216:219], v[2:5]
	s_barrier
	s_setprio 2
	v_mfma_f32_16x16x32_bf16 v[2:5], v[188:191], v[220:223], v[2:5]
	v_mfma_f32_16x16x32_bf16 v[18:21], v[188:191], v[212:215], v[18:21]
	v_mfma_f32_16x16x32_bf16 v[34:37], v[188:191], v[204:207], v[34:37]
	v_mfma_f32_16x16x32_bf16 v[50:53], v[188:191], v[196:199], v[50:53]
	s_setprio 0
	s_cmp_gt_u32 s57, 29
	s_mov_b32 s57, s28
	s_cbranch_scc1 .LBB0_631

; #define PG8_STAGE(bufoff, gbase, voff) do { if constexpr (!pg8_noload<Epi>::value) { _Pragma("unroll") for (int _i = 0; _i < 2; ++_i) \
;         __builtin_amdgcn_global_load_lds((const unsigned*)((const char*)(gbase) + (size_t)_i * pstep + (voff)[0]), (PG8_LAS unsigned*)(lds + (bufoff) + ldsw + _i * 8192), 16, 0, 0); } } while (0)
; #define PG8_LDA(dst, b, h) do { _Pragma("unroll") for (int m = 0; m < 4; ++m) _Pragma("unroll") for (int k = 0; k < 2; ++k) dst[m][k] = *(const PG8_LAS bf16x8*)(lds + PG8_SA(b, h) + aoff + m * 2048 + k * 1024); } while (0)
; #define PG8_LDB(dst, b, h) do { _Pragma("unroll") for (int n = 0; n < 2; ++n) _Pragma("unroll") for (int k = 0; k < 2; ++k) dst[n][k] = *(const PG8_LAS bf16x8*)(lds + PG8_SB(b, h) + boff + n * 2048 + k * 1024); } while (0)
; #define PG8_MMA(ai, bj, At, Bt) do { __builtin_amdgcn_s_setprio(1); _Pragma("unroll") for (int m = 0; m < 4; ++m) _Pragma("unroll") for (int n = 0; n < 2; ++n) _Pragma("unroll") for (int k = 0; k < 2; ++k) \
;         acc[ai][bj][m][n] = __builtin_amdgcn_mfma_f32_16x16x32_bf16(Bt[n][k], At[m][k], acc[ai][bj][m][n], 0, 0, 0); __builtin_amdgcn_s_setprio(0); } while (0)
; #define PG8_BAR __builtin_amdgcn_s_barrier()
; template <class Epi, class Sched, bool ALIGN_EPI = false, bool SP2 = false, bool ABLK = false>
; __device__ __forceinline__ void gemm_phase(PG8_LAS unsigned char* lds, const Gemm g, const Sched& S, const Epi& E) {
;     ...
;         for (int t = 0; t < nt; t += 2) {
;             const bool last = (t == nt - 2);
;             const char* a1 = cA + (size_t)(t + 1) * kstep;
;             const char* a2 = last ? nA : cA + (size_t)(t + 2) * kstep; const char* b2 = last ? nB : cB + (size_t)(t + 2) * kstepB;
;             const char* a3 = a2 + kstep; const char* b3 = b2 + kstepB;
;             if (last && has_next) S.a_ready(nxt);
;             if constexpr (SP2) {
;             PG8_LDB(B0, 0, 0); PG8_LDB(B1, 0, 1); PG8_SCHED; PG8_LDA(At, 0, 0); PG8_STAGE(PG8_SA(1, 1), a1 + hstep, voffA);
;             PG8_WAIT_V(8); PG8_WAIT_L(0); PG8_BAR; PG8_MMA(0, 0, At, B0); PG8_MMA(0, 1, At, B1); PG8_BAR; PG8_SCHED;
;             PG8_LDA(At, 0, 1); PG8_STAGE(PG8_SB(0, 0), b2, voffB); PG8_STAGE(PG8_SB(0, 1), b2 + hstep, voffB); PG8_STAGE(PG8_SA(0, 0), a2, voffA);
;             PG8_WAIT_V(8); PG8_WAIT_L(0); PG8_BAR; PG8_MMA(1, 0, At, B0); PG8_MMA(1, 1, At, B1); PG8_BAR; PG8_SCHED;
.LBB0_1533:
	ds_read_b128 v[114:117], v167
	ds_read_b128 v[126:129], v167 offset:1024
	ds_read_b128 v[130:133], v167 offset:2048
	ds_read_b128 v[142:145], v167 offset:3072
	ds_read_b128 v[146:149], v168
	ds_read_b128 v[150:153], v168 offset:1024
	ds_read_b128 v[174:177], v168 offset:2048
	ds_read_b128 v[178:181], v168 offset:3072
	s_add_i32 s41, s39, 2
	s_add_u32 s70, s68, 0xfff00800
	s_addc_u32 s71, s69, -1
	s_cmp_eq_u32 s3, s39
	s_cselect_b32 s71, s43, s71
	s_cselect_b32 s70, s42, s70
	s_cselect_b32 s81, s65, s37
	s_cselect_b32 s80, s64, s11
	v_lshl_add_u64 v[162:163], s[68:69], 0, v[158:159]
	s_add_i32 m0, s56, 0xc000
	ds_read_b128 v[184:187], v169
	ds_read_b128 v[188:191], v169 offset:1024
	ds_read_b128 v[192:195], v169 offset:2048
	ds_read_b128 v[196:199], v169 offset:3072
	ds_read_b128 v[200:203], v169 offset:4096
	ds_read_b128 v[204:207], v169 offset:5120
	ds_read_b128 v[208:211], v169 offset:6144
	ds_read_b128 v[212:215], v169 offset:7168
	global_load_lds_dwordx4 v[162:163], off
	v_lshl_add_u64 v[162:163], v[162:163], 0, s[12:13]
	s_add_i32 m0, s56, 0xe000
	s_nop 0
	global_load_lds_dwordx4 v[162:163], off
	s_waitcnt vmcnt(8)
	s_waitcnt lgkmcnt(0)
	s_barrier
	s_setprio 1
	s_waitcnt lgkmcnt(0)
	v_mfma_f32_16x16x32_bf16 v[138:141], v[114:117], v[184:187], v[138:141]
	v_mfma_f32_16x16x32_bf16 v[110:113], v[114:117], v[192:195], v[110:113]
	v_mfma_f32_16x16x32_bf16 v[94:97], v[114:117], v[200:203], v[94:97]
	v_mfma_f32_16x16x32_bf16 v[78:81], v[114:117], v[208:211], v[78:81]
	v_mfma_f32_16x16x32_bf16 v[78:81], v[126:129], v[212:215], v[78:81]
	v_mfma_f32_16x16x32_bf16 v[94:97], v[126:129], v[204:207], v[94:97]
	v_mfma_f32_16x16x32_bf16 v[110:113], v[126:129], v[196:199], v[110:113]
	v_mfma_f32_16x16x32_bf16 v[138:141], v[126:129], v[188:191], v[138:141]
	v_mfma_f32_16x16x32_bf16 v[134:137], v[130:133], v[184:187], v[134:137]
	v_mfma_f32_16x16x32_bf16 v[106:109], v[130:133], v[192:195], v[106:109]
	v_mfma_f32_16x16x32_bf16 v[90:93], v[130:133], v[200:203], v[90:93]
	v_mfma_f32_16x16x32_bf16 v[74:77], v[130:133], v[208:211], v[74:77]
	v_mfma_f32_16x16x32_bf16 v[74:77], v[142:145], v[212:215], v[74:77]
	v_mfma_f32_16x16x32_bf16 v[90:93], v[142:145], v[204:207], v[90:93]
	v_mfma_f32_16x16x32_bf16 v[106:109], v[142:145], v[196:199], v[106:109]
	v_mfma_f32_16x16x32_bf16 v[134:137], v[142:145], v[188:191], v[134:137]
	v_mfma_f32_16x16x32_bf16 v[122:125], v[146:149], v[184:187], v[122:125]
	v_mfma_f32_16x16x32_bf16 v[102:105], v[146:149], v[192:195], v[102:105]
	v_mfma_f32_16x16x32_bf16 v[86:89], v[146:149], v[200:203], v[86:89]
	v_mfma_f32_16x16x32_bf16 v[70:73], v[146:149], v[208:211], v[70:73]
	v_mfma_f32_16x16x32_bf16 v[70:73], v[150:153], v[212:215], v[70:73]
	v_mfma_f32_16x16x32_bf16 v[86:89], v[150:153], v[204:207], v[86:89]
	v_mfma_f32_16x16x32_bf16 v[102:105], v[150:153], v[196:199], v[102:105]
	v_mfma_f32_16x16x32_bf16 v[122:125], v[150:153], v[188:191], v[122:125]
	v_mfma_f32_16x16x32_bf16 v[118:121], v[174:177], v[184:187], v[118:121]
	v_mfma_f32_16x16x32_bf16 v[98:101], v[174:177], v[192:195], v[98:101]
	v_mfma_f32_16x16x32_bf16 v[82:85], v[174:177], v[200:203], v[82:85]
	v_mfma_f32_16x16x32_bf16 v[66:69], v[174:177], v[208:211], v[66:69]
	s_barrier
	s_setprio 2
	v_mfma_f32_16x16x32_bf16 v[66:69], v[178:181], v[212:215], v[66:69]
	v_mfma_f32_16x16x32_bf16 v[82:85], v[178:181], v[204:207], v[82:85]
	v_mfma_f32_16x16x32_bf16 v[98:101], v[178:181], v[196:199], v[98:101]
	v_mfma_f32_16x16x32_bf16 v[118:121], v[178:181], v[188:191], v[118:121]
	s_setprio 0
	s_add_i32 s39, s74, s55
	v_lshl_add_u64 v[162:163], s[80:81], 0, v[154:155]
	s_mov_b32 m0, s39
	ds_read_b128 v[184:187], v169 offset:16384
	ds_read_b128 v[188:191], v169 offset:17408
	ds_read_b128 v[192:195], v169 offset:18432
	ds_read_b128 v[196:199], v169 offset:19456
	ds_read_b128 v[200:203], v169 offset:20480
	ds_read_b128 v[204:207], v169 offset:21504
	ds_read_b128 v[208:211], v169 offset:22528
	ds_read_b128 v[212:215], v169 offset:23552
	global_load_lds_dwordx4 v[162:163], off
	v_lshl_add_u64 v[216:217], v[162:163], 0, s[12:13]
	s_add_i32 m0, s39, 0x2000
	s_add_i32 s39, s75, s55
	global_load_lds_dwordx4 v[216:217], off
	v_lshl_add_u64 v[216:217], v[162:163], 0, s[14:15]
	s_mov_b32 m0, s39
	s_nop 0
	global_load_lds_dwordx4 v[216:217], off
	v_lshl_add_u64 v[216:217], v[162:163], 0, s[16:17]
	s_add_i32 m0, s39, 0x2000
	s_nop 0
	global_load_lds_dwordx4 v[216:217], off
	v_lshl_add_u64 v[216:217], s[70:71], 0, v[154:155]
	s_mov_b32 m0, s56
	v_lshl_add_u64 v[218:219], v[216:217], 0, s[12:13]
	global_load_lds_dwordx4 v[216:217], off
	s_mov_b32 m0, s57
	s_nop 0
	global_load_lds_dwordx4 v[218:219], off
	s_waitcnt vmcnt(8)
	s_waitcnt lgkmcnt(0)
	s_barrier
; #define PG8_STAGE(bufoff, gbase, voff) do { if constexpr (!pg8_noload<Epi>::value) { _Pragma("unroll") for (int _i = 0; _i < 2; ++_i) \
;         __builtin_amdgcn_global_load_lds((const unsigned*)((const char*)(gbase) + (size_t)_i * pstep + (voff)[0]), (PG8_LAS unsigned*)(lds + (bufoff) + ldsw + _i * 8192), 16, 0, 0); } } while (0)
; #define PG8_LDA(dst, b, h) do { _Pragma("unroll") for (int m = 0; m < 4; ++m) _Pragma("unroll") for (int k = 0; k < 2; ++k) dst[m][k] = *(const PG8_LAS bf16x8*)(lds + PG8_SA(b, h) + aoff + m * 2048 + k * 1024); } while (0)
; #define PG8_LDB(dst, b, h) do { _Pragma("unroll") for (int n = 0; n < 2; ++n) _Pragma("unroll") for (int k = 0; k < 2; ++k) dst[n][k] = *(const PG8_LAS bf16x8*)(lds + PG8_SB(b, h) + boff + n * 2048 + k * 1024); } while (0)
; #define PG8_MMA(ai, bj, At, Bt) do { __builtin_amdgcn_s_setprio(1); _Pragma("unroll") for (int m = 0; m < 4; ++m) _Pragma("unroll") for (int n = 0; n < 2; ++n) _Pragma("unroll") for (int k = 0; k < 2; ++k) \
;         acc[ai][bj][m][n] = __builtin_amdgcn_mfma_f32_16x16x32_bf16(Bt[n][k], At[m][k], acc[ai][bj][m][n], 0, 0, 0); __builtin_amdgcn_s_setprio(0); } while (0)
; #define PG8_WAIT_V(n) asm volatile("s_waitcnt vmcnt(" #n ")" ::: "memory")
; #define PG8_WAIT_L(n) asm volatile("s_waitcnt lgkmcnt(" #n ")" ::: "memory")
; #define PG8_BAR __builtin_amdgcn_s_barrier()
; #define PG8_SCHED __builtin_amdgcn_sched_barrier(0)
; template <class Epi, class Sched, bool ALIGN_EPI = false, bool SP2 = false, bool ABLK = false>
; __device__ __forceinline__ void gemm_phase(PG8_LAS unsigned char* lds, const Gemm g, const Sched& S, const Epi& E) {
;     ...
;             PG8_WAIT_V(8); PG8_WAIT_L(0); PG8_BAR; PG8_MMA(0, 0, At, B0); PG8_MMA(0, 1, At, B1); PG8_BAR; PG8_SCHED;
;             PG8_LDA(At, 0, 1); PG8_STAGE(PG8_SB(0, 0), b2, voffB); PG8_STAGE(PG8_SB(0, 1), b2 + hstep, voffB); PG8_STAGE(PG8_SA(0, 0), a2, voffA);
;             PG8_WAIT_V(8); PG8_WAIT_L(0); PG8_BAR; PG8_MMA(1, 0, At, B0); PG8_MMA(1, 1, At, B1); PG8_BAR; PG8_SCHED;
;             PG8_LDB(B0, 1, 0); PG8_LDB(B1, 1, 1); PG8_SCHED; PG8_LDA(At, 1, 0); PG8_STAGE(PG8_SA(0, 1), a2 + hstep, voffA);
;             PG8_WAIT_V(8); PG8_WAIT_L(0); PG8_BAR; PG8_MMA(0, 0, At, B0); PG8_MMA(0, 1, At, B1); PG8_BAR; PG8_SCHED;
	s_setprio 1
	s_waitcnt lgkmcnt(0)
	v_mfma_f32_16x16x32_bf16 v[62:65], v[114:117], v[184:187], v[62:65]
	v_mfma_f32_16x16x32_bf16 v[46:49], v[114:117], v[192:195], v[46:49]
	v_mfma_f32_16x16x32_bf16 v[30:33], v[114:117], v[200:203], v[30:33]
	v_mfma_f32_16x16x32_bf16 v[14:17], v[114:117], v[208:211], v[14:17]
	v_mfma_f32_16x16x32_bf16 v[14:17], v[126:129], v[212:215], v[14:17]
	v_mfma_f32_16x16x32_bf16 v[30:33], v[126:129], v[204:207], v[30:33]
	v_mfma_f32_16x16x32_bf16 v[46:49], v[126:129], v[196:199], v[46:49]
	v_mfma_f32_16x16x32_bf16 v[62:65], v[126:129], v[188:191], v[62:65]
	v_mfma_f32_16x16x32_bf16 v[58:61], v[130:133], v[184:187], v[58:61]
	v_mfma_f32_16x16x32_bf16 v[42:45], v[130:133], v[192:195], v[42:45]
	v_mfma_f32_16x16x32_bf16 v[26:29], v[130:133], v[200:203], v[26:29]
	v_mfma_f32_16x16x32_bf16 v[10:13], v[130:133], v[208:211], v[10:13]
	v_mfma_f32_16x16x32_bf16 v[10:13], v[142:145], v[212:215], v[10:13]
	v_mfma_f32_16x16x32_bf16 v[26:29], v[142:145], v[204:207], v[26:29]
	v_mfma_f32_16x16x32_bf16 v[42:45], v[142:145], v[196:199], v[42:45]
	v_mfma_f32_16x16x32_bf16 v[58:61], v[142:145], v[188:191], v[58:61]
	v_mfma_f32_16x16x32_bf16 v[54:57], v[146:149], v[184:187], v[54:57]
	v_mfma_f32_16x16x32_bf16 v[38:41], v[146:149], v[192:195], v[38:41]
	v_mfma_f32_16x16x32_bf16 v[22:25], v[146:149], v[200:203], v[22:25]
	v_mfma_f32_16x16x32_bf16 v[6:9], v[146:149], v[208:211], v[6:9]
	v_mfma_f32_16x16x32_bf16 v[6:9], v[150:153], v[212:215], v[6:9]
	v_mfma_f32_16x16x32_bf16 v[22:25], v[150:153], v[204:207], v[22:25]
	v_mfma_f32_16x16x32_bf16 v[38:41], v[150:153], v[196:199], v[38:41]
	v_mfma_f32_16x16x32_bf16 v[54:57], v[150:153], v[188:191], v[54:57]
	v_mfma_f32_16x16x32_bf16 v[50:53], v[174:177], v[184:187], v[50:53]
	v_mfma_f32_16x16x32_bf16 v[34:37], v[174:177], v[192:195], v[34:37]
	v_mfma_f32_16x16x32_bf16 v[18:21], v[174:177], v[200:203], v[18:21]
	v_mfma_f32_16x16x32_bf16 v[2:5], v[174:177], v[208:211], v[2:5]
	s_barrier
	s_setprio 2
	v_mfma_f32_16x16x32_bf16 v[2:5], v[178:181], v[212:215], v[2:5]
	v_mfma_f32_16x16x32_bf16 v[18:21], v[178:181], v[204:207], v[18:21]
	v_mfma_f32_16x16x32_bf16 v[34:37], v[178:181], v[196:199], v[34:37]
	v_mfma_f32_16x16x32_bf16 v[50:53], v[178:181], v[188:191], v[50:53]
	s_setprio 0
	s_add_i32 s39, 0, 0x18000
	s_add_i32 s70, 0, 0x1c000
	v_add_u32_e32 v142, s39, v1
	v_add_u32_e32 v173, s70, v1
	ds_read_b128 v[114:117], v142
	ds_read_b128 v[126:129], v142 offset:1024
	ds_read_b128 v[130:133], v142 offset:2048
	ds_read_b128 v[142:145], v142 offset:3072
	ds_read_b128 v[146:149], v173
	ds_read_b128 v[150:153], v173 offset:1024
	ds_read_b128 v[174:177], v173 offset:2048
	ds_read_b128 v[178:181], v173 offset:3072
	s_mov_b32 m0, s58
	v_lshl_add_u64 v[218:219], v[216:217], 0, s[14:15]
	ds_read_b128 v[184:187], v169 offset:32768
	ds_read_b128 v[188:191], v169 offset:33792
	ds_read_b128 v[192:195], v169 offset:34816
	ds_read_b128 v[196:199], v169 offset:35840
	ds_read_b128 v[200:203], v169 offset:36864
	ds_read_b128 v[204:207], v169 offset:37888
	ds_read_b128 v[208:211], v169 offset:38912
	ds_read_b128 v[212:215], v169 offset:39936
	global_load_lds_dwordx4 v[218:219], off
	v_lshl_add_u64 v[218:219], v[216:217], 0, s[16:17]
	s_mov_b32 m0, s59
	s_nop 0
	global_load_lds_dwordx4 v[218:219], off
	s_waitcnt vmcnt(8)
	s_waitcnt lgkmcnt(0)
	s_barrier
	s_setprio 1
	s_waitcnt lgkmcnt(0)
	v_mfma_f32_16x16x32_bf16 v[138:141], v[114:117], v[184:187], v[138:141]
	v_mfma_f32_16x16x32_bf16 v[110:113], v[114:117], v[192:195], v[110:113]
	v_mfma_f32_16x16x32_bf16 v[94:97], v[114:117], v[200:203], v[94:97]
	v_mfma_f32_16x16x32_bf16 v[78:81], v[114:117], v[208:211], v[78:81]
	v_mfma_f32_16x16x32_bf16 v[78:81], v[126:129], v[212:215], v[78:81]
	v_mfma_f32_16x16x32_bf16 v[94:97], v[126:129], v[204:207], v[94:97]
	v_mfma_f32_16x16x32_bf16 v[110:113], v[126:129], v[196:199], v[110:113]
	v_mfma_f32_16x16x32_bf16 v[138:141], v[126:129], v[188:191], v[138:141]
	v_mfma_f32_16x16x32_bf16 v[134:137], v[130:133], v[184:187], v[134:137]
	v_mfma_f32_16x16x32_bf16 v[106:109], v[130:133], v[192:195], v[106:109]
	v_mfma_f32_16x16x32_bf16 v[90:93], v[130:133], v[200:203], v[90:93]
	v_mfma_f32_16x16x32_bf16 v[74:77], v[130:133], v[208:211], v[74:77]
	v_mfma_f32_16x16x32_bf16 v[74:77], v[142:145], v[212:215], v[74:77]
	v_mfma_f32_16x16x32_bf16 v[90:93], v[142:145], v[204:207], v[90:93]
	v_mfma_f32_16x16x32_bf16 v[106:109], v[142:145], v[196:199], v[106:109]
	v_mfma_f32_16x16x32_bf16 v[134:137], v[142:145], v[188:191], v[134:137]
	v_mfma_f32_16x16x32_bf16 v[122:125], v[146:149], v[184:187], v[122:125]
	v_mfma_f32_16x16x32_bf16 v[102:105], v[146:149], v[192:195], v[102:105]
	v_mfma_f32_16x16x32_bf16 v[86:89], v[146:149], v[200:203], v[86:89]
	v_mfma_f32_16x16x32_bf16 v[70:73], v[146:149], v[208:211], v[70:73]
	v_mfma_f32_16x16x32_bf16 v[70:73], v[150:153], v[212:215], v[70:73]
	v_mfma_f32_16x16x32_bf16 v[86:89], v[150:153], v[204:207], v[86:89]
	v_mfma_f32_16x16x32_bf16 v[102:105], v[150:153], v[196:199], v[102:105]
	v_mfma_f32_16x16x32_bf16 v[122:125], v[150:153], v[188:191], v[122:125]
	v_mfma_f32_16x16x32_bf16 v[118:121], v[174:177], v[184:187], v[118:121]
	v_mfma_f32_16x16x32_bf16 v[98:101], v[174:177], v[192:195], v[98:101]
	v_mfma_f32_16x16x32_bf16 v[82:85], v[174:177], v[200:203], v[82:85]
	v_mfma_f32_16x16x32_bf16 v[66:69], v[174:177], v[208:211], v[66:69]
	s_barrier
; #define PG8_STAGE(bufoff, gbase, voff) do { if constexpr (!pg8_noload<Epi>::value) { _Pragma("unroll") for (int _i = 0; _i < 2; ++_i) \
;         __builtin_amdgcn_global_load_lds((const unsigned*)((const char*)(gbase) + (size_t)_i * pstep + (voff)[0]), (PG8_LAS unsigned*)(lds + (bufoff) + ldsw + _i * 8192), 16, 0, 0); } } while (0)
; #define PG8_LDA(dst, b, h) do { _Pragma("unroll") for (int m = 0; m < 4; ++m) _Pragma("unroll") for (int k = 0; k < 2; ++k) dst[m][k] = *(const PG8_LAS bf16x8*)(lds + PG8_SA(b, h) + aoff + m * 2048 + k * 1024); } while (0)
; #define PG8_LDB(dst, b, h) do { _Pragma("unroll") for (int n = 0; n < 2; ++n) _Pragma("unroll") for (int k = 0; k < 2; ++k) dst[n][k] = *(const PG8_LAS bf16x8*)(lds + PG8_SB(b, h) + boff + n * 2048 + k * 1024); } while (0)
; #define PG8_WAIT_V(n) asm volatile("s_waitcnt vmcnt(" #n ")" ::: "memory")
; #define PG8_WAIT_L(n) asm volatile("s_waitcnt lgkmcnt(" #n ")" ::: "memory")
; #define PG8_BAR __builtin_amdgcn_s_barrier()
; #define PG8_SCHED __builtin_amdgcn_sched_barrier(0)
; template <class Epi, class Sched, bool ALIGN_EPI = false, bool SP2 = false, bool ABLK = false>
; __device__ __forceinline__ void gemm_phase(PG8_LAS unsigned char* lds, const Gemm g, const Sched& S, const Epi& E) {
;     ...
;         for (int t = 0; t < nt; t += 2) {
;             const bool last = (t == nt - 2);
;             const char* a1 = cA + (size_t)(t + 1) * kstep;
;             const char* a2 = last ? nA : cA + (size_t)(t + 2) * kstep; const char* b2 = last ? nB : cB + (size_t)(t + 2) * kstepB;
;             const char* a3 = a2 + kstep; const char* b3 = b2 + kstepB;
;             if (last && has_next) S.a_ready(nxt);
;     ...
;             PG8_WAIT_V(8); PG8_WAIT_L(0); PG8_BAR; PG8_MMA(1, 0, At, B0); PG8_MMA(1, 1, At, B1); PG8_BAR; PG8_SCHED;
;             PG8_LDB(B0, 1, 0); PG8_LDB(B1, 1, 1); PG8_SCHED; PG8_LDA(At, 1, 0); PG8_STAGE(PG8_SA(0, 1), a2 + hstep, voffA);
;             PG8_WAIT_V(8); PG8_WAIT_L(0); PG8_BAR; PG8_MMA(0, 0, At, B0); PG8_MMA(0, 1, At, B1); PG8_BAR; PG8_SCHED;
;             PG8_LDA(At, 1, 1); PG8_STAGE(PG8_SB(1, 0), b3, voffB); PG8_STAGE(PG8_SB(1, 1), b3 + hstep, voffB); PG8_STAGE(PG8_SA(1, 0), a3, voffA);
;             PG8_WAIT_V(8); PG8_WAIT_L(0); PG8_BAR; PG8_MMA(1, 0, At, B0); PG8_MMA(1, 1, At, B1); PG8_BAR; PG8_SCHED;
	s_setprio 2
	v_mfma_f32_16x16x32_bf16 v[66:69], v[178:181], v[212:215], v[66:69]
	v_mfma_f32_16x16x32_bf16 v[82:85], v[178:181], v[204:207], v[82:85]
	v_mfma_f32_16x16x32_bf16 v[98:101], v[178:181], v[196:199], v[98:101]
	v_mfma_f32_16x16x32_bf16 v[118:121], v[178:181], v[188:191], v[118:121]
	s_setprio 0
	s_add_i32 s39, s39, s55
	v_lshl_add_u64 v[218:219], v[162:163], 0, s[24:25]
	s_mov_b32 m0, s39
	ds_read_b128 v[184:187], v169 offset:49152
	ds_read_b128 v[188:191], v169 offset:50176
	ds_read_b128 v[192:195], v169 offset:51200
	ds_read_b128 v[196:199], v169 offset:52224
	ds_read_b128 v[200:203], v169 offset:53248
	ds_read_b128 v[204:207], v169 offset:54272
	ds_read_b128 v[208:211], v169 offset:55296
	ds_read_b128 v[212:215], v169 offset:56320
	global_load_lds_dwordx4 v[218:219], off
	v_lshl_add_u64 v[218:219], v[162:163], 0, s[26:27]
	s_add_i32 m0, s39, 0x2000
	s_add_i32 s39, s70, s55
	global_load_lds_dwordx4 v[218:219], off
	v_lshl_add_u64 v[218:219], v[162:163], 0, s[28:29]
	s_mov_b32 m0, s39
	v_lshl_add_u64 v[162:163], v[162:163], 0, s[30:31]
	global_load_lds_dwordx4 v[218:219], off
	s_add_i32 m0, s39, 0x2000
	s_nop 0
	global_load_lds_dwordx4 v[162:163], off
	v_lshl_add_u64 v[162:163], v[216:217], 0, s[24:25]
	s_mov_b32 m0, s62
	s_nop 0
	global_load_lds_dwordx4 v[162:163], off
	v_lshl_add_u64 v[162:163], v[216:217], 0, s[26:27]
	s_mov_b32 m0, s63
	s_nop 0
	global_load_lds_dwordx4 v[162:163], off
	s_waitcnt vmcnt(8)
	s_waitcnt lgkmcnt(0)
	s_barrier
	s_setprio 1
	s_waitcnt lgkmcnt(0)
	v_mfma_f32_16x16x32_bf16 v[62:65], v[114:117], v[184:187], v[62:65]
	v_mfma_f32_16x16x32_bf16 v[46:49], v[114:117], v[192:195], v[46:49]
	v_mfma_f32_16x16x32_bf16 v[30:33], v[114:117], v[200:203], v[30:33]
	v_mfma_f32_16x16x32_bf16 v[14:17], v[114:117], v[208:211], v[14:17]
	v_mfma_f32_16x16x32_bf16 v[14:17], v[126:129], v[212:215], v[14:17]
	v_mfma_f32_16x16x32_bf16 v[30:33], v[126:129], v[204:207], v[30:33]
	v_mfma_f32_16x16x32_bf16 v[46:49], v[126:129], v[196:199], v[46:49]
	v_mfma_f32_16x16x32_bf16 v[62:65], v[126:129], v[188:191], v[62:65]
	v_mfma_f32_16x16x32_bf16 v[58:61], v[130:133], v[184:187], v[58:61]
	v_mfma_f32_16x16x32_bf16 v[42:45], v[130:133], v[192:195], v[42:45]
	v_mfma_f32_16x16x32_bf16 v[26:29], v[130:133], v[200:203], v[26:29]
	v_mfma_f32_16x16x32_bf16 v[10:13], v[130:133], v[208:211], v[10:13]
	v_mfma_f32_16x16x32_bf16 v[10:13], v[142:145], v[212:215], v[10:13]
	v_mfma_f32_16x16x32_bf16 v[26:29], v[142:145], v[204:207], v[26:29]
	v_mfma_f32_16x16x32_bf16 v[42:45], v[142:145], v[196:199], v[42:45]
	v_mfma_f32_16x16x32_bf16 v[58:61], v[142:145], v[188:191], v[58:61]
	v_mfma_f32_16x16x32_bf16 v[54:57], v[146:149], v[184:187], v[54:57]
	v_mfma_f32_16x16x32_bf16 v[38:41], v[146:149], v[192:195], v[38:41]
	v_mfma_f32_16x16x32_bf16 v[22:25], v[146:149], v[200:203], v[22:25]
	v_mfma_f32_16x16x32_bf16 v[6:9], v[146:149], v[208:211], v[6:9]
	v_mfma_f32_16x16x32_bf16 v[6:9], v[150:153], v[212:215], v[6:9]
	v_mfma_f32_16x16x32_bf16 v[22:25], v[150:153], v[204:207], v[22:25]
	v_mfma_f32_16x16x32_bf16 v[38:41], v[150:153], v[196:199], v[38:41]
	v_mfma_f32_16x16x32_bf16 v[54:57], v[150:153], v[188:191], v[54:57]
	v_mfma_f32_16x16x32_bf16 v[50:53], v[174:177], v[184:187], v[50:53]
	v_mfma_f32_16x16x32_bf16 v[34:37], v[174:177], v[192:195], v[34:37]
	v_mfma_f32_16x16x32_bf16 v[18:21], v[174:177], v[200:203], v[18:21]
	v_mfma_f32_16x16x32_bf16 v[2:5], v[174:177], v[208:211], v[2:5]
	s_barrier
	s_setprio 2
	v_mfma_f32_16x16x32_bf16 v[2:5], v[178:181], v[212:215], v[2:5]
	v_mfma_f32_16x16x32_bf16 v[18:21], v[178:181], v[204:207], v[18:21]
	v_mfma_f32_16x16x32_bf16 v[34:37], v[178:181], v[196:199], v[34:37]
	v_mfma_f32_16x16x32_bf16 v[50:53], v[178:181], v[188:191], v[50:53]
	s_setprio 0
	s_add_u32 s68, s68, 0x1000
	s_addc_u32 s69, s69, 0
	s_add_u32 s11, s11, 0x1000
	s_addc_u32 s37, s37, 0
	s_cmp_ge_i32 s41, s79
	s_mov_b32 s39, s41
	s_cbranch_scc0 .LBB0_1533
	s_and_b64 vcc, exec, s[34:35]
	s_cbranch_vccnz .LBB0_1538
	s_lshl_b32 s11, s2, 8
	s_cmp_gt_i32 s2, 63
	s_mov_b64 s[68:69], -1
	s_cbranch_scc1 .LBB0_1539

; #define PG8_STAGE(bufoff, gbase, voff) do { if constexpr (!pg8_noload<Epi>::value) { _Pragma("unroll") for (int _i = 0; _i < 2; ++_i) \
;         __builtin_amdgcn_global_load_lds((const unsigned*)((const char*)(gbase) + (size_t)_i * pstep + (voff)[0]), (PG8_LAS unsigned*)(lds + (bufoff) + ldsw + _i * 8192), 16, 0, 0); } } while (0)
; #define PG8_LDA(dst, b, h) do { _Pragma("unroll") for (int m = 0; m < 4; ++m) _Pragma("unroll") for (int k = 0; k < 2; ++k) dst[m][k] = *(const PG8_LAS bf16x8*)(lds + PG8_SA(b, h) + aoff + m * 2048 + k * 1024); } while (0)
; #define PG8_LDB(dst, b, h) do { _Pragma("unroll") for (int n = 0; n < 2; ++n) _Pragma("unroll") for (int k = 0; k < 2; ++k) dst[n][k] = *(const PG8_LAS bf16x8*)(lds + PG8_SB(b, h) + boff + n * 2048 + k * 1024); } while (0)
; #define PG8_MMA(ai, bj, At, Bt) do { __builtin_amdgcn_s_setprio(1); _Pragma("unroll") for (int m = 0; m < 4; ++m) _Pragma("unroll") for (int n = 0; n < 2; ++n) _Pragma("unroll") for (int k = 0; k < 2; ++k) \
;         acc[ai][bj][m][n] = __builtin_amdgcn_mfma_f32_16x16x32_bf16(Bt[n][k], At[m][k], acc[ai][bj][m][n], 0, 0, 0); __builtin_amdgcn_s_setprio(0); } while (0)
; #define PG8_BAR __builtin_amdgcn_s_barrier()
; template <class Epi, class Sched, bool ALIGN_EPI = false, bool SP2 = false, bool ABLK = false>
; __device__ __forceinline__ void gemm_phase(PG8_LAS unsigned char* lds, const Gemm g, const Sched& S, const Epi& E) {
;     ...
;         for (int t = 0; t < nt; t += 2) {
;             const bool last = (t == nt - 2);
;             const char* a1 = cA + (size_t)(t + 1) * kstep;
;             const char* a2 = last ? nA : cA + (size_t)(t + 2) * kstep; const char* b2 = last ? nB : cB + (size_t)(t + 2) * kstepB;
;             const char* a3 = a2 + kstep; const char* b3 = b2 + kstepB;
;             if (last && has_next) S.a_ready(nxt);
;             if constexpr (SP2) {
;             PG8_LDB(B0, 0, 0); PG8_LDB(B1, 0, 1); PG8_SCHED; PG8_LDA(At, 0, 0); PG8_STAGE(PG8_SA(1, 1), a1 + hstep, voffA);
;             PG8_WAIT_V(8); PG8_WAIT_L(0); PG8_BAR; PG8_MMA(0, 0, At, B0); PG8_MMA(0, 1, At, B1); PG8_BAR; PG8_SCHED;
;             PG8_LDA(At, 0, 1); PG8_STAGE(PG8_SB(0, 0), b2, voffB); PG8_STAGE(PG8_SB(0, 1), b2 + hstep, voffB); PG8_STAGE(PG8_SA(0, 0), a2, voffA);
;             PG8_WAIT_V(8); PG8_WAIT_L(0); PG8_BAR; PG8_MMA(1, 0, At, B0); PG8_MMA(1, 1, At, B1); PG8_BAR; PG8_SCHED;
.LBB0_1657:
	s_or_b32 s26, s94, 1
	s_lshl_b64 s[82:83], s[26:27], 11
	s_add_u32 s88, s74, s82
	v_add_u32_e32 v140, s12, v173
	s_addc_u32 s89, s75, s83
	s_add_i32 s26, s94, 2
	ds_read_b128 v[130:133], v140
	ds_read_b128 v[134:137], v140 offset:1024
	ds_read_b128 v[154:157], v140 offset:2048
	ds_read_b128 v[158:161], v140 offset:3072
	v_add_u32_e32 v140, s13, v173
	s_lshl_b64 s[90:91], s[26:27], 11
	ds_read_b128 v[162:165], v140
	ds_read_b128 v[166:169], v140 offset:1024
	ds_read_b128 v[184:187], v140 offset:2048
	ds_read_b128 v[188:191], v140 offset:3072
	s_add_u32 s92, s74, s90
	s_addc_u32 s93, s75, s91
	s_and_b64 s[82:83], s[80:81], exec
	s_cselect_b32 s83, s93, s3
	s_cselect_b32 s82, s92, s25
	s_add_u32 s90, s76, s90
	s_addc_u32 s91, s77, s91
	s_and_b64 s[80:81], s[80:81], exec
	s_cselect_b32 s81, s91, s65
	s_cselect_b32 s80, s90, s67
	v_lshl_add_u64 v[170:171], s[88:89], 0, v[138:139]
	v_lshl_add_u64 v[224:225], v[170:171], 0, s[20:21]
	s_add_i32 m0, s56, 0xc000
	ds_read_b128 v[192:195], v178
	ds_read_b128 v[196:199], v178 offset:1024
	ds_read_b128 v[200:203], v178 offset:2048
	ds_read_b128 v[204:207], v178 offset:3072
	ds_read_b128 v[208:211], v178 offset:4096
	ds_read_b128 v[212:215], v178 offset:5120
	ds_read_b128 v[216:219], v178 offset:6144
	ds_read_b128 v[220:223], v178 offset:7168
	global_load_lds_dwordx4 v[224:225], off
	v_lshl_add_u64 v[170:171], v[170:171], 0, s[22:23]
	s_add_i32 m0, s56, 0xe000
	s_nop 0
	global_load_lds_dwordx4 v[170:171], off
	s_waitcnt vmcnt(8)
	s_waitcnt lgkmcnt(0)
	s_barrier
	s_setprio 1
	s_waitcnt lgkmcnt(0)
	v_mfma_f32_16x16x32_bf16 v[126:129], v[130:133], v[192:195], v[126:129]
	v_mfma_f32_16x16x32_bf16 v[110:113], v[130:133], v[200:203], v[110:113]
	v_mfma_f32_16x16x32_bf16 v[94:97], v[130:133], v[208:211], v[94:97]
	v_mfma_f32_16x16x32_bf16 v[78:81], v[130:133], v[216:219], v[78:81]
	v_mfma_f32_16x16x32_bf16 v[78:81], v[134:137], v[220:223], v[78:81]
	v_mfma_f32_16x16x32_bf16 v[94:97], v[134:137], v[212:215], v[94:97]
	v_mfma_f32_16x16x32_bf16 v[110:113], v[134:137], v[204:207], v[110:113]
	v_mfma_f32_16x16x32_bf16 v[126:129], v[134:137], v[196:199], v[126:129]
	v_mfma_f32_16x16x32_bf16 v[122:125], v[154:157], v[192:195], v[122:125]
	v_mfma_f32_16x16x32_bf16 v[106:109], v[154:157], v[200:203], v[106:109]
	v_mfma_f32_16x16x32_bf16 v[90:93], v[154:157], v[208:211], v[90:93]
	v_mfma_f32_16x16x32_bf16 v[74:77], v[154:157], v[216:219], v[74:77]
	v_mfma_f32_16x16x32_bf16 v[74:77], v[158:161], v[220:223], v[74:77]
	v_mfma_f32_16x16x32_bf16 v[90:93], v[158:161], v[212:215], v[90:93]
	v_mfma_f32_16x16x32_bf16 v[106:109], v[158:161], v[204:207], v[106:109]
	v_mfma_f32_16x16x32_bf16 v[122:125], v[158:161], v[196:199], v[122:125]
	v_mfma_f32_16x16x32_bf16 v[118:121], v[162:165], v[192:195], v[118:121]
	v_mfma_f32_16x16x32_bf16 v[102:105], v[162:165], v[200:203], v[102:105]
	v_mfma_f32_16x16x32_bf16 v[86:89], v[162:165], v[208:211], v[86:89]
	v_mfma_f32_16x16x32_bf16 v[70:73], v[162:165], v[216:219], v[70:73]
	v_mfma_f32_16x16x32_bf16 v[70:73], v[166:169], v[220:223], v[70:73]
	v_mfma_f32_16x16x32_bf16 v[86:89], v[166:169], v[212:215], v[86:89]
	v_mfma_f32_16x16x32_bf16 v[102:105], v[166:169], v[204:207], v[102:105]
	v_mfma_f32_16x16x32_bf16 v[118:121], v[166:169], v[196:199], v[118:121]
	v_mfma_f32_16x16x32_bf16 v[114:117], v[184:187], v[192:195], v[114:117]
	v_mfma_f32_16x16x32_bf16 v[98:101], v[184:187], v[200:203], v[98:101]
	v_mfma_f32_16x16x32_bf16 v[82:85], v[184:187], v[208:211], v[82:85]
	v_mfma_f32_16x16x32_bf16 v[66:69], v[184:187], v[216:219], v[66:69]
	s_barrier
	s_setprio 2
	v_mfma_f32_16x16x32_bf16 v[66:69], v[188:191], v[220:223], v[66:69]
	v_mfma_f32_16x16x32_bf16 v[82:85], v[188:191], v[212:215], v[82:85]
	v_mfma_f32_16x16x32_bf16 v[98:101], v[188:191], v[204:207], v[98:101]
	v_mfma_f32_16x16x32_bf16 v[114:117], v[188:191], v[196:199], v[114:117]
	s_setprio 0
	v_lshl_add_u64 v[170:171], s[80:81], 0, v[138:139]
	s_add_i32 s80, s12, s55
	s_mov_b32 m0, s80
	ds_read_b128 v[192:195], v178 offset:16384
	ds_read_b128 v[196:199], v178 offset:17408
	ds_read_b128 v[200:203], v178 offset:18432
	ds_read_b128 v[204:207], v178 offset:19456
	ds_read_b128 v[208:211], v178 offset:20480
	ds_read_b128 v[212:215], v178 offset:21504
	ds_read_b128 v[216:219], v178 offset:22528
	ds_read_b128 v[220:223], v178 offset:23552
	global_load_lds_dwordx4 v[170:171], off
	v_lshl_add_u64 v[224:225], v[170:171], 0, s[18:19]
	s_add_i32 m0, s80, 0x2000
	s_add_i32 s80, s13, s55
	global_load_lds_dwordx4 v[224:225], off
	v_lshl_add_u64 v[224:225], v[170:171], 0, s[20:21]
	s_mov_b32 m0, s80
	s_nop 0
	global_load_lds_dwordx4 v[224:225], off
	v_lshl_add_u64 v[224:225], v[170:171], 0, s[22:23]
	s_add_i32 m0, s80, 0x2000
	s_nop 0
	global_load_lds_dwordx4 v[224:225], off
	v_lshl_add_u64 v[224:225], s[82:83], 0, v[138:139]
	s_mov_b32 m0, s56
	v_lshl_add_u64 v[226:227], v[224:225], 0, s[18:19]
	global_load_lds_dwordx4 v[224:225], off
	s_mov_b32 m0, s57
	s_nop 0
	global_load_lds_dwordx4 v[226:227], off
	s_waitcnt vmcnt(8)
	s_waitcnt lgkmcnt(0)
	s_barrier
; #define PG8_STAGE(bufoff, gbase, voff) do { if constexpr (!pg8_noload<Epi>::value) { _Pragma("unroll") for (int _i = 0; _i < 2; ++_i) \
;         __builtin_amdgcn_global_load_lds((const unsigned*)((const char*)(gbase) + (size_t)_i * pstep + (voff)[0]), (PG8_LAS unsigned*)(lds + (bufoff) + ldsw + _i * 8192), 16, 0, 0); } } while (0)
; #define PG8_LDA(dst, b, h) do { _Pragma("unroll") for (int m = 0; m < 4; ++m) _Pragma("unroll") for (int k = 0; k < 2; ++k) dst[m][k] = *(const PG8_LAS bf16x8*)(lds + PG8_SA(b, h) + aoff + m * 2048 + k * 1024); } while (0)
; #define PG8_LDB(dst, b, h) do { _Pragma("unroll") for (int n = 0; n < 2; ++n) _Pragma("unroll") for (int k = 0; k < 2; ++k) dst[n][k] = *(const PG8_LAS bf16x8*)(lds + PG8_SB(b, h) + boff + n * 2048 + k * 1024); } while (0)
; #define PG8_MMA(ai, bj, At, Bt) do { __builtin_amdgcn_s_setprio(1); _Pragma("unroll") for (int m = 0; m < 4; ++m) _Pragma("unroll") for (int n = 0; n < 2; ++n) _Pragma("unroll") for (int k = 0; k < 2; ++k) \
;         acc[ai][bj][m][n] = __builtin_amdgcn_mfma_f32_16x16x32_bf16(Bt[n][k], At[m][k], acc[ai][bj][m][n], 0, 0, 0); __builtin_amdgcn_s_setprio(0); } while (0)
; #define PG8_WAIT_V(n) asm volatile("s_waitcnt vmcnt(" #n ")" ::: "memory")
; #define PG8_WAIT_L(n) asm volatile("s_waitcnt lgkmcnt(" #n ")" ::: "memory")
; #define PG8_BAR __builtin_amdgcn_s_barrier()
; #define PG8_SCHED __builtin_amdgcn_sched_barrier(0)
; template <class Epi, class Sched, bool ALIGN_EPI = false, bool SP2 = false, bool ABLK = false>
; __device__ __forceinline__ void gemm_phase(PG8_LAS unsigned char* lds, const Gemm g, const Sched& S, const Epi& E) {
;     ...
;             PG8_WAIT_V(8); PG8_WAIT_L(0); PG8_BAR; PG8_MMA(0, 0, At, B0); PG8_MMA(0, 1, At, B1); PG8_BAR; PG8_SCHED;
;             PG8_LDA(At, 0, 1); PG8_STAGE(PG8_SB(0, 0), b2, voffB); PG8_STAGE(PG8_SB(0, 1), b2 + hstep, voffB); PG8_STAGE(PG8_SA(0, 0), a2, voffA);
;             PG8_WAIT_V(8); PG8_WAIT_L(0); PG8_BAR; PG8_MMA(1, 0, At, B0); PG8_MMA(1, 1, At, B1); PG8_BAR; PG8_SCHED;
;             PG8_LDB(B0, 1, 0); PG8_LDB(B1, 1, 1); PG8_SCHED; PG8_LDA(At, 1, 0); PG8_STAGE(PG8_SA(0, 1), a2 + hstep, voffA);
;             PG8_WAIT_V(8); PG8_WAIT_L(0); PG8_BAR; PG8_MMA(0, 0, At, B0); PG8_MMA(0, 1, At, B1); PG8_BAR; PG8_SCHED;
	s_setprio 1
	s_waitcnt lgkmcnt(0)
	v_mfma_f32_16x16x32_bf16 v[62:65], v[130:133], v[192:195], v[62:65]
	v_mfma_f32_16x16x32_bf16 v[46:49], v[130:133], v[200:203], v[46:49]
	v_mfma_f32_16x16x32_bf16 v[30:33], v[130:133], v[208:211], v[30:33]
	v_mfma_f32_16x16x32_bf16 v[14:17], v[130:133], v[216:219], v[14:17]
	v_mfma_f32_16x16x32_bf16 v[14:17], v[134:137], v[220:223], v[14:17]
	v_mfma_f32_16x16x32_bf16 v[30:33], v[134:137], v[212:215], v[30:33]
	v_mfma_f32_16x16x32_bf16 v[46:49], v[134:137], v[204:207], v[46:49]
	v_mfma_f32_16x16x32_bf16 v[62:65], v[134:137], v[196:199], v[62:65]
	v_mfma_f32_16x16x32_bf16 v[58:61], v[154:157], v[192:195], v[58:61]
	v_mfma_f32_16x16x32_bf16 v[42:45], v[154:157], v[200:203], v[42:45]
	v_mfma_f32_16x16x32_bf16 v[26:29], v[154:157], v[208:211], v[26:29]
	v_mfma_f32_16x16x32_bf16 v[10:13], v[154:157], v[216:219], v[10:13]
	v_mfma_f32_16x16x32_bf16 v[10:13], v[158:161], v[220:223], v[10:13]
	v_mfma_f32_16x16x32_bf16 v[26:29], v[158:161], v[212:215], v[26:29]
	v_mfma_f32_16x16x32_bf16 v[42:45], v[158:161], v[204:207], v[42:45]
	v_mfma_f32_16x16x32_bf16 v[58:61], v[158:161], v[196:199], v[58:61]
	v_mfma_f32_16x16x32_bf16 v[54:57], v[162:165], v[192:195], v[54:57]
	v_mfma_f32_16x16x32_bf16 v[38:41], v[162:165], v[200:203], v[38:41]
	v_mfma_f32_16x16x32_bf16 v[22:25], v[162:165], v[208:211], v[22:25]
	v_mfma_f32_16x16x32_bf16 v[6:9], v[162:165], v[216:219], v[6:9]
	v_mfma_f32_16x16x32_bf16 v[6:9], v[166:169], v[220:223], v[6:9]
	v_mfma_f32_16x16x32_bf16 v[22:25], v[166:169], v[212:215], v[22:25]
	v_mfma_f32_16x16x32_bf16 v[38:41], v[166:169], v[204:207], v[38:41]
	v_mfma_f32_16x16x32_bf16 v[54:57], v[166:169], v[196:199], v[54:57]
	v_mfma_f32_16x16x32_bf16 v[50:53], v[184:187], v[192:195], v[50:53]
	v_mfma_f32_16x16x32_bf16 v[34:37], v[184:187], v[200:203], v[34:37]
	v_mfma_f32_16x16x32_bf16 v[18:21], v[184:187], v[208:211], v[18:21]
	v_mfma_f32_16x16x32_bf16 v[2:5], v[184:187], v[216:219], v[2:5]
	s_barrier
	s_setprio 2
	v_mfma_f32_16x16x32_bf16 v[2:5], v[188:191], v[220:223], v[2:5]
	v_mfma_f32_16x16x32_bf16 v[18:21], v[188:191], v[212:215], v[18:21]
	v_mfma_f32_16x16x32_bf16 v[34:37], v[188:191], v[204:207], v[34:37]
	v_mfma_f32_16x16x32_bf16 v[50:53], v[188:191], v[196:199], v[50:53]
	s_setprio 0
	s_add_i32 s80, 0, 0x18000
	v_add_u32_e32 v140, s80, v173
	s_add_i32 s81, 0, 0x1c000
	ds_read_b128 v[130:133], v140
	ds_read_b128 v[134:137], v140 offset:1024
	ds_read_b128 v[154:157], v140 offset:2048
	ds_read_b128 v[158:161], v140 offset:3072
	v_add_u32_e32 v140, s81, v173
	ds_read_b128 v[162:165], v140
	ds_read_b128 v[166:169], v140 offset:1024
	ds_read_b128 v[184:187], v140 offset:2048
	ds_read_b128 v[188:191], v140 offset:3072
	s_mov_b32 m0, s58
	v_lshl_add_u64 v[226:227], v[224:225], 0, s[20:21]
	ds_read_b128 v[192:195], v178 offset:32768
	ds_read_b128 v[196:199], v178 offset:33792
	ds_read_b128 v[200:203], v178 offset:34816
	ds_read_b128 v[204:207], v178 offset:35840
	ds_read_b128 v[208:211], v178 offset:36864
	ds_read_b128 v[212:215], v178 offset:37888
	ds_read_b128 v[216:219], v178 offset:38912
	ds_read_b128 v[220:223], v178 offset:39936
	global_load_lds_dwordx4 v[226:227], off
	v_lshl_add_u64 v[226:227], v[224:225], 0, s[22:23]
	s_mov_b32 m0, s59
	s_nop 0
	global_load_lds_dwordx4 v[226:227], off
	s_waitcnt vmcnt(8)
	s_waitcnt lgkmcnt(0)
	s_barrier
	s_setprio 1
	s_waitcnt lgkmcnt(0)
	v_mfma_f32_16x16x32_bf16 v[126:129], v[130:133], v[192:195], v[126:129]
	v_mfma_f32_16x16x32_bf16 v[110:113], v[130:133], v[200:203], v[110:113]
	v_mfma_f32_16x16x32_bf16 v[94:97], v[130:133], v[208:211], v[94:97]
	v_mfma_f32_16x16x32_bf16 v[78:81], v[130:133], v[216:219], v[78:81]
	v_mfma_f32_16x16x32_bf16 v[78:81], v[134:137], v[220:223], v[78:81]
	v_mfma_f32_16x16x32_bf16 v[94:97], v[134:137], v[212:215], v[94:97]
	v_mfma_f32_16x16x32_bf16 v[110:113], v[134:137], v[204:207], v[110:113]
	v_mfma_f32_16x16x32_bf16 v[126:129], v[134:137], v[196:199], v[126:129]
	v_mfma_f32_16x16x32_bf16 v[122:125], v[154:157], v[192:195], v[122:125]
	v_mfma_f32_16x16x32_bf16 v[106:109], v[154:157], v[200:203], v[106:109]
	v_mfma_f32_16x16x32_bf16 v[90:93], v[154:157], v[208:211], v[90:93]
	v_mfma_f32_16x16x32_bf16 v[74:77], v[154:157], v[216:219], v[74:77]
	v_mfma_f32_16x16x32_bf16 v[74:77], v[158:161], v[220:223], v[74:77]
	v_mfma_f32_16x16x32_bf16 v[90:93], v[158:161], v[212:215], v[90:93]
	v_mfma_f32_16x16x32_bf16 v[106:109], v[158:161], v[204:207], v[106:109]
	v_mfma_f32_16x16x32_bf16 v[122:125], v[158:161], v[196:199], v[122:125]
	v_mfma_f32_16x16x32_bf16 v[118:121], v[162:165], v[192:195], v[118:121]
	v_mfma_f32_16x16x32_bf16 v[102:105], v[162:165], v[200:203], v[102:105]
	v_mfma_f32_16x16x32_bf16 v[86:89], v[162:165], v[208:211], v[86:89]
	v_mfma_f32_16x16x32_bf16 v[70:73], v[162:165], v[216:219], v[70:73]
	v_mfma_f32_16x16x32_bf16 v[70:73], v[166:169], v[220:223], v[70:73]
	v_mfma_f32_16x16x32_bf16 v[86:89], v[166:169], v[212:215], v[86:89]
	v_mfma_f32_16x16x32_bf16 v[102:105], v[166:169], v[204:207], v[102:105]
	v_mfma_f32_16x16x32_bf16 v[118:121], v[166:169], v[196:199], v[118:121]
	v_mfma_f32_16x16x32_bf16 v[114:117], v[184:187], v[192:195], v[114:117]
	v_mfma_f32_16x16x32_bf16 v[98:101], v[184:187], v[200:203], v[98:101]
	v_mfma_f32_16x16x32_bf16 v[82:85], v[184:187], v[208:211], v[82:85]
	v_mfma_f32_16x16x32_bf16 v[66:69], v[184:187], v[216:219], v[66:69]
	s_barrier
; #define PG8_STAGE(bufoff, gbase, voff) do { if constexpr (!pg8_noload<Epi>::value) { _Pragma("unroll") for (int _i = 0; _i < 2; ++_i) \
;         __builtin_amdgcn_global_load_lds((const unsigned*)((const char*)(gbase) + (size_t)_i * pstep + (voff)[0]), (PG8_LAS unsigned*)(lds + (bufoff) + ldsw + _i * 8192), 16, 0, 0); } } while (0)
; #define PG8_LDA(dst, b, h) do { _Pragma("unroll") for (int m = 0; m < 4; ++m) _Pragma("unroll") for (int k = 0; k < 2; ++k) dst[m][k] = *(const PG8_LAS bf16x8*)(lds + PG8_SA(b, h) + aoff + m * 2048 + k * 1024); } while (0)
; #define PG8_LDB(dst, b, h) do { _Pragma("unroll") for (int n = 0; n < 2; ++n) _Pragma("unroll") for (int k = 0; k < 2; ++k) dst[n][k] = *(const PG8_LAS bf16x8*)(lds + PG8_SB(b, h) + boff + n * 2048 + k * 1024); } while (0)
; #define PG8_MMA(ai, bj, At, Bt) do { __builtin_amdgcn_s_setprio(1); _Pragma("unroll") for (int m = 0; m < 4; ++m) _Pragma("unroll") for (int n = 0; n < 2; ++n) _Pragma("unroll") for (int k = 0; k < 2; ++k) \
;         acc[ai][bj][m][n] = __builtin_amdgcn_mfma_f32_16x16x32_bf16(Bt[n][k], At[m][k], acc[ai][bj][m][n], 0, 0, 0); __builtin_amdgcn_s_setprio(0); } while (0)
; #define PG8_WAIT_V(n) asm volatile("s_waitcnt vmcnt(" #n ")" ::: "memory")
; #define PG8_WAIT_L(n) asm volatile("s_waitcnt lgkmcnt(" #n ")" ::: "memory")
; #define PG8_BAR __builtin_amdgcn_s_barrier()
; #define PG8_SCHED __builtin_amdgcn_sched_barrier(0)
; template <class Epi, class Sched, bool ALIGN_EPI = false, bool SP2 = false, bool ABLK = false>
; __device__ __forceinline__ void gemm_phase(PG8_LAS unsigned char* lds, const Gemm g, const Sched& S, const Epi& E) {
;     ...
;             PG8_WAIT_V(8); PG8_WAIT_L(0); PG8_BAR; PG8_MMA(1, 0, At, B0); PG8_MMA(1, 1, At, B1); PG8_BAR; PG8_SCHED;
;             PG8_LDB(B0, 1, 0); PG8_LDB(B1, 1, 1); PG8_SCHED; PG8_LDA(At, 1, 0); PG8_STAGE(PG8_SA(0, 1), a2 + hstep, voffA);
;             PG8_WAIT_V(8); PG8_WAIT_L(0); PG8_BAR; PG8_MMA(0, 0, At, B0); PG8_MMA(0, 1, At, B1); PG8_BAR; PG8_SCHED;
;             PG8_LDA(At, 1, 1); PG8_STAGE(PG8_SB(1, 0), b3, voffB); PG8_STAGE(PG8_SB(1, 1), b3 + hstep, voffB); PG8_STAGE(PG8_SA(1, 0), a3, voffA);
;             PG8_WAIT_V(8); PG8_WAIT_L(0); PG8_BAR; PG8_MMA(1, 0, At, B0); PG8_MMA(1, 1, At, B1); PG8_BAR; PG8_SCHED;
	s_setprio 2
	v_mfma_f32_16x16x32_bf16 v[66:69], v[188:191], v[220:223], v[66:69]
	v_mfma_f32_16x16x32_bf16 v[82:85], v[188:191], v[212:215], v[82:85]
	v_mfma_f32_16x16x32_bf16 v[98:101], v[188:191], v[204:207], v[98:101]
	v_mfma_f32_16x16x32_bf16 v[114:117], v[188:191], v[196:199], v[114:117]
	s_setprio 0
	s_add_i32 s80, s80, s55
	v_lshl_add_u64 v[226:227], v[170:171], 0, s[30:31]
	s_mov_b32 m0, s80
	ds_read_b128 v[192:195], v178 offset:49152
	ds_read_b128 v[196:199], v178 offset:50176
	ds_read_b128 v[200:203], v178 offset:51200
	ds_read_b128 v[204:207], v178 offset:52224
	ds_read_b128 v[208:211], v178 offset:53248
	ds_read_b128 v[212:215], v178 offset:54272
	ds_read_b128 v[216:219], v178 offset:55296
	ds_read_b128 v[220:223], v178 offset:56320
	global_load_lds_dwordx4 v[226:227], off
	v_lshl_add_u64 v[226:227], v[170:171], 0, s[34:35]
	s_add_i32 m0, s80, 0x2000
	s_add_i32 s80, s81, s55
	global_load_lds_dwordx4 v[226:227], off
	v_lshl_add_u64 v[226:227], v[170:171], 0, s[36:37]
	s_mov_b32 m0, s80
	v_lshl_add_u64 v[170:171], v[170:171], 0, s[38:39]
	global_load_lds_dwordx4 v[226:227], off
	s_add_i32 m0, s80, 0x2000
	s_nop 0
	global_load_lds_dwordx4 v[170:171], off
	v_lshl_add_u64 v[170:171], v[224:225], 0, s[30:31]
	s_mov_b32 m0, s63
	s_nop 0
	global_load_lds_dwordx4 v[170:171], off
	v_lshl_add_u64 v[170:171], v[224:225], 0, s[34:35]
	s_mov_b32 m0, s73
	s_nop 0
	global_load_lds_dwordx4 v[170:171], off
	s_waitcnt vmcnt(8)
	s_waitcnt lgkmcnt(0)
	s_barrier
	s_setprio 1
	s_waitcnt lgkmcnt(0)
	v_mfma_f32_16x16x32_bf16 v[62:65], v[130:133], v[192:195], v[62:65]
	v_mfma_f32_16x16x32_bf16 v[46:49], v[130:133], v[200:203], v[46:49]
	v_mfma_f32_16x16x32_bf16 v[30:33], v[130:133], v[208:211], v[30:33]
	v_mfma_f32_16x16x32_bf16 v[14:17], v[130:133], v[216:219], v[14:17]
	v_mfma_f32_16x16x32_bf16 v[14:17], v[134:137], v[220:223], v[14:17]
	v_mfma_f32_16x16x32_bf16 v[30:33], v[134:137], v[212:215], v[30:33]
	v_mfma_f32_16x16x32_bf16 v[46:49], v[134:137], v[204:207], v[46:49]
	v_mfma_f32_16x16x32_bf16 v[62:65], v[134:137], v[196:199], v[62:65]
	v_mfma_f32_16x16x32_bf16 v[58:61], v[154:157], v[192:195], v[58:61]
	v_mfma_f32_16x16x32_bf16 v[42:45], v[154:157], v[200:203], v[42:45]
	v_mfma_f32_16x16x32_bf16 v[26:29], v[154:157], v[208:211], v[26:29]
	v_mfma_f32_16x16x32_bf16 v[10:13], v[154:157], v[216:219], v[10:13]
	v_mfma_f32_16x16x32_bf16 v[10:13], v[158:161], v[220:223], v[10:13]
	v_mfma_f32_16x16x32_bf16 v[26:29], v[158:161], v[212:215], v[26:29]
	v_mfma_f32_16x16x32_bf16 v[42:45], v[158:161], v[204:207], v[42:45]
	v_mfma_f32_16x16x32_bf16 v[58:61], v[158:161], v[196:199], v[58:61]
	v_mfma_f32_16x16x32_bf16 v[54:57], v[162:165], v[192:195], v[54:57]
	v_mfma_f32_16x16x32_bf16 v[38:41], v[162:165], v[200:203], v[38:41]
	v_mfma_f32_16x16x32_bf16 v[22:25], v[162:165], v[208:211], v[22:25]
	v_mfma_f32_16x16x32_bf16 v[6:9], v[162:165], v[216:219], v[6:9]
	v_mfma_f32_16x16x32_bf16 v[6:9], v[166:169], v[220:223], v[6:9]
	v_mfma_f32_16x16x32_bf16 v[22:25], v[166:169], v[212:215], v[22:25]
	v_mfma_f32_16x16x32_bf16 v[38:41], v[166:169], v[204:207], v[38:41]
	v_mfma_f32_16x16x32_bf16 v[54:57], v[166:169], v[196:199], v[54:57]
	v_mfma_f32_16x16x32_bf16 v[50:53], v[184:187], v[192:195], v[50:53]
	v_mfma_f32_16x16x32_bf16 v[34:37], v[184:187], v[200:203], v[34:37]
	v_mfma_f32_16x16x32_bf16 v[18:21], v[184:187], v[208:211], v[18:21]
	v_mfma_f32_16x16x32_bf16 v[2:5], v[184:187], v[216:219], v[2:5]
	s_barrier
	s_setprio 2
	v_mfma_f32_16x16x32_bf16 v[2:5], v[188:191], v[220:223], v[2:5]
	v_mfma_f32_16x16x32_bf16 v[18:21], v[188:191], v[212:215], v[18:21]
	v_mfma_f32_16x16x32_bf16 v[34:37], v[188:191], v[204:207], v[34:37]
	v_mfma_f32_16x16x32_bf16 v[50:53], v[188:191], v[196:199], v[50:53]
	s_setprio 0
	s_cmp_gt_u32 s94, 29
	s_mov_b32 s94, s26
	s_cbranch_scc1 .LBB0_1669

; #define PG8_STAGE(bufoff, gbase, voff) do { if constexpr (!pg8_noload<Epi>::value) { _Pragma("unroll") for (int _i = 0; _i < 2; ++_i) \
;         __builtin_amdgcn_global_load_lds((const unsigned*)((const char*)(gbase) + (size_t)_i * pstep + (voff)[0]), (PG8_LAS unsigned*)(lds + (bufoff) + ldsw + _i * 8192), 16, 0, 0); } } while (0)
; #define PG8_LDA(dst, b, h) do { _Pragma("unroll") for (int m = 0; m < 4; ++m) _Pragma("unroll") for (int k = 0; k < 2; ++k) dst[m][k] = *(const PG8_LAS bf16x8*)(lds + PG8_SA(b, h) + aoff + m * 2048 + k * 1024); } while (0)
; #define PG8_LDB(dst, b, h) do { _Pragma("unroll") for (int n = 0; n < 2; ++n) _Pragma("unroll") for (int k = 0; k < 2; ++k) dst[n][k] = *(const PG8_LAS bf16x8*)(lds + PG8_SB(b, h) + boff + n * 2048 + k * 1024); } while (0)
; #define PG8_MMA(ai, bj, At, Bt) do { __builtin_amdgcn_s_setprio(1); _Pragma("unroll") for (int m = 0; m < 4; ++m) _Pragma("unroll") for (int n = 0; n < 2; ++n) _Pragma("unroll") for (int k = 0; k < 2; ++k) \
;         acc[ai][bj][m][n] = __builtin_amdgcn_mfma_f32_16x16x32_bf16(Bt[n][k], At[m][k], acc[ai][bj][m][n], 0, 0, 0); __builtin_amdgcn_s_setprio(0); } while (0)
; #define PG8_BAR __builtin_amdgcn_s_barrier()
; template <class Epi, class Sched, bool ALIGN_EPI = false, bool SP2 = false, bool ABLK = false>
; __device__ __forceinline__ void gemm_phase(PG8_LAS unsigned char* lds, const Gemm g, const Sched& S, const Epi& E) {
;     ...
;         for (int t = 0; t < nt; t += 2) {
;             const bool last = (t == nt - 2);
;             const char* a1 = cA + (size_t)(t + 1) * kstep;
;             const char* a2 = last ? nA : cA + (size_t)(t + 2) * kstep; const char* b2 = last ? nB : cB + (size_t)(t + 2) * kstepB;
;             const char* a3 = a2 + kstep; const char* b3 = b2 + kstepB;
;             if (last && has_next) S.a_ready(nxt);
;             if constexpr (SP2) {
;             PG8_LDB(B0, 0, 0); PG8_LDB(B1, 0, 1); PG8_SCHED; PG8_LDA(At, 0, 0); PG8_STAGE(PG8_SA(1, 1), a1 + hstep, voffA);
;             PG8_WAIT_V(8); PG8_WAIT_L(0); PG8_BAR; PG8_MMA(0, 0, At, B0); PG8_MMA(0, 1, At, B1); PG8_BAR; PG8_SCHED;
;             PG8_LDA(At, 0, 1); PG8_STAGE(PG8_SB(0, 0), b2, voffB); PG8_STAGE(PG8_SB(0, 1), b2 + hstep, voffB); PG8_STAGE(PG8_SA(0, 0), a2, voffA);
;             PG8_WAIT_V(8); PG8_WAIT_L(0); PG8_BAR; PG8_MMA(1, 0, At, B0); PG8_MMA(1, 1, At, B1); PG8_BAR; PG8_SCHED;
.LBB0_1997:
	ds_read_b128 v[130:133], v175
	ds_read_b128 v[134:137], v175 offset:1024
	ds_read_b128 v[138:141], v175 offset:2048
	ds_read_b128 v[142:145], v175 offset:3072
	ds_read_b128 v[146:149], v176
	ds_read_b128 v[150:153], v176 offset:1024
	ds_read_b128 v[154:157], v176 offset:2048
	ds_read_b128 v[158:161], v176 offset:3072
	s_add_i32 s43, s41, 2
	s_add_u32 s62, s52, 0xfff80800
	s_addc_u32 s63, s53, -1
	s_cmp_eq_u32 s3, s41
	s_cselect_b32 s63, s45, s63
	s_cselect_b32 s62, s44, s62
	s_cselect_b32 s77, s47, s39
	s_cselect_b32 s76, s46, s11
	v_lshl_add_u64 v[170:171], s[52:53], 0, v[166:167]
	s_add_i32 m0, s49, 0xc000
	ds_read_b128 v[184:187], v177
	ds_read_b128 v[188:191], v177 offset:1024
	ds_read_b128 v[192:195], v177 offset:2048
	ds_read_b128 v[196:199], v177 offset:3072
	ds_read_b128 v[200:203], v177 offset:4096
	ds_read_b128 v[204:207], v177 offset:5120
	ds_read_b128 v[208:211], v177 offset:6144
	ds_read_b128 v[212:215], v177 offset:7168
	global_load_lds_dwordx4 v[170:171], off
	v_lshl_add_u64 v[170:171], v[170:171], 0, s[12:13]
	s_add_i32 m0, s49, 0xe000
	s_nop 0
	global_load_lds_dwordx4 v[170:171], off
	s_waitcnt vmcnt(8)
	s_waitcnt lgkmcnt(0)
	s_barrier
	s_setprio 1
	s_waitcnt lgkmcnt(0)
	v_mfma_f32_16x16x32_bf16 v[126:129], v[130:133], v[184:187], v[126:129]
	v_mfma_f32_16x16x32_bf16 v[110:113], v[130:133], v[192:195], v[110:113]
	v_mfma_f32_16x16x32_bf16 v[94:97], v[130:133], v[200:203], v[94:97]
	v_mfma_f32_16x16x32_bf16 v[78:81], v[130:133], v[208:211], v[78:81]
	v_mfma_f32_16x16x32_bf16 v[78:81], v[134:137], v[212:215], v[78:81]
	v_mfma_f32_16x16x32_bf16 v[94:97], v[134:137], v[204:207], v[94:97]
	v_mfma_f32_16x16x32_bf16 v[110:113], v[134:137], v[196:199], v[110:113]
	v_mfma_f32_16x16x32_bf16 v[126:129], v[134:137], v[188:191], v[126:129]
	v_mfma_f32_16x16x32_bf16 v[122:125], v[138:141], v[184:187], v[122:125]
	v_mfma_f32_16x16x32_bf16 v[106:109], v[138:141], v[192:195], v[106:109]
	v_mfma_f32_16x16x32_bf16 v[90:93], v[138:141], v[200:203], v[90:93]
	v_mfma_f32_16x16x32_bf16 v[74:77], v[138:141], v[208:211], v[74:77]
	v_mfma_f32_16x16x32_bf16 v[74:77], v[142:145], v[212:215], v[74:77]
	v_mfma_f32_16x16x32_bf16 v[90:93], v[142:145], v[204:207], v[90:93]
	v_mfma_f32_16x16x32_bf16 v[106:109], v[142:145], v[196:199], v[106:109]
	v_mfma_f32_16x16x32_bf16 v[122:125], v[142:145], v[188:191], v[122:125]
	v_mfma_f32_16x16x32_bf16 v[118:121], v[146:149], v[184:187], v[118:121]
	v_mfma_f32_16x16x32_bf16 v[102:105], v[146:149], v[192:195], v[102:105]
	v_mfma_f32_16x16x32_bf16 v[86:89], v[146:149], v[200:203], v[86:89]
	v_mfma_f32_16x16x32_bf16 v[70:73], v[146:149], v[208:211], v[70:73]
	v_mfma_f32_16x16x32_bf16 v[70:73], v[150:153], v[212:215], v[70:73]
	v_mfma_f32_16x16x32_bf16 v[86:89], v[150:153], v[204:207], v[86:89]
	v_mfma_f32_16x16x32_bf16 v[102:105], v[150:153], v[196:199], v[102:105]
	v_mfma_f32_16x16x32_bf16 v[118:121], v[150:153], v[188:191], v[118:121]
	v_mfma_f32_16x16x32_bf16 v[114:117], v[154:157], v[184:187], v[114:117]
	v_mfma_f32_16x16x32_bf16 v[98:101], v[154:157], v[192:195], v[98:101]
	v_mfma_f32_16x16x32_bf16 v[82:85], v[154:157], v[200:203], v[82:85]
	v_mfma_f32_16x16x32_bf16 v[66:69], v[154:157], v[208:211], v[66:69]
	s_barrier
	s_setprio 2
	v_mfma_f32_16x16x32_bf16 v[66:69], v[158:161], v[212:215], v[66:69]
	v_mfma_f32_16x16x32_bf16 v[82:85], v[158:161], v[204:207], v[82:85]
	v_mfma_f32_16x16x32_bf16 v[98:101], v[158:161], v[196:199], v[98:101]
	v_mfma_f32_16x16x32_bf16 v[114:117], v[158:161], v[188:191], v[114:117]
	s_setprio 0
	s_add_i32 s41, s70, s57
	v_lshl_add_u64 v[170:171], s[76:77], 0, v[162:163]
	s_mov_b32 m0, s41
	ds_read_b128 v[184:187], v177 offset:16384
	ds_read_b128 v[188:191], v177 offset:17408
	ds_read_b128 v[192:195], v177 offset:18432
	ds_read_b128 v[196:199], v177 offset:19456
	ds_read_b128 v[200:203], v177 offset:20480
	ds_read_b128 v[204:207], v177 offset:21504
	ds_read_b128 v[208:211], v177 offset:22528
	ds_read_b128 v[212:215], v177 offset:23552
	global_load_lds_dwordx4 v[170:171], off
	v_lshl_add_u64 v[216:217], v[170:171], 0, s[12:13]
	s_add_i32 m0, s41, 0x2000
	s_add_i32 s41, s71, s57
	global_load_lds_dwordx4 v[216:217], off
	v_lshl_add_u64 v[216:217], v[170:171], 0, s[14:15]
	s_mov_b32 m0, s41
	s_nop 0
	global_load_lds_dwordx4 v[216:217], off
	v_lshl_add_u64 v[216:217], v[170:171], 0, s[16:17]
	s_add_i32 m0, s41, 0x2000
	s_nop 0
	global_load_lds_dwordx4 v[216:217], off
	v_lshl_add_u64 v[216:217], s[62:63], 0, v[162:163]
	s_mov_b32 m0, s49
	v_lshl_add_u64 v[218:219], v[216:217], 0, s[12:13]
	global_load_lds_dwordx4 v[216:217], off
	s_mov_b32 m0, s58
	s_nop 0
	global_load_lds_dwordx4 v[218:219], off
	s_waitcnt vmcnt(8)
	s_waitcnt lgkmcnt(0)
	s_barrier
; #define PG8_STAGE(bufoff, gbase, voff) do { if constexpr (!pg8_noload<Epi>::value) { _Pragma("unroll") for (int _i = 0; _i < 2; ++_i) \
;         __builtin_amdgcn_global_load_lds((const unsigned*)((const char*)(gbase) + (size_t)_i * pstep + (voff)[0]), (PG8_LAS unsigned*)(lds + (bufoff) + ldsw + _i * 8192), 16, 0, 0); } } while (0)
; #define PG8_LDA(dst, b, h) do { _Pragma("unroll") for (int m = 0; m < 4; ++m) _Pragma("unroll") for (int k = 0; k < 2; ++k) dst[m][k] = *(const PG8_LAS bf16x8*)(lds + PG8_SA(b, h) + aoff + m * 2048 + k * 1024); } while (0)
; #define PG8_LDB(dst, b, h) do { _Pragma("unroll") for (int n = 0; n < 2; ++n) _Pragma("unroll") for (int k = 0; k < 2; ++k) dst[n][k] = *(const PG8_LAS bf16x8*)(lds + PG8_SB(b, h) + boff + n * 2048 + k * 1024); } while (0)
; #define PG8_MMA(ai, bj, At, Bt) do { __builtin_amdgcn_s_setprio(1); _Pragma("unroll") for (int m = 0; m < 4; ++m) _Pragma("unroll") for (int n = 0; n < 2; ++n) _Pragma("unroll") for (int k = 0; k < 2; ++k) \
;         acc[ai][bj][m][n] = __builtin_amdgcn_mfma_f32_16x16x32_bf16(Bt[n][k], At[m][k], acc[ai][bj][m][n], 0, 0, 0); __builtin_amdgcn_s_setprio(0); } while (0)
; #define PG8_WAIT_V(n) asm volatile("s_waitcnt vmcnt(" #n ")" ::: "memory")
; #define PG8_WAIT_L(n) asm volatile("s_waitcnt lgkmcnt(" #n ")" ::: "memory")
; #define PG8_BAR __builtin_amdgcn_s_barrier()
; #define PG8_SCHED __builtin_amdgcn_sched_barrier(0)
; template <class Epi, class Sched, bool ALIGN_EPI = false, bool SP2 = false, bool ABLK = false>
; __device__ __forceinline__ void gemm_phase(PG8_LAS unsigned char* lds, const Gemm g, const Sched& S, const Epi& E) {
;     ...
;             PG8_WAIT_V(8); PG8_WAIT_L(0); PG8_BAR; PG8_MMA(0, 0, At, B0); PG8_MMA(0, 1, At, B1); PG8_BAR; PG8_SCHED;
;             PG8_LDA(At, 0, 1); PG8_STAGE(PG8_SB(0, 0), b2, voffB); PG8_STAGE(PG8_SB(0, 1), b2 + hstep, voffB); PG8_STAGE(PG8_SA(0, 0), a2, voffA);
;             PG8_WAIT_V(8); PG8_WAIT_L(0); PG8_BAR; PG8_MMA(1, 0, At, B0); PG8_MMA(1, 1, At, B1); PG8_BAR; PG8_SCHED;
;             PG8_LDB(B0, 1, 0); PG8_LDB(B1, 1, 1); PG8_SCHED; PG8_LDA(At, 1, 0); PG8_STAGE(PG8_SA(0, 1), a2 + hstep, voffA);
;             PG8_WAIT_V(8); PG8_WAIT_L(0); PG8_BAR; PG8_MMA(0, 0, At, B0); PG8_MMA(0, 1, At, B1); PG8_BAR; PG8_SCHED;
	s_setprio 1
	s_waitcnt lgkmcnt(0)
	v_mfma_f32_16x16x32_bf16 v[62:65], v[130:133], v[184:187], v[62:65]
	v_mfma_f32_16x16x32_bf16 v[46:49], v[130:133], v[192:195], v[46:49]
	v_mfma_f32_16x16x32_bf16 v[30:33], v[130:133], v[200:203], v[30:33]
	v_mfma_f32_16x16x32_bf16 v[14:17], v[130:133], v[208:211], v[14:17]
	v_mfma_f32_16x16x32_bf16 v[14:17], v[134:137], v[212:215], v[14:17]
	v_mfma_f32_16x16x32_bf16 v[30:33], v[134:137], v[204:207], v[30:33]
	v_mfma_f32_16x16x32_bf16 v[46:49], v[134:137], v[196:199], v[46:49]
	v_mfma_f32_16x16x32_bf16 v[62:65], v[134:137], v[188:191], v[62:65]
	v_mfma_f32_16x16x32_bf16 v[58:61], v[138:141], v[184:187], v[58:61]
	v_mfma_f32_16x16x32_bf16 v[42:45], v[138:141], v[192:195], v[42:45]
	v_mfma_f32_16x16x32_bf16 v[26:29], v[138:141], v[200:203], v[26:29]
	v_mfma_f32_16x16x32_bf16 v[10:13], v[138:141], v[208:211], v[10:13]
	v_mfma_f32_16x16x32_bf16 v[10:13], v[142:145], v[212:215], v[10:13]
	v_mfma_f32_16x16x32_bf16 v[26:29], v[142:145], v[204:207], v[26:29]
	v_mfma_f32_16x16x32_bf16 v[42:45], v[142:145], v[196:199], v[42:45]
	v_mfma_f32_16x16x32_bf16 v[58:61], v[142:145], v[188:191], v[58:61]
	v_mfma_f32_16x16x32_bf16 v[54:57], v[146:149], v[184:187], v[54:57]
	v_mfma_f32_16x16x32_bf16 v[38:41], v[146:149], v[192:195], v[38:41]
	v_mfma_f32_16x16x32_bf16 v[22:25], v[146:149], v[200:203], v[22:25]
	v_mfma_f32_16x16x32_bf16 v[6:9], v[146:149], v[208:211], v[6:9]
	v_mfma_f32_16x16x32_bf16 v[6:9], v[150:153], v[212:215], v[6:9]
	v_mfma_f32_16x16x32_bf16 v[22:25], v[150:153], v[204:207], v[22:25]
	v_mfma_f32_16x16x32_bf16 v[38:41], v[150:153], v[196:199], v[38:41]
	v_mfma_f32_16x16x32_bf16 v[54:57], v[150:153], v[188:191], v[54:57]
	v_mfma_f32_16x16x32_bf16 v[50:53], v[154:157], v[184:187], v[50:53]
	v_mfma_f32_16x16x32_bf16 v[34:37], v[154:157], v[192:195], v[34:37]
	v_mfma_f32_16x16x32_bf16 v[18:21], v[154:157], v[200:203], v[18:21]
	v_mfma_f32_16x16x32_bf16 v[2:5], v[154:157], v[208:211], v[2:5]
	s_barrier
	s_setprio 2
	v_mfma_f32_16x16x32_bf16 v[2:5], v[158:161], v[212:215], v[2:5]
	v_mfma_f32_16x16x32_bf16 v[18:21], v[158:161], v[204:207], v[18:21]
	v_mfma_f32_16x16x32_bf16 v[34:37], v[158:161], v[196:199], v[34:37]
	v_mfma_f32_16x16x32_bf16 v[50:53], v[158:161], v[188:191], v[50:53]
	s_setprio 0
	s_add_i32 s41, 0, 0x18000
	s_add_i32 s62, 0, 0x1c000
	v_add_u32_e32 v142, s41, v1
	v_add_u32_e32 v158, s62, v1
	ds_read_b128 v[130:133], v142
	ds_read_b128 v[134:137], v142 offset:1024
	ds_read_b128 v[138:141], v142 offset:2048
	ds_read_b128 v[142:145], v142 offset:3072
	ds_read_b128 v[146:149], v158
	ds_read_b128 v[150:153], v158 offset:1024
	ds_read_b128 v[154:157], v158 offset:2048
	ds_read_b128 v[158:161], v158 offset:3072
	s_mov_b32 m0, s59
	v_lshl_add_u64 v[218:219], v[216:217], 0, s[14:15]
	ds_read_b128 v[184:187], v177 offset:32768
	ds_read_b128 v[188:191], v177 offset:33792
	ds_read_b128 v[192:195], v177 offset:34816
	ds_read_b128 v[196:199], v177 offset:35840
	ds_read_b128 v[200:203], v177 offset:36864
	ds_read_b128 v[204:207], v177 offset:37888
	ds_read_b128 v[208:211], v177 offset:38912
	ds_read_b128 v[212:215], v177 offset:39936
	global_load_lds_dwordx4 v[218:219], off
	v_lshl_add_u64 v[218:219], v[216:217], 0, s[16:17]
	s_mov_b32 m0, s60
	s_nop 0
	global_load_lds_dwordx4 v[218:219], off
	s_waitcnt vmcnt(8)
	s_waitcnt lgkmcnt(0)
	s_barrier
	s_setprio 1
	s_waitcnt lgkmcnt(0)
	v_mfma_f32_16x16x32_bf16 v[126:129], v[130:133], v[184:187], v[126:129]
	v_mfma_f32_16x16x32_bf16 v[110:113], v[130:133], v[192:195], v[110:113]
	v_mfma_f32_16x16x32_bf16 v[94:97], v[130:133], v[200:203], v[94:97]
	v_mfma_f32_16x16x32_bf16 v[78:81], v[130:133], v[208:211], v[78:81]
	v_mfma_f32_16x16x32_bf16 v[78:81], v[134:137], v[212:215], v[78:81]
	v_mfma_f32_16x16x32_bf16 v[94:97], v[134:137], v[204:207], v[94:97]
	v_mfma_f32_16x16x32_bf16 v[110:113], v[134:137], v[196:199], v[110:113]
	v_mfma_f32_16x16x32_bf16 v[126:129], v[134:137], v[188:191], v[126:129]
	v_mfma_f32_16x16x32_bf16 v[122:125], v[138:141], v[184:187], v[122:125]
	v_mfma_f32_16x16x32_bf16 v[106:109], v[138:141], v[192:195], v[106:109]
	v_mfma_f32_16x16x32_bf16 v[90:93], v[138:141], v[200:203], v[90:93]
	v_mfma_f32_16x16x32_bf16 v[74:77], v[138:141], v[208:211], v[74:77]
	v_mfma_f32_16x16x32_bf16 v[74:77], v[142:145], v[212:215], v[74:77]
	v_mfma_f32_16x16x32_bf16 v[90:93], v[142:145], v[204:207], v[90:93]
	v_mfma_f32_16x16x32_bf16 v[106:109], v[142:145], v[196:199], v[106:109]
	v_mfma_f32_16x16x32_bf16 v[122:125], v[142:145], v[188:191], v[122:125]
	v_mfma_f32_16x16x32_bf16 v[118:121], v[146:149], v[184:187], v[118:121]
	v_mfma_f32_16x16x32_bf16 v[102:105], v[146:149], v[192:195], v[102:105]
	v_mfma_f32_16x16x32_bf16 v[86:89], v[146:149], v[200:203], v[86:89]
	v_mfma_f32_16x16x32_bf16 v[70:73], v[146:149], v[208:211], v[70:73]
	v_mfma_f32_16x16x32_bf16 v[70:73], v[150:153], v[212:215], v[70:73]
	v_mfma_f32_16x16x32_bf16 v[86:89], v[150:153], v[204:207], v[86:89]
	v_mfma_f32_16x16x32_bf16 v[102:105], v[150:153], v[196:199], v[102:105]
	v_mfma_f32_16x16x32_bf16 v[118:121], v[150:153], v[188:191], v[118:121]
	v_mfma_f32_16x16x32_bf16 v[114:117], v[154:157], v[184:187], v[114:117]
	v_mfma_f32_16x16x32_bf16 v[98:101], v[154:157], v[192:195], v[98:101]
	v_mfma_f32_16x16x32_bf16 v[82:85], v[154:157], v[200:203], v[82:85]
	v_mfma_f32_16x16x32_bf16 v[66:69], v[154:157], v[208:211], v[66:69]
	s_barrier
; #define PG8_STAGE(bufoff, gbase, voff) do { if constexpr (!pg8_noload<Epi>::value) { _Pragma("unroll") for (int _i = 0; _i < 2; ++_i) \
;         __builtin_amdgcn_global_load_lds((const unsigned*)((const char*)(gbase) + (size_t)_i * pstep + (voff)[0]), (PG8_LAS unsigned*)(lds + (bufoff) + ldsw + _i * 8192), 16, 0, 0); } } while (0)
; #define PG8_LDA(dst, b, h) do { _Pragma("unroll") for (int m = 0; m < 4; ++m) _Pragma("unroll") for (int k = 0; k < 2; ++k) dst[m][k] = *(const PG8_LAS bf16x8*)(lds + PG8_SA(b, h) + aoff + m * 2048 + k * 1024); } while (0)
; #define PG8_LDB(dst, b, h) do { _Pragma("unroll") for (int n = 0; n < 2; ++n) _Pragma("unroll") for (int k = 0; k < 2; ++k) dst[n][k] = *(const PG8_LAS bf16x8*)(lds + PG8_SB(b, h) + boff + n * 2048 + k * 1024); } while (0)
; #define PG8_WAIT_V(n) asm volatile("s_waitcnt vmcnt(" #n ")" ::: "memory")
; #define PG8_WAIT_L(n) asm volatile("s_waitcnt lgkmcnt(" #n ")" ::: "memory")
; #define PG8_BAR __builtin_amdgcn_s_barrier()
; #define PG8_SCHED __builtin_amdgcn_sched_barrier(0)
; template <class Epi, class Sched, bool ALIGN_EPI = false, bool SP2 = false, bool ABLK = false>
; __device__ __forceinline__ void gemm_phase(PG8_LAS unsigned char* lds, const Gemm g, const Sched& S, const Epi& E) {
;     ...
;         for (int t = 0; t < nt; t += 2) {
;             const bool last = (t == nt - 2);
;             const char* a1 = cA + (size_t)(t + 1) * kstep;
;             const char* a2 = last ? nA : cA + (size_t)(t + 2) * kstep; const char* b2 = last ? nB : cB + (size_t)(t + 2) * kstepB;
;             const char* a3 = a2 + kstep; const char* b3 = b2 + kstepB;
;             if (last && has_next) S.a_ready(nxt);
;     ...
;             PG8_WAIT_V(8); PG8_WAIT_L(0); PG8_BAR; PG8_MMA(1, 0, At, B0); PG8_MMA(1, 1, At, B1); PG8_BAR; PG8_SCHED;
;             PG8_LDB(B0, 1, 0); PG8_LDB(B1, 1, 1); PG8_SCHED; PG8_LDA(At, 1, 0); PG8_STAGE(PG8_SA(0, 1), a2 + hstep, voffA);
;             PG8_WAIT_V(8); PG8_WAIT_L(0); PG8_BAR; PG8_MMA(0, 0, At, B0); PG8_MMA(0, 1, At, B1); PG8_BAR; PG8_SCHED;
;             PG8_LDA(At, 1, 1); PG8_STAGE(PG8_SB(1, 0), b3, voffB); PG8_STAGE(PG8_SB(1, 1), b3 + hstep, voffB); PG8_STAGE(PG8_SA(1, 0), a3, voffA);
;             PG8_WAIT_V(8); PG8_WAIT_L(0); PG8_BAR; PG8_MMA(1, 0, At, B0); PG8_MMA(1, 1, At, B1); PG8_BAR; PG8_SCHED;
	s_setprio 2
	v_mfma_f32_16x16x32_bf16 v[66:69], v[158:161], v[212:215], v[66:69]
	v_mfma_f32_16x16x32_bf16 v[82:85], v[158:161], v[204:207], v[82:85]
	v_mfma_f32_16x16x32_bf16 v[98:101], v[158:161], v[196:199], v[98:101]
	v_mfma_f32_16x16x32_bf16 v[114:117], v[158:161], v[188:191], v[114:117]
	s_setprio 0
	s_add_i32 s41, s41, s57
	v_lshl_add_u64 v[218:219], v[170:171], 0, s[24:25]
	s_mov_b32 m0, s41
	ds_read_b128 v[184:187], v177 offset:49152
	ds_read_b128 v[188:191], v177 offset:50176
	ds_read_b128 v[192:195], v177 offset:51200
	ds_read_b128 v[196:199], v177 offset:52224
	ds_read_b128 v[200:203], v177 offset:53248
	ds_read_b128 v[204:207], v177 offset:54272
	ds_read_b128 v[208:211], v177 offset:55296
	ds_read_b128 v[212:215], v177 offset:56320
	global_load_lds_dwordx4 v[218:219], off
	v_lshl_add_u64 v[218:219], v[170:171], 0, s[26:27]
	s_add_i32 m0, s41, 0x2000
	s_add_i32 s41, s62, s57
	global_load_lds_dwordx4 v[218:219], off
	v_lshl_add_u64 v[218:219], v[170:171], 0, s[28:29]
	s_mov_b32 m0, s41
	v_lshl_add_u64 v[170:171], v[170:171], 0, s[30:31]
	global_load_lds_dwordx4 v[218:219], off
	s_add_i32 m0, s41, 0x2000
	s_nop 0
	global_load_lds_dwordx4 v[170:171], off
	v_lshl_add_u64 v[170:171], v[216:217], 0, s[24:25]
	s_mov_b32 m0, s65
	s_nop 0
	global_load_lds_dwordx4 v[170:171], off
	v_lshl_add_u64 v[170:171], v[216:217], 0, s[26:27]
	s_mov_b32 m0, s66
	s_nop 0
	global_load_lds_dwordx4 v[170:171], off
	s_waitcnt vmcnt(8)
	s_waitcnt lgkmcnt(0)
	s_barrier
	s_setprio 1
	s_waitcnt lgkmcnt(0)
	v_mfma_f32_16x16x32_bf16 v[62:65], v[130:133], v[184:187], v[62:65]
	v_mfma_f32_16x16x32_bf16 v[46:49], v[130:133], v[192:195], v[46:49]
	v_mfma_f32_16x16x32_bf16 v[30:33], v[130:133], v[200:203], v[30:33]
	v_mfma_f32_16x16x32_bf16 v[14:17], v[130:133], v[208:211], v[14:17]
	v_mfma_f32_16x16x32_bf16 v[14:17], v[134:137], v[212:215], v[14:17]
	v_mfma_f32_16x16x32_bf16 v[30:33], v[134:137], v[204:207], v[30:33]
	v_mfma_f32_16x16x32_bf16 v[46:49], v[134:137], v[196:199], v[46:49]
	v_mfma_f32_16x16x32_bf16 v[62:65], v[134:137], v[188:191], v[62:65]
	v_mfma_f32_16x16x32_bf16 v[58:61], v[138:141], v[184:187], v[58:61]
	v_mfma_f32_16x16x32_bf16 v[42:45], v[138:141], v[192:195], v[42:45]
	v_mfma_f32_16x16x32_bf16 v[26:29], v[138:141], v[200:203], v[26:29]
	v_mfma_f32_16x16x32_bf16 v[10:13], v[138:141], v[208:211], v[10:13]
	v_mfma_f32_16x16x32_bf16 v[10:13], v[142:145], v[212:215], v[10:13]
	v_mfma_f32_16x16x32_bf16 v[26:29], v[142:145], v[204:207], v[26:29]
	v_mfma_f32_16x16x32_bf16 v[42:45], v[142:145], v[196:199], v[42:45]
	v_mfma_f32_16x16x32_bf16 v[58:61], v[142:145], v[188:191], v[58:61]
	v_mfma_f32_16x16x32_bf16 v[54:57], v[146:149], v[184:187], v[54:57]
	v_mfma_f32_16x16x32_bf16 v[38:41], v[146:149], v[192:195], v[38:41]
	v_mfma_f32_16x16x32_bf16 v[22:25], v[146:149], v[200:203], v[22:25]
	v_mfma_f32_16x16x32_bf16 v[6:9], v[146:149], v[208:211], v[6:9]
	v_mfma_f32_16x16x32_bf16 v[6:9], v[150:153], v[212:215], v[6:9]
	v_mfma_f32_16x16x32_bf16 v[22:25], v[150:153], v[204:207], v[22:25]
	v_mfma_f32_16x16x32_bf16 v[38:41], v[150:153], v[196:199], v[38:41]
	v_mfma_f32_16x16x32_bf16 v[54:57], v[150:153], v[188:191], v[54:57]
	v_mfma_f32_16x16x32_bf16 v[50:53], v[154:157], v[184:187], v[50:53]
	v_mfma_f32_16x16x32_bf16 v[34:37], v[154:157], v[192:195], v[34:37]
	v_mfma_f32_16x16x32_bf16 v[18:21], v[154:157], v[200:203], v[18:21]
	v_mfma_f32_16x16x32_bf16 v[2:5], v[154:157], v[208:211], v[2:5]
	s_barrier
	s_setprio 2
	v_mfma_f32_16x16x32_bf16 v[2:5], v[158:161], v[212:215], v[2:5]
	v_mfma_f32_16x16x32_bf16 v[18:21], v[158:161], v[204:207], v[18:21]
	v_mfma_f32_16x16x32_bf16 v[34:37], v[158:161], v[196:199], v[34:37]
	v_mfma_f32_16x16x32_bf16 v[50:53], v[158:161], v[188:191], v[50:53]
	s_setprio 0
	s_add_u32 s52, s52, 0x1000
	s_addc_u32 s53, s53, 0
	s_add_u32 s11, s11, 0x1000
	s_addc_u32 s39, s39, 0
	s_cmp_ge_i32 s43, s75
	s_mov_b32 s41, s43
	s_cbranch_scc0 .LBB0_1997
	s_and_b64 vcc, exec, s[34:35]
	s_cbranch_vccnz .LBB0_2002
	s_lshl_b32 s11, s2, 8
	s_cmp_gt_i32 s2, 63
	s_mov_b64 s[52:53], -1
	s_cbranch_scc1 .LBB0_2003

; #define PG8_STAGE(bufoff, gbase, voff) do { if constexpr (!pg8_noload<Epi>::value) { _Pragma("unroll") for (int _i = 0; _i < 2; ++_i) \
;         __builtin_amdgcn_global_load_lds((const unsigned*)((const char*)(gbase) + (size_t)_i * pstep + (voff)[0]), (PG8_LAS unsigned*)(lds + (bufoff) + ldsw + _i * 8192), 16, 0, 0); } } while (0)
; #define PG8_LDA(dst, b, h) do { _Pragma("unroll") for (int m = 0; m < 4; ++m) _Pragma("unroll") for (int k = 0; k < 2; ++k) dst[m][k] = *(const PG8_LAS bf16x8*)(lds + PG8_SA(b, h) + aoff + m * 2048 + k * 1024); } while (0)
; #define PG8_LDB(dst, b, h) do { _Pragma("unroll") for (int n = 0; n < 2; ++n) _Pragma("unroll") for (int k = 0; k < 2; ++k) dst[n][k] = *(const PG8_LAS bf16x8*)(lds + PG8_SB(b, h) + boff + n * 2048 + k * 1024); } while (0)
; #define PG8_MMA(ai, bj, At, Bt) do { __builtin_amdgcn_s_setprio(1); _Pragma("unroll") for (int m = 0; m < 4; ++m) _Pragma("unroll") for (int n = 0; n < 2; ++n) _Pragma("unroll") for (int k = 0; k < 2; ++k) \
;         acc[ai][bj][m][n] = __builtin_amdgcn_mfma_f32_16x16x32_bf16(Bt[n][k], At[m][k], acc[ai][bj][m][n], 0, 0, 0); __builtin_amdgcn_s_setprio(0); } while (0)
; #define PG8_BAR __builtin_amdgcn_s_barrier()
; template <class Epi, class Sched, bool ALIGN_EPI = false, bool SP2 = false, bool ABLK = false>
; __device__ __forceinline__ void gemm_phase(PG8_LAS unsigned char* lds, const Gemm g, const Sched& S, const Epi& E) {
;     ...
;         for (int t = 0; t < nt; t += 2) {
;             const bool last = (t == nt - 2);
;             const char* a1 = cA + (size_t)(t + 1) * kstep;
;             const char* a2 = last ? nA : cA + (size_t)(t + 2) * kstep; const char* b2 = last ? nB : cB + (size_t)(t + 2) * kstepB;
;             const char* a3 = a2 + kstep; const char* b3 = b2 + kstepB;
;             if (last && has_next) S.a_ready(nxt);
;             if constexpr (SP2) {
;             PG8_LDB(B0, 0, 0); PG8_LDB(B1, 0, 1); PG8_SCHED; PG8_LDA(At, 0, 0); PG8_STAGE(PG8_SA(1, 1), a1 + hstep, voffA);
;             PG8_WAIT_V(8); PG8_WAIT_L(0); PG8_BAR; PG8_MMA(0, 0, At, B0); PG8_MMA(0, 1, At, B1); PG8_BAR; PG8_SCHED;
;             PG8_LDA(At, 0, 1); PG8_STAGE(PG8_SB(0, 0), b2, voffB); PG8_STAGE(PG8_SB(0, 1), b2 + hstep, voffB); PG8_STAGE(PG8_SA(0, 0), a2, voffA);
;             PG8_WAIT_V(8); PG8_WAIT_L(0); PG8_BAR; PG8_MMA(1, 0, At, B0); PG8_MMA(1, 1, At, B1); PG8_BAR; PG8_SCHED;
.LBB0_2119:
	s_or_b32 s30, s59, 1
	s_lshl_b64 s[14:15], s[30:31], 11
	s_add_u32 s14, s82, s14
	v_add_u32_e32 v133, s71, v148
	s_addc_u32 s15, s83, s15
	s_add_i32 s30, s59, 2
	ds_read_b128 v[144:147], v133
	ds_read_b128 v[184:187], v133 offset:1024
	ds_read_b128 v[188:191], v133 offset:2048
	ds_read_b128 v[192:195], v133 offset:3072
	v_add_u32_e32 v133, s73, v148
	s_lshl_b64 s[34:35], s[30:31], 11
	ds_read_b128 v[196:199], v133
	ds_read_b128 v[200:203], v133 offset:1024
	ds_read_b128 v[204:207], v133 offset:2048
	ds_read_b128 v[208:211], v133 offset:3072
	s_add_u32 s96, s82, s34
	s_addc_u32 s97, s83, s35
	s_and_b64 s[94:95], s[92:93], exec
	s_cselect_b32 s95, s97, s77
	s_cselect_b32 s94, s96, s28
	s_add_u32 s96, s88, s34
	s_addc_u32 s97, s89, s35
	s_and_b64 s[34:35], s[92:93], exec
	s_cselect_b32 s35, s97, s29
	s_cselect_b32 s34, s96, s75
	v_lshl_add_u64 v[180:181], s[14:15], 0, v[130:131]
	v_lshl_add_u64 v[244:245], v[180:181], 0, s[24:25]
	s_add_i32 m0, s17, 0xc000
	ds_read_b128 v[212:215], v168
	ds_read_b128 v[216:219], v168 offset:1024
	ds_read_b128 v[220:223], v168 offset:2048
	ds_read_b128 v[224:227], v168 offset:3072
	ds_read_b128 v[228:231], v168 offset:4096
	ds_read_b128 v[232:235], v168 offset:5120
	ds_read_b128 v[236:239], v168 offset:6144
	ds_read_b128 v[240:243], v168 offset:7168
	global_load_lds_dwordx4 v[244:245], off
	v_lshl_add_u64 v[180:181], v[180:181], 0, s[26:27]
	s_add_i32 m0, s17, 0xe000
	s_nop 0
	global_load_lds_dwordx4 v[180:181], off
	s_waitcnt vmcnt(8)
	s_waitcnt lgkmcnt(0)
	s_barrier
	s_setprio 1
	s_waitcnt lgkmcnt(0)
	v_mfma_f32_16x16x32_bf16 v[126:129], v[144:147], v[212:215], v[126:129]
	v_mfma_f32_16x16x32_bf16 v[110:113], v[144:147], v[220:223], v[110:113]
	v_mfma_f32_16x16x32_bf16 v[94:97], v[144:147], v[228:231], v[94:97]
	v_mfma_f32_16x16x32_bf16 v[78:81], v[144:147], v[236:239], v[78:81]
	v_mfma_f32_16x16x32_bf16 v[78:81], v[184:187], v[240:243], v[78:81]
	v_mfma_f32_16x16x32_bf16 v[94:97], v[184:187], v[232:235], v[94:97]
	v_mfma_f32_16x16x32_bf16 v[110:113], v[184:187], v[224:227], v[110:113]
	v_mfma_f32_16x16x32_bf16 v[126:129], v[184:187], v[216:219], v[126:129]
	v_mfma_f32_16x16x32_bf16 v[122:125], v[188:191], v[212:215], v[122:125]
	v_mfma_f32_16x16x32_bf16 v[106:109], v[188:191], v[220:223], v[106:109]
	v_mfma_f32_16x16x32_bf16 v[90:93], v[188:191], v[228:231], v[90:93]
	v_mfma_f32_16x16x32_bf16 v[74:77], v[188:191], v[236:239], v[74:77]
	v_mfma_f32_16x16x32_bf16 v[74:77], v[192:195], v[240:243], v[74:77]
	v_mfma_f32_16x16x32_bf16 v[90:93], v[192:195], v[232:235], v[90:93]
	v_mfma_f32_16x16x32_bf16 v[106:109], v[192:195], v[224:227], v[106:109]
	v_mfma_f32_16x16x32_bf16 v[122:125], v[192:195], v[216:219], v[122:125]
	v_mfma_f32_16x16x32_bf16 v[118:121], v[196:199], v[212:215], v[118:121]
	v_mfma_f32_16x16x32_bf16 v[102:105], v[196:199], v[220:223], v[102:105]
	v_mfma_f32_16x16x32_bf16 v[86:89], v[196:199], v[228:231], v[86:89]
	v_mfma_f32_16x16x32_bf16 v[70:73], v[196:199], v[236:239], v[70:73]
	v_mfma_f32_16x16x32_bf16 v[70:73], v[200:203], v[240:243], v[70:73]
	v_mfma_f32_16x16x32_bf16 v[86:89], v[200:203], v[232:235], v[86:89]
	v_mfma_f32_16x16x32_bf16 v[102:105], v[200:203], v[224:227], v[102:105]
	v_mfma_f32_16x16x32_bf16 v[118:121], v[200:203], v[216:219], v[118:121]
	v_mfma_f32_16x16x32_bf16 v[114:117], v[204:207], v[212:215], v[114:117]
	v_mfma_f32_16x16x32_bf16 v[98:101], v[204:207], v[220:223], v[98:101]
	v_mfma_f32_16x16x32_bf16 v[82:85], v[204:207], v[228:231], v[82:85]
	v_mfma_f32_16x16x32_bf16 v[66:69], v[204:207], v[236:239], v[66:69]
	s_barrier
	s_setprio 2
	v_mfma_f32_16x16x32_bf16 v[66:69], v[208:211], v[240:243], v[66:69]
	v_mfma_f32_16x16x32_bf16 v[82:85], v[208:211], v[232:235], v[82:85]
	v_mfma_f32_16x16x32_bf16 v[98:101], v[208:211], v[224:227], v[98:101]
	v_mfma_f32_16x16x32_bf16 v[114:117], v[208:211], v[216:219], v[114:117]
	s_setprio 0
	s_add_i32 s14, s71, s3
	v_lshl_add_u64 v[180:181], s[34:35], 0, v[130:131]
	s_mov_b32 m0, s14
	ds_read_b128 v[212:215], v168 offset:16384
	ds_read_b128 v[216:219], v168 offset:17408
	ds_read_b128 v[220:223], v168 offset:18432
	ds_read_b128 v[224:227], v168 offset:19456
	ds_read_b128 v[228:231], v168 offset:20480
	ds_read_b128 v[232:235], v168 offset:21504
	ds_read_b128 v[236:239], v168 offset:22528
	ds_read_b128 v[240:243], v168 offset:23552
	global_load_lds_dwordx4 v[180:181], off
	v_lshl_add_u64 v[244:245], v[180:181], 0, s[22:23]
	s_add_i32 m0, s14, 0x2000
	s_add_i32 s14, s73, s3
	global_load_lds_dwordx4 v[244:245], off
	v_lshl_add_u64 v[244:245], v[180:181], 0, s[24:25]
	s_mov_b32 m0, s14
	s_nop 0
	global_load_lds_dwordx4 v[244:245], off
	v_lshl_add_u64 v[244:245], v[180:181], 0, s[26:27]
	s_add_i32 m0, s14, 0x2000
	s_nop 0
	global_load_lds_dwordx4 v[244:245], off
	v_lshl_add_u64 v[244:245], s[94:95], 0, v[130:131]
	s_mov_b32 m0, s17
	v_lshl_add_u64 v[246:247], v[244:245], 0, s[22:23]
	global_load_lds_dwordx4 v[244:245], off
	s_mov_b32 m0, s56
	s_nop 0
	global_load_lds_dwordx4 v[246:247], off
	s_waitcnt vmcnt(8)
	s_waitcnt lgkmcnt(0)
	s_barrier
; #define PG8_STAGE(bufoff, gbase, voff) do { if constexpr (!pg8_noload<Epi>::value) { _Pragma("unroll") for (int _i = 0; _i < 2; ++_i) \
;         __builtin_amdgcn_global_load_lds((const unsigned*)((const char*)(gbase) + (size_t)_i * pstep + (voff)[0]), (PG8_LAS unsigned*)(lds + (bufoff) + ldsw + _i * 8192), 16, 0, 0); } } while (0)
; #define PG8_LDA(dst, b, h) do { _Pragma("unroll") for (int m = 0; m < 4; ++m) _Pragma("unroll") for (int k = 0; k < 2; ++k) dst[m][k] = *(const PG8_LAS bf16x8*)(lds + PG8_SA(b, h) + aoff + m * 2048 + k * 1024); } while (0)
; #define PG8_LDB(dst, b, h) do { _Pragma("unroll") for (int n = 0; n < 2; ++n) _Pragma("unroll") for (int k = 0; k < 2; ++k) dst[n][k] = *(const PG8_LAS bf16x8*)(lds + PG8_SB(b, h) + boff + n * 2048 + k * 1024); } while (0)
; #define PG8_MMA(ai, bj, At, Bt) do { __builtin_amdgcn_s_setprio(1); _Pragma("unroll") for (int m = 0; m < 4; ++m) _Pragma("unroll") for (int n = 0; n < 2; ++n) _Pragma("unroll") for (int k = 0; k < 2; ++k) \
;         acc[ai][bj][m][n] = __builtin_amdgcn_mfma_f32_16x16x32_bf16(Bt[n][k], At[m][k], acc[ai][bj][m][n], 0, 0, 0); __builtin_amdgcn_s_setprio(0); } while (0)
; #define PG8_WAIT_V(n) asm volatile("s_waitcnt vmcnt(" #n ")" ::: "memory")
; #define PG8_WAIT_L(n) asm volatile("s_waitcnt lgkmcnt(" #n ")" ::: "memory")
; #define PG8_BAR __builtin_amdgcn_s_barrier()
; #define PG8_SCHED __builtin_amdgcn_sched_barrier(0)
; template <class Epi, class Sched, bool ALIGN_EPI = false, bool SP2 = false, bool ABLK = false>
; __device__ __forceinline__ void gemm_phase(PG8_LAS unsigned char* lds, const Gemm g, const Sched& S, const Epi& E) {
;     ...
;             PG8_WAIT_V(8); PG8_WAIT_L(0); PG8_BAR; PG8_MMA(0, 0, At, B0); PG8_MMA(0, 1, At, B1); PG8_BAR; PG8_SCHED;
;             PG8_LDA(At, 0, 1); PG8_STAGE(PG8_SB(0, 0), b2, voffB); PG8_STAGE(PG8_SB(0, 1), b2 + hstep, voffB); PG8_STAGE(PG8_SA(0, 0), a2, voffA);
;             PG8_WAIT_V(8); PG8_WAIT_L(0); PG8_BAR; PG8_MMA(1, 0, At, B0); PG8_MMA(1, 1, At, B1); PG8_BAR; PG8_SCHED;
;             PG8_LDB(B0, 1, 0); PG8_LDB(B1, 1, 1); PG8_SCHED; PG8_LDA(At, 1, 0); PG8_STAGE(PG8_SA(0, 1), a2 + hstep, voffA);
;             PG8_WAIT_V(8); PG8_WAIT_L(0); PG8_BAR; PG8_MMA(0, 0, At, B0); PG8_MMA(0, 1, At, B1); PG8_BAR; PG8_SCHED;
	s_setprio 1
	s_waitcnt lgkmcnt(0)
	v_mfma_f32_16x16x32_bf16 v[62:65], v[144:147], v[212:215], v[62:65]
	v_mfma_f32_16x16x32_bf16 v[46:49], v[144:147], v[220:223], v[46:49]
	v_mfma_f32_16x16x32_bf16 v[30:33], v[144:147], v[228:231], v[30:33]
	v_mfma_f32_16x16x32_bf16 v[14:17], v[144:147], v[236:239], v[14:17]
	v_mfma_f32_16x16x32_bf16 v[14:17], v[184:187], v[240:243], v[14:17]
	v_mfma_f32_16x16x32_bf16 v[30:33], v[184:187], v[232:235], v[30:33]
	v_mfma_f32_16x16x32_bf16 v[46:49], v[184:187], v[224:227], v[46:49]
	v_mfma_f32_16x16x32_bf16 v[62:65], v[184:187], v[216:219], v[62:65]
	v_mfma_f32_16x16x32_bf16 v[58:61], v[188:191], v[212:215], v[58:61]
	v_mfma_f32_16x16x32_bf16 v[42:45], v[188:191], v[220:223], v[42:45]
	v_mfma_f32_16x16x32_bf16 v[26:29], v[188:191], v[228:231], v[26:29]
	v_mfma_f32_16x16x32_bf16 v[10:13], v[188:191], v[236:239], v[10:13]
	v_mfma_f32_16x16x32_bf16 v[10:13], v[192:195], v[240:243], v[10:13]
	v_mfma_f32_16x16x32_bf16 v[26:29], v[192:195], v[232:235], v[26:29]
	v_mfma_f32_16x16x32_bf16 v[42:45], v[192:195], v[224:227], v[42:45]
	v_mfma_f32_16x16x32_bf16 v[58:61], v[192:195], v[216:219], v[58:61]
	v_mfma_f32_16x16x32_bf16 v[54:57], v[196:199], v[212:215], v[54:57]
	v_mfma_f32_16x16x32_bf16 v[38:41], v[196:199], v[220:223], v[38:41]
	v_mfma_f32_16x16x32_bf16 v[22:25], v[196:199], v[228:231], v[22:25]
	v_mfma_f32_16x16x32_bf16 v[6:9], v[196:199], v[236:239], v[6:9]
	v_mfma_f32_16x16x32_bf16 v[6:9], v[200:203], v[240:243], v[6:9]
	v_mfma_f32_16x16x32_bf16 v[22:25], v[200:203], v[232:235], v[22:25]
	v_mfma_f32_16x16x32_bf16 v[38:41], v[200:203], v[224:227], v[38:41]
	v_mfma_f32_16x16x32_bf16 v[54:57], v[200:203], v[216:219], v[54:57]
	v_mfma_f32_16x16x32_bf16 v[50:53], v[204:207], v[212:215], v[50:53]
	v_mfma_f32_16x16x32_bf16 v[34:37], v[204:207], v[220:223], v[34:37]
	v_mfma_f32_16x16x32_bf16 v[18:21], v[204:207], v[228:231], v[18:21]
	v_mfma_f32_16x16x32_bf16 v[2:5], v[204:207], v[236:239], v[2:5]
	s_barrier
	s_setprio 2
	v_mfma_f32_16x16x32_bf16 v[2:5], v[208:211], v[240:243], v[2:5]
	v_mfma_f32_16x16x32_bf16 v[18:21], v[208:211], v[232:235], v[18:21]
	v_mfma_f32_16x16x32_bf16 v[34:37], v[208:211], v[224:227], v[34:37]
	v_mfma_f32_16x16x32_bf16 v[50:53], v[208:211], v[216:219], v[50:53]
	s_setprio 0
	s_add_i32 s14, 0, 0x18000
	v_add_u32_e32 v133, s14, v148
	s_add_i32 s15, 0, 0x1c000
	ds_read_b128 v[144:147], v133
	ds_read_b128 v[184:187], v133 offset:1024
	ds_read_b128 v[188:191], v133 offset:2048
	ds_read_b128 v[192:195], v133 offset:3072
	v_add_u32_e32 v133, s15, v148
	ds_read_b128 v[196:199], v133
	ds_read_b128 v[200:203], v133 offset:1024
	ds_read_b128 v[204:207], v133 offset:2048
	ds_read_b128 v[208:211], v133 offset:3072
	s_mov_b32 m0, s57
	v_lshl_add_u64 v[246:247], v[244:245], 0, s[24:25]
	ds_read_b128 v[212:215], v168 offset:32768
	ds_read_b128 v[216:219], v168 offset:33792
	ds_read_b128 v[220:223], v168 offset:34816
	ds_read_b128 v[224:227], v168 offset:35840
	ds_read_b128 v[228:231], v168 offset:36864
	ds_read_b128 v[232:235], v168 offset:37888
	ds_read_b128 v[236:239], v168 offset:38912
	ds_read_b128 v[240:243], v168 offset:39936
	global_load_lds_dwordx4 v[246:247], off
	v_lshl_add_u64 v[246:247], v[244:245], 0, s[26:27]
	s_mov_b32 m0, s58
	s_nop 0
	global_load_lds_dwordx4 v[246:247], off
	s_waitcnt vmcnt(8)
	s_waitcnt lgkmcnt(0)
	s_barrier
	s_setprio 1
	s_waitcnt lgkmcnt(0)
	v_mfma_f32_16x16x32_bf16 v[126:129], v[144:147], v[212:215], v[126:129]
	v_mfma_f32_16x16x32_bf16 v[110:113], v[144:147], v[220:223], v[110:113]
	v_mfma_f32_16x16x32_bf16 v[94:97], v[144:147], v[228:231], v[94:97]
	v_mfma_f32_16x16x32_bf16 v[78:81], v[144:147], v[236:239], v[78:81]
	v_mfma_f32_16x16x32_bf16 v[78:81], v[184:187], v[240:243], v[78:81]
	v_mfma_f32_16x16x32_bf16 v[94:97], v[184:187], v[232:235], v[94:97]
	v_mfma_f32_16x16x32_bf16 v[110:113], v[184:187], v[224:227], v[110:113]
	v_mfma_f32_16x16x32_bf16 v[126:129], v[184:187], v[216:219], v[126:129]
	v_mfma_f32_16x16x32_bf16 v[122:125], v[188:191], v[212:215], v[122:125]
	v_mfma_f32_16x16x32_bf16 v[106:109], v[188:191], v[220:223], v[106:109]
	v_mfma_f32_16x16x32_bf16 v[90:93], v[188:191], v[228:231], v[90:93]
	v_mfma_f32_16x16x32_bf16 v[74:77], v[188:191], v[236:239], v[74:77]
	v_mfma_f32_16x16x32_bf16 v[74:77], v[192:195], v[240:243], v[74:77]
	v_mfma_f32_16x16x32_bf16 v[90:93], v[192:195], v[232:235], v[90:93]
	v_mfma_f32_16x16x32_bf16 v[106:109], v[192:195], v[224:227], v[106:109]
	v_mfma_f32_16x16x32_bf16 v[122:125], v[192:195], v[216:219], v[122:125]
	v_mfma_f32_16x16x32_bf16 v[118:121], v[196:199], v[212:215], v[118:121]
	v_mfma_f32_16x16x32_bf16 v[102:105], v[196:199], v[220:223], v[102:105]
	v_mfma_f32_16x16x32_bf16 v[86:89], v[196:199], v[228:231], v[86:89]
	v_mfma_f32_16x16x32_bf16 v[70:73], v[196:199], v[236:239], v[70:73]
	v_mfma_f32_16x16x32_bf16 v[70:73], v[200:203], v[240:243], v[70:73]
	v_mfma_f32_16x16x32_bf16 v[86:89], v[200:203], v[232:235], v[86:89]
	v_mfma_f32_16x16x32_bf16 v[102:105], v[200:203], v[224:227], v[102:105]
	v_mfma_f32_16x16x32_bf16 v[118:121], v[200:203], v[216:219], v[118:121]
	v_mfma_f32_16x16x32_bf16 v[114:117], v[204:207], v[212:215], v[114:117]
	v_mfma_f32_16x16x32_bf16 v[98:101], v[204:207], v[220:223], v[98:101]
	v_mfma_f32_16x16x32_bf16 v[82:85], v[204:207], v[228:231], v[82:85]
	v_mfma_f32_16x16x32_bf16 v[66:69], v[204:207], v[236:239], v[66:69]
	s_barrier
; #define PG8_STAGE(bufoff, gbase, voff) do { if constexpr (!pg8_noload<Epi>::value) { _Pragma("unroll") for (int _i = 0; _i < 2; ++_i) \
;         __builtin_amdgcn_global_load_lds((const unsigned*)((const char*)(gbase) + (size_t)_i * pstep + (voff)[0]), (PG8_LAS unsigned*)(lds + (bufoff) + ldsw + _i * 8192), 16, 0, 0); } } while (0)
; #define PG8_LDA(dst, b, h) do { _Pragma("unroll") for (int m = 0; m < 4; ++m) _Pragma("unroll") for (int k = 0; k < 2; ++k) dst[m][k] = *(const PG8_LAS bf16x8*)(lds + PG8_SA(b, h) + aoff + m * 2048 + k * 1024); } while (0)
; #define PG8_LDB(dst, b, h) do { _Pragma("unroll") for (int n = 0; n < 2; ++n) _Pragma("unroll") for (int k = 0; k < 2; ++k) dst[n][k] = *(const PG8_LAS bf16x8*)(lds + PG8_SB(b, h) + boff + n * 2048 + k * 1024); } while (0)
; #define PG8_MMA(ai, bj, At, Bt) do { __builtin_amdgcn_s_setprio(1); _Pragma("unroll") for (int m = 0; m < 4; ++m) _Pragma("unroll") for (int n = 0; n < 2; ++n) _Pragma("unroll") for (int k = 0; k < 2; ++k) \
;         acc[ai][bj][m][n] = __builtin_amdgcn_mfma_f32_16x16x32_bf16(Bt[n][k], At[m][k], acc[ai][bj][m][n], 0, 0, 0); __builtin_amdgcn_s_setprio(0); } while (0)
; #define PG8_WAIT_V(n) asm volatile("s_waitcnt vmcnt(" #n ")" ::: "memory")
; #define PG8_WAIT_L(n) asm volatile("s_waitcnt lgkmcnt(" #n ")" ::: "memory")
; #define PG8_BAR __builtin_amdgcn_s_barrier()
; #define PG8_SCHED __builtin_amdgcn_sched_barrier(0)
; template <class Epi, class Sched, bool ALIGN_EPI = false, bool SP2 = false, bool ABLK = false>
; __device__ __forceinline__ void gemm_phase(PG8_LAS unsigned char* lds, const Gemm g, const Sched& S, const Epi& E) {
;     ...
;             PG8_WAIT_V(8); PG8_WAIT_L(0); PG8_BAR; PG8_MMA(1, 0, At, B0); PG8_MMA(1, 1, At, B1); PG8_BAR; PG8_SCHED;
;             PG8_LDB(B0, 1, 0); PG8_LDB(B1, 1, 1); PG8_SCHED; PG8_LDA(At, 1, 0); PG8_STAGE(PG8_SA(0, 1), a2 + hstep, voffA);
;             PG8_WAIT_V(8); PG8_WAIT_L(0); PG8_BAR; PG8_MMA(0, 0, At, B0); PG8_MMA(0, 1, At, B1); PG8_BAR; PG8_SCHED;
;             PG8_LDA(At, 1, 1); PG8_STAGE(PG8_SB(1, 0), b3, voffB); PG8_STAGE(PG8_SB(1, 1), b3 + hstep, voffB); PG8_STAGE(PG8_SA(1, 0), a3, voffA);
;             PG8_WAIT_V(8); PG8_WAIT_L(0); PG8_BAR; PG8_MMA(1, 0, At, B0); PG8_MMA(1, 1, At, B1); PG8_BAR; PG8_SCHED;
	s_setprio 2
	v_mfma_f32_16x16x32_bf16 v[66:69], v[208:211], v[240:243], v[66:69]
	v_mfma_f32_16x16x32_bf16 v[82:85], v[208:211], v[232:235], v[82:85]
	v_mfma_f32_16x16x32_bf16 v[98:101], v[208:211], v[224:227], v[98:101]
	v_mfma_f32_16x16x32_bf16 v[114:117], v[208:211], v[216:219], v[114:117]
	s_setprio 0
	s_add_i32 s14, s14, s3
	v_lshl_add_u64 v[246:247], v[180:181], 0, s[38:39]
	s_mov_b32 m0, s14
	ds_read_b128 v[212:215], v168 offset:49152
	ds_read_b128 v[216:219], v168 offset:50176
	ds_read_b128 v[220:223], v168 offset:51200
	ds_read_b128 v[224:227], v168 offset:52224
	ds_read_b128 v[228:231], v168 offset:53248
	ds_read_b128 v[232:235], v168 offset:54272
	ds_read_b128 v[236:239], v168 offset:55296
	ds_read_b128 v[240:243], v168 offset:56320
	global_load_lds_dwordx4 v[246:247], off
	v_lshl_add_u64 v[246:247], v[180:181], 0, s[40:41]
	s_add_i32 m0, s14, 0x2000
	s_add_i32 s14, s15, s3
	global_load_lds_dwordx4 v[246:247], off
	v_lshl_add_u64 v[246:247], v[180:181], 0, s[42:43]
	s_mov_b32 m0, s14
	v_lshl_add_u64 v[180:181], v[180:181], 0, s[44:45]
	global_load_lds_dwordx4 v[246:247], off
	s_add_i32 m0, s14, 0x2000
	s_nop 0
	global_load_lds_dwordx4 v[180:181], off
	v_lshl_add_u64 v[180:181], v[244:245], 0, s[38:39]
	s_mov_b32 m0, s61
	s_nop 0
	global_load_lds_dwordx4 v[180:181], off
	v_lshl_add_u64 v[180:181], v[244:245], 0, s[40:41]
	s_mov_b32 m0, s63
	s_nop 0
	global_load_lds_dwordx4 v[180:181], off
	s_waitcnt vmcnt(8)
	s_waitcnt lgkmcnt(0)
	s_barrier
	s_setprio 1
	s_waitcnt lgkmcnt(0)
	v_mfma_f32_16x16x32_bf16 v[62:65], v[144:147], v[212:215], v[62:65]
	v_mfma_f32_16x16x32_bf16 v[46:49], v[144:147], v[220:223], v[46:49]
	v_mfma_f32_16x16x32_bf16 v[30:33], v[144:147], v[228:231], v[30:33]
	v_mfma_f32_16x16x32_bf16 v[14:17], v[144:147], v[236:239], v[14:17]
	v_mfma_f32_16x16x32_bf16 v[14:17], v[184:187], v[240:243], v[14:17]
	v_mfma_f32_16x16x32_bf16 v[30:33], v[184:187], v[232:235], v[30:33]
	v_mfma_f32_16x16x32_bf16 v[46:49], v[184:187], v[224:227], v[46:49]
	v_mfma_f32_16x16x32_bf16 v[62:65], v[184:187], v[216:219], v[62:65]
	v_mfma_f32_16x16x32_bf16 v[58:61], v[188:191], v[212:215], v[58:61]
	v_mfma_f32_16x16x32_bf16 v[42:45], v[188:191], v[220:223], v[42:45]
	v_mfma_f32_16x16x32_bf16 v[26:29], v[188:191], v[228:231], v[26:29]
	v_mfma_f32_16x16x32_bf16 v[10:13], v[188:191], v[236:239], v[10:13]
	v_mfma_f32_16x16x32_bf16 v[10:13], v[192:195], v[240:243], v[10:13]
	v_mfma_f32_16x16x32_bf16 v[26:29], v[192:195], v[232:235], v[26:29]
	v_mfma_f32_16x16x32_bf16 v[42:45], v[192:195], v[224:227], v[42:45]
	v_mfma_f32_16x16x32_bf16 v[58:61], v[192:195], v[216:219], v[58:61]
	v_mfma_f32_16x16x32_bf16 v[54:57], v[196:199], v[212:215], v[54:57]
	v_mfma_f32_16x16x32_bf16 v[38:41], v[196:199], v[220:223], v[38:41]
	v_mfma_f32_16x16x32_bf16 v[22:25], v[196:199], v[228:231], v[22:25]
	v_mfma_f32_16x16x32_bf16 v[6:9], v[196:199], v[236:239], v[6:9]
	v_mfma_f32_16x16x32_bf16 v[6:9], v[200:203], v[240:243], v[6:9]
	v_mfma_f32_16x16x32_bf16 v[22:25], v[200:203], v[232:235], v[22:25]
	v_mfma_f32_16x16x32_bf16 v[38:41], v[200:203], v[224:227], v[38:41]
	v_mfma_f32_16x16x32_bf16 v[54:57], v[200:203], v[216:219], v[54:57]
	v_mfma_f32_16x16x32_bf16 v[50:53], v[204:207], v[212:215], v[50:53]
	v_mfma_f32_16x16x32_bf16 v[34:37], v[204:207], v[220:223], v[34:37]
	v_mfma_f32_16x16x32_bf16 v[18:21], v[204:207], v[228:231], v[18:21]
	v_mfma_f32_16x16x32_bf16 v[2:5], v[204:207], v[236:239], v[2:5]
	s_barrier
	s_setprio 2
	v_mfma_f32_16x16x32_bf16 v[2:5], v[208:211], v[240:243], v[2:5]
	v_mfma_f32_16x16x32_bf16 v[18:21], v[208:211], v[232:235], v[18:21]
	v_mfma_f32_16x16x32_bf16 v[34:37], v[208:211], v[224:227], v[34:37]
	v_mfma_f32_16x16x32_bf16 v[50:53], v[208:211], v[216:219], v[50:53]
	s_setprio 0
	s_cmp_gt_u32 s59, 29
	s_mov_b32 s59, s30
	s_cbranch_scc1 .LBB0_2131

; #define PG8_STAGE(bufoff, gbase, voff) do { if constexpr (!pg8_noload<Epi>::value) { _Pragma("unroll") for (int _i = 0; _i < 2; ++_i) \
;         __builtin_amdgcn_global_load_lds((const unsigned*)((const char*)(gbase) + (size_t)_i * pstep + (voff)[0]), (PG8_LAS unsigned*)(lds + (bufoff) + ldsw + _i * 8192), 16, 0, 0); } } while (0)
; #define PG8_LDA(dst, b, h) do { _Pragma("unroll") for (int m = 0; m < 4; ++m) _Pragma("unroll") for (int k = 0; k < 2; ++k) dst[m][k] = *(const PG8_LAS bf16x8*)(lds + PG8_SA(b, h) + aoff + m * 2048 + k * 1024); } while (0)
; #define PG8_LDB(dst, b, h) do { _Pragma("unroll") for (int n = 0; n < 2; ++n) _Pragma("unroll") for (int k = 0; k < 2; ++k) dst[n][k] = *(const PG8_LAS bf16x8*)(lds + PG8_SB(b, h) + boff + n * 2048 + k * 1024); } while (0)
; #define PG8_MMA(ai, bj, At, Bt) do { __builtin_amdgcn_s_setprio(1); _Pragma("unroll") for (int m = 0; m < 4; ++m) _Pragma("unroll") for (int n = 0; n < 2; ++n) _Pragma("unroll") for (int k = 0; k < 2; ++k) \
;         acc[ai][bj][m][n] = __builtin_amdgcn_mfma_f32_16x16x32_bf16(Bt[n][k], At[m][k], acc[ai][bj][m][n], 0, 0, 0); __builtin_amdgcn_s_setprio(0); } while (0)
; #define PG8_BAR __builtin_amdgcn_s_barrier()
; template <class Epi, class Sched, bool ALIGN_EPI = false, bool SP2 = false, bool ABLK = false>
; __device__ __forceinline__ void gemm_phase(PG8_LAS unsigned char* lds, const Gemm g, const Sched& S, const Epi& E) {
;     ...
;         for (int t = 0; t < nt; t += 2) {
;             const bool last = (t == nt - 2);
;             const char* a1 = cA + (size_t)(t + 1) * kstep;
;             const char* a2 = last ? nA : cA + (size_t)(t + 2) * kstep; const char* b2 = last ? nB : cB + (size_t)(t + 2) * kstepB;
;             const char* a3 = a2 + kstep; const char* b3 = b2 + kstepB;
;             if (last && has_next) S.a_ready(nxt);
;             if constexpr (SP2) {
;             PG8_LDB(B0, 0, 0); PG8_LDB(B1, 0, 1); PG8_SCHED; PG8_LDA(At, 0, 0); PG8_STAGE(PG8_SA(1, 1), a1 + hstep, voffA);
;             PG8_WAIT_V(8); PG8_WAIT_L(0); PG8_BAR; PG8_MMA(0, 0, At, B0); PG8_MMA(0, 1, At, B1); PG8_BAR; PG8_SCHED;
;             PG8_LDA(At, 0, 1); PG8_STAGE(PG8_SB(0, 0), b2, voffB); PG8_STAGE(PG8_SB(0, 1), b2 + hstep, voffB); PG8_STAGE(PG8_SA(0, 0), a2, voffA);
;             PG8_WAIT_V(8); PG8_WAIT_L(0); PG8_BAR; PG8_MMA(1, 0, At, B0); PG8_MMA(1, 1, At, B1); PG8_BAR; PG8_SCHED;
.LBB0_2399:
	ds_read_b128 v[130:133], v175
	ds_read_b128 v[134:137], v175 offset:1024
	ds_read_b128 v[138:141], v175 offset:2048
	ds_read_b128 v[142:145], v175 offset:3072
	ds_read_b128 v[146:149], v176
	ds_read_b128 v[150:153], v176 offset:1024
	ds_read_b128 v[154:157], v176 offset:2048
	ds_read_b128 v[158:161], v176 offset:3072
	s_add_i32 s55, s53, 2
	s_add_u32 s64, s62, 0xfff00800
	s_addc_u32 s65, s63, -1
	s_cmp_eq_u32 s3, s53
	s_cselect_b32 s65, s57, s65
	s_cselect_b32 s64, s56, s64
	s_cselect_b32 s91, s59, s49
	s_cselect_b32 s90, s58, s11
	v_lshl_add_u64 v[170:171], s[62:63], 0, v[166:167]
	s_add_i32 m0, s61, 0xc000
	ds_read_b128 v[184:187], v177
	ds_read_b128 v[188:191], v177 offset:1024
	ds_read_b128 v[192:195], v177 offset:2048
	ds_read_b128 v[196:199], v177 offset:3072
	ds_read_b128 v[200:203], v177 offset:4096
	ds_read_b128 v[204:207], v177 offset:5120
	ds_read_b128 v[208:211], v177 offset:6144
	ds_read_b128 v[212:215], v177 offset:7168
	global_load_lds_dwordx4 v[170:171], off
	v_lshl_add_u64 v[170:171], v[170:171], 0, s[12:13]
	s_add_i32 m0, s61, 0xe000
	s_nop 0
	global_load_lds_dwordx4 v[170:171], off
	s_waitcnt vmcnt(8)
	s_waitcnt lgkmcnt(0)
	s_barrier
	s_setprio 1
	s_waitcnt lgkmcnt(0)
	v_mfma_f32_16x16x32_bf16 v[126:129], v[130:133], v[184:187], v[126:129]
	v_mfma_f32_16x16x32_bf16 v[110:113], v[130:133], v[192:195], v[110:113]
	v_mfma_f32_16x16x32_bf16 v[94:97], v[130:133], v[200:203], v[94:97]
	v_mfma_f32_16x16x32_bf16 v[78:81], v[130:133], v[208:211], v[78:81]
	v_mfma_f32_16x16x32_bf16 v[78:81], v[134:137], v[212:215], v[78:81]
	v_mfma_f32_16x16x32_bf16 v[94:97], v[134:137], v[204:207], v[94:97]
	v_mfma_f32_16x16x32_bf16 v[110:113], v[134:137], v[196:199], v[110:113]
	v_mfma_f32_16x16x32_bf16 v[126:129], v[134:137], v[188:191], v[126:129]
	v_mfma_f32_16x16x32_bf16 v[122:125], v[138:141], v[184:187], v[122:125]
	v_mfma_f32_16x16x32_bf16 v[106:109], v[138:141], v[192:195], v[106:109]
	v_mfma_f32_16x16x32_bf16 v[90:93], v[138:141], v[200:203], v[90:93]
	v_mfma_f32_16x16x32_bf16 v[74:77], v[138:141], v[208:211], v[74:77]
	v_mfma_f32_16x16x32_bf16 v[74:77], v[142:145], v[212:215], v[74:77]
	v_mfma_f32_16x16x32_bf16 v[90:93], v[142:145], v[204:207], v[90:93]
	v_mfma_f32_16x16x32_bf16 v[106:109], v[142:145], v[196:199], v[106:109]
	v_mfma_f32_16x16x32_bf16 v[122:125], v[142:145], v[188:191], v[122:125]
	v_mfma_f32_16x16x32_bf16 v[118:121], v[146:149], v[184:187], v[118:121]
	v_mfma_f32_16x16x32_bf16 v[102:105], v[146:149], v[192:195], v[102:105]
	v_mfma_f32_16x16x32_bf16 v[86:89], v[146:149], v[200:203], v[86:89]
	v_mfma_f32_16x16x32_bf16 v[70:73], v[146:149], v[208:211], v[70:73]
	v_mfma_f32_16x16x32_bf16 v[70:73], v[150:153], v[212:215], v[70:73]
	v_mfma_f32_16x16x32_bf16 v[86:89], v[150:153], v[204:207], v[86:89]
	v_mfma_f32_16x16x32_bf16 v[102:105], v[150:153], v[196:199], v[102:105]
	v_mfma_f32_16x16x32_bf16 v[118:121], v[150:153], v[188:191], v[118:121]
	v_mfma_f32_16x16x32_bf16 v[114:117], v[154:157], v[184:187], v[114:117]
	v_mfma_f32_16x16x32_bf16 v[98:101], v[154:157], v[192:195], v[98:101]
	v_mfma_f32_16x16x32_bf16 v[82:85], v[154:157], v[200:203], v[82:85]
	v_mfma_f32_16x16x32_bf16 v[66:69], v[154:157], v[208:211], v[66:69]
	s_barrier
	s_setprio 2
	v_mfma_f32_16x16x32_bf16 v[66:69], v[158:161], v[212:215], v[66:69]
	v_mfma_f32_16x16x32_bf16 v[82:85], v[158:161], v[204:207], v[82:85]
	v_mfma_f32_16x16x32_bf16 v[98:101], v[158:161], v[196:199], v[98:101]
	v_mfma_f32_16x16x32_bf16 v[114:117], v[158:161], v[188:191], v[114:117]
	s_setprio 0
	s_add_i32 s53, s80, s69
	v_lshl_add_u64 v[170:171], s[90:91], 0, v[162:163]
	s_mov_b32 m0, s53
	ds_read_b128 v[184:187], v177 offset:16384
	ds_read_b128 v[188:191], v177 offset:17408
	ds_read_b128 v[192:195], v177 offset:18432
	ds_read_b128 v[196:199], v177 offset:19456
	ds_read_b128 v[200:203], v177 offset:20480
	ds_read_b128 v[204:207], v177 offset:21504
	ds_read_b128 v[208:211], v177 offset:22528
	ds_read_b128 v[212:215], v177 offset:23552
	global_load_lds_dwordx4 v[170:171], off
	v_lshl_add_u64 v[216:217], v[170:171], 0, s[12:13]
	s_add_i32 m0, s53, 0x2000
	s_add_i32 s53, s81, s69
	global_load_lds_dwordx4 v[216:217], off
	v_lshl_add_u64 v[216:217], v[170:171], 0, s[14:15]
	s_mov_b32 m0, s53
	s_nop 0
	global_load_lds_dwordx4 v[216:217], off
	v_lshl_add_u64 v[216:217], v[170:171], 0, s[16:17]
	s_add_i32 m0, s53, 0x2000
	s_nop 0
	global_load_lds_dwordx4 v[216:217], off
	v_lshl_add_u64 v[216:217], s[64:65], 0, v[162:163]
	s_mov_b32 m0, s61
	v_lshl_add_u64 v[218:219], v[216:217], 0, s[12:13]
	global_load_lds_dwordx4 v[216:217], off
	s_mov_b32 m0, s70
	s_nop 0
	global_load_lds_dwordx4 v[218:219], off
	s_waitcnt vmcnt(8)
	s_waitcnt lgkmcnt(0)
	s_barrier
; #define PG8_STAGE(bufoff, gbase, voff) do { if constexpr (!pg8_noload<Epi>::value) { _Pragma("unroll") for (int _i = 0; _i < 2; ++_i) \
;         __builtin_amdgcn_global_load_lds((const unsigned*)((const char*)(gbase) + (size_t)_i * pstep + (voff)[0]), (PG8_LAS unsigned*)(lds + (bufoff) + ldsw + _i * 8192), 16, 0, 0); } } while (0)
; #define PG8_LDA(dst, b, h) do { _Pragma("unroll") for (int m = 0; m < 4; ++m) _Pragma("unroll") for (int k = 0; k < 2; ++k) dst[m][k] = *(const PG8_LAS bf16x8*)(lds + PG8_SA(b, h) + aoff + m * 2048 + k * 1024); } while (0)
; #define PG8_LDB(dst, b, h) do { _Pragma("unroll") for (int n = 0; n < 2; ++n) _Pragma("unroll") for (int k = 0; k < 2; ++k) dst[n][k] = *(const PG8_LAS bf16x8*)(lds + PG8_SB(b, h) + boff + n * 2048 + k * 1024); } while (0)
; #define PG8_MMA(ai, bj, At, Bt) do { __builtin_amdgcn_s_setprio(1); _Pragma("unroll") for (int m = 0; m < 4; ++m) _Pragma("unroll") for (int n = 0; n < 2; ++n) _Pragma("unroll") for (int k = 0; k < 2; ++k) \
;         acc[ai][bj][m][n] = __builtin_amdgcn_mfma_f32_16x16x32_bf16(Bt[n][k], At[m][k], acc[ai][bj][m][n], 0, 0, 0); __builtin_amdgcn_s_setprio(0); } while (0)
; #define PG8_WAIT_V(n) asm volatile("s_waitcnt vmcnt(" #n ")" ::: "memory")
; #define PG8_WAIT_L(n) asm volatile("s_waitcnt lgkmcnt(" #n ")" ::: "memory")
; #define PG8_BAR __builtin_amdgcn_s_barrier()
; #define PG8_SCHED __builtin_amdgcn_sched_barrier(0)
; template <class Epi, class Sched, bool ALIGN_EPI = false, bool SP2 = false, bool ABLK = false>
; __device__ __forceinline__ void gemm_phase(PG8_LAS unsigned char* lds, const Gemm g, const Sched& S, const Epi& E) {
;     ...
;             PG8_WAIT_V(8); PG8_WAIT_L(0); PG8_BAR; PG8_MMA(0, 0, At, B0); PG8_MMA(0, 1, At, B1); PG8_BAR; PG8_SCHED;
;             PG8_LDA(At, 0, 1); PG8_STAGE(PG8_SB(0, 0), b2, voffB); PG8_STAGE(PG8_SB(0, 1), b2 + hstep, voffB); PG8_STAGE(PG8_SA(0, 0), a2, voffA);
;             PG8_WAIT_V(8); PG8_WAIT_L(0); PG8_BAR; PG8_MMA(1, 0, At, B0); PG8_MMA(1, 1, At, B1); PG8_BAR; PG8_SCHED;
;             PG8_LDB(B0, 1, 0); PG8_LDB(B1, 1, 1); PG8_SCHED; PG8_LDA(At, 1, 0); PG8_STAGE(PG8_SA(0, 1), a2 + hstep, voffA);
;             PG8_WAIT_V(8); PG8_WAIT_L(0); PG8_BAR; PG8_MMA(0, 0, At, B0); PG8_MMA(0, 1, At, B1); PG8_BAR; PG8_SCHED;
	s_setprio 1
	s_waitcnt lgkmcnt(0)
	v_mfma_f32_16x16x32_bf16 v[62:65], v[130:133], v[184:187], v[62:65]
	v_mfma_f32_16x16x32_bf16 v[46:49], v[130:133], v[192:195], v[46:49]
	v_mfma_f32_16x16x32_bf16 v[30:33], v[130:133], v[200:203], v[30:33]
	v_mfma_f32_16x16x32_bf16 v[14:17], v[130:133], v[208:211], v[14:17]
	v_mfma_f32_16x16x32_bf16 v[14:17], v[134:137], v[212:215], v[14:17]
	v_mfma_f32_16x16x32_bf16 v[30:33], v[134:137], v[204:207], v[30:33]
	v_mfma_f32_16x16x32_bf16 v[46:49], v[134:137], v[196:199], v[46:49]
	v_mfma_f32_16x16x32_bf16 v[62:65], v[134:137], v[188:191], v[62:65]
	v_mfma_f32_16x16x32_bf16 v[58:61], v[138:141], v[184:187], v[58:61]
	v_mfma_f32_16x16x32_bf16 v[42:45], v[138:141], v[192:195], v[42:45]
	v_mfma_f32_16x16x32_bf16 v[26:29], v[138:141], v[200:203], v[26:29]
	v_mfma_f32_16x16x32_bf16 v[10:13], v[138:141], v[208:211], v[10:13]
	v_mfma_f32_16x16x32_bf16 v[10:13], v[142:145], v[212:215], v[10:13]
	v_mfma_f32_16x16x32_bf16 v[26:29], v[142:145], v[204:207], v[26:29]
	v_mfma_f32_16x16x32_bf16 v[42:45], v[142:145], v[196:199], v[42:45]
	v_mfma_f32_16x16x32_bf16 v[58:61], v[142:145], v[188:191], v[58:61]
	v_mfma_f32_16x16x32_bf16 v[54:57], v[146:149], v[184:187], v[54:57]
	v_mfma_f32_16x16x32_bf16 v[38:41], v[146:149], v[192:195], v[38:41]
	v_mfma_f32_16x16x32_bf16 v[22:25], v[146:149], v[200:203], v[22:25]
	v_mfma_f32_16x16x32_bf16 v[6:9], v[146:149], v[208:211], v[6:9]
	v_mfma_f32_16x16x32_bf16 v[6:9], v[150:153], v[212:215], v[6:9]
	v_mfma_f32_16x16x32_bf16 v[22:25], v[150:153], v[204:207], v[22:25]
	v_mfma_f32_16x16x32_bf16 v[38:41], v[150:153], v[196:199], v[38:41]
	v_mfma_f32_16x16x32_bf16 v[54:57], v[150:153], v[188:191], v[54:57]
	v_mfma_f32_16x16x32_bf16 v[50:53], v[154:157], v[184:187], v[50:53]
	v_mfma_f32_16x16x32_bf16 v[34:37], v[154:157], v[192:195], v[34:37]
	v_mfma_f32_16x16x32_bf16 v[18:21], v[154:157], v[200:203], v[18:21]
	v_mfma_f32_16x16x32_bf16 v[2:5], v[154:157], v[208:211], v[2:5]
	s_barrier
	s_setprio 2
	v_mfma_f32_16x16x32_bf16 v[2:5], v[158:161], v[212:215], v[2:5]
	v_mfma_f32_16x16x32_bf16 v[18:21], v[158:161], v[204:207], v[18:21]
	v_mfma_f32_16x16x32_bf16 v[34:37], v[158:161], v[196:199], v[34:37]
	v_mfma_f32_16x16x32_bf16 v[50:53], v[158:161], v[188:191], v[50:53]
	s_setprio 0
	s_add_i32 s53, 0, 0x18000
	s_add_i32 s64, 0, 0x1c000
	v_add_u32_e32 v142, s53, v1
	v_add_u32_e32 v158, s64, v1
	ds_read_b128 v[130:133], v142
	ds_read_b128 v[134:137], v142 offset:1024
	ds_read_b128 v[138:141], v142 offset:2048
	ds_read_b128 v[142:145], v142 offset:3072
	ds_read_b128 v[146:149], v158
	ds_read_b128 v[150:153], v158 offset:1024
	ds_read_b128 v[154:157], v158 offset:2048
	ds_read_b128 v[158:161], v158 offset:3072
	s_mov_b32 m0, s71
	v_lshl_add_u64 v[218:219], v[216:217], 0, s[14:15]
	ds_read_b128 v[184:187], v177 offset:32768
	ds_read_b128 v[188:191], v177 offset:33792
	ds_read_b128 v[192:195], v177 offset:34816
	ds_read_b128 v[196:199], v177 offset:35840
	ds_read_b128 v[200:203], v177 offset:36864
	ds_read_b128 v[204:207], v177 offset:37888
	ds_read_b128 v[208:211], v177 offset:38912
	ds_read_b128 v[212:215], v177 offset:39936
	global_load_lds_dwordx4 v[218:219], off
	v_lshl_add_u64 v[218:219], v[216:217], 0, s[16:17]
	s_mov_b32 m0, s72
	s_nop 0
	global_load_lds_dwordx4 v[218:219], off
	s_waitcnt vmcnt(8)
	s_waitcnt lgkmcnt(0)
	s_barrier
	s_setprio 1
	s_waitcnt lgkmcnt(0)
	v_mfma_f32_16x16x32_bf16 v[126:129], v[130:133], v[184:187], v[126:129]
	v_mfma_f32_16x16x32_bf16 v[110:113], v[130:133], v[192:195], v[110:113]
	v_mfma_f32_16x16x32_bf16 v[94:97], v[130:133], v[200:203], v[94:97]
	v_mfma_f32_16x16x32_bf16 v[78:81], v[130:133], v[208:211], v[78:81]
	v_mfma_f32_16x16x32_bf16 v[78:81], v[134:137], v[212:215], v[78:81]
	v_mfma_f32_16x16x32_bf16 v[94:97], v[134:137], v[204:207], v[94:97]
	v_mfma_f32_16x16x32_bf16 v[110:113], v[134:137], v[196:199], v[110:113]
	v_mfma_f32_16x16x32_bf16 v[126:129], v[134:137], v[188:191], v[126:129]
	v_mfma_f32_16x16x32_bf16 v[122:125], v[138:141], v[184:187], v[122:125]
	v_mfma_f32_16x16x32_bf16 v[106:109], v[138:141], v[192:195], v[106:109]
	v_mfma_f32_16x16x32_bf16 v[90:93], v[138:141], v[200:203], v[90:93]
	v_mfma_f32_16x16x32_bf16 v[74:77], v[138:141], v[208:211], v[74:77]
	v_mfma_f32_16x16x32_bf16 v[74:77], v[142:145], v[212:215], v[74:77]
	v_mfma_f32_16x16x32_bf16 v[90:93], v[142:145], v[204:207], v[90:93]
	v_mfma_f32_16x16x32_bf16 v[106:109], v[142:145], v[196:199], v[106:109]
	v_mfma_f32_16x16x32_bf16 v[122:125], v[142:145], v[188:191], v[122:125]
	v_mfma_f32_16x16x32_bf16 v[118:121], v[146:149], v[184:187], v[118:121]
	v_mfma_f32_16x16x32_bf16 v[102:105], v[146:149], v[192:195], v[102:105]
	v_mfma_f32_16x16x32_bf16 v[86:89], v[146:149], v[200:203], v[86:89]
	v_mfma_f32_16x16x32_bf16 v[70:73], v[146:149], v[208:211], v[70:73]
	v_mfma_f32_16x16x32_bf16 v[70:73], v[150:153], v[212:215], v[70:73]
	v_mfma_f32_16x16x32_bf16 v[86:89], v[150:153], v[204:207], v[86:89]
	v_mfma_f32_16x16x32_bf16 v[102:105], v[150:153], v[196:199], v[102:105]
	v_mfma_f32_16x16x32_bf16 v[118:121], v[150:153], v[188:191], v[118:121]
	v_mfma_f32_16x16x32_bf16 v[114:117], v[154:157], v[184:187], v[114:117]
	v_mfma_f32_16x16x32_bf16 v[98:101], v[154:157], v[192:195], v[98:101]
	v_mfma_f32_16x16x32_bf16 v[82:85], v[154:157], v[200:203], v[82:85]
	v_mfma_f32_16x16x32_bf16 v[66:69], v[154:157], v[208:211], v[66:69]
	s_barrier
; #define PG8_STAGE(bufoff, gbase, voff) do { if constexpr (!pg8_noload<Epi>::value) { _Pragma("unroll") for (int _i = 0; _i < 2; ++_i) \
;         __builtin_amdgcn_global_load_lds((const unsigned*)((const char*)(gbase) + (size_t)_i * pstep + (voff)[0]), (PG8_LAS unsigned*)(lds + (bufoff) + ldsw + _i * 8192), 16, 0, 0); } } while (0)
; #define PG8_LDA(dst, b, h) do { _Pragma("unroll") for (int m = 0; m < 4; ++m) _Pragma("unroll") for (int k = 0; k < 2; ++k) dst[m][k] = *(const PG8_LAS bf16x8*)(lds + PG8_SA(b, h) + aoff + m * 2048 + k * 1024); } while (0)
; #define PG8_LDB(dst, b, h) do { _Pragma("unroll") for (int n = 0; n < 2; ++n) _Pragma("unroll") for (int k = 0; k < 2; ++k) dst[n][k] = *(const PG8_LAS bf16x8*)(lds + PG8_SB(b, h) + boff + n * 2048 + k * 1024); } while (0)
; #define PG8_WAIT_V(n) asm volatile("s_waitcnt vmcnt(" #n ")" ::: "memory")
; #define PG8_WAIT_L(n) asm volatile("s_waitcnt lgkmcnt(" #n ")" ::: "memory")
; #define PG8_BAR __builtin_amdgcn_s_barrier()
; #define PG8_SCHED __builtin_amdgcn_sched_barrier(0)
; template <class Epi, class Sched, bool ALIGN_EPI = false, bool SP2 = false, bool ABLK = false>
; __device__ __forceinline__ void gemm_phase(PG8_LAS unsigned char* lds, const Gemm g, const Sched& S, const Epi& E) {
;     ...
;         for (int t = 0; t < nt; t += 2) {
;             const bool last = (t == nt - 2);
;             const char* a1 = cA + (size_t)(t + 1) * kstep;
;             const char* a2 = last ? nA : cA + (size_t)(t + 2) * kstep; const char* b2 = last ? nB : cB + (size_t)(t + 2) * kstepB;
;             const char* a3 = a2 + kstep; const char* b3 = b2 + kstepB;
;             if (last && has_next) S.a_ready(nxt);
;     ...
;             PG8_WAIT_V(8); PG8_WAIT_L(0); PG8_BAR; PG8_MMA(1, 0, At, B0); PG8_MMA(1, 1, At, B1); PG8_BAR; PG8_SCHED;
;             PG8_LDB(B0, 1, 0); PG8_LDB(B1, 1, 1); PG8_SCHED; PG8_LDA(At, 1, 0); PG8_STAGE(PG8_SA(0, 1), a2 + hstep, voffA);
;             PG8_WAIT_V(8); PG8_WAIT_L(0); PG8_BAR; PG8_MMA(0, 0, At, B0); PG8_MMA(0, 1, At, B1); PG8_BAR; PG8_SCHED;
;             PG8_LDA(At, 1, 1); PG8_STAGE(PG8_SB(1, 0), b3, voffB); PG8_STAGE(PG8_SB(1, 1), b3 + hstep, voffB); PG8_STAGE(PG8_SA(1, 0), a3, voffA);
;             PG8_WAIT_V(8); PG8_WAIT_L(0); PG8_BAR; PG8_MMA(1, 0, At, B0); PG8_MMA(1, 1, At, B1); PG8_BAR; PG8_SCHED;
	s_setprio 2
	v_mfma_f32_16x16x32_bf16 v[66:69], v[158:161], v[212:215], v[66:69]
	v_mfma_f32_16x16x32_bf16 v[82:85], v[158:161], v[204:207], v[82:85]
	v_mfma_f32_16x16x32_bf16 v[98:101], v[158:161], v[196:199], v[98:101]
	v_mfma_f32_16x16x32_bf16 v[114:117], v[158:161], v[188:191], v[114:117]
	s_setprio 0
	s_add_i32 s53, s53, s69
	v_lshl_add_u64 v[218:219], v[170:171], 0, s[24:25]
	s_mov_b32 m0, s53
	ds_read_b128 v[184:187], v177 offset:49152
	ds_read_b128 v[188:191], v177 offset:50176
	ds_read_b128 v[192:195], v177 offset:51200
	ds_read_b128 v[196:199], v177 offset:52224
	ds_read_b128 v[200:203], v177 offset:53248
	ds_read_b128 v[204:207], v177 offset:54272
	ds_read_b128 v[208:211], v177 offset:55296
	ds_read_b128 v[212:215], v177 offset:56320
	global_load_lds_dwordx4 v[218:219], off
	v_lshl_add_u64 v[218:219], v[170:171], 0, s[26:27]
	s_add_i32 m0, s53, 0x2000
	s_add_i32 s53, s64, s69
	global_load_lds_dwordx4 v[218:219], off
	v_lshl_add_u64 v[218:219], v[170:171], 0, s[28:29]
	s_mov_b32 m0, s53
	v_lshl_add_u64 v[170:171], v[170:171], 0, s[30:31]
	global_load_lds_dwordx4 v[218:219], off
	s_add_i32 m0, s53, 0x2000
	s_nop 0
	global_load_lds_dwordx4 v[170:171], off
	v_lshl_add_u64 v[170:171], v[216:217], 0, s[24:25]
	s_mov_b32 m0, s75
	s_nop 0
	global_load_lds_dwordx4 v[170:171], off
	v_lshl_add_u64 v[170:171], v[216:217], 0, s[26:27]
	s_mov_b32 m0, s76
	s_nop 0
	global_load_lds_dwordx4 v[170:171], off
	s_waitcnt vmcnt(8)
	s_waitcnt lgkmcnt(0)
	s_barrier
	s_setprio 1
	s_waitcnt lgkmcnt(0)
	v_mfma_f32_16x16x32_bf16 v[62:65], v[130:133], v[184:187], v[62:65]
	v_mfma_f32_16x16x32_bf16 v[46:49], v[130:133], v[192:195], v[46:49]
	v_mfma_f32_16x16x32_bf16 v[30:33], v[130:133], v[200:203], v[30:33]
	v_mfma_f32_16x16x32_bf16 v[14:17], v[130:133], v[208:211], v[14:17]
	v_mfma_f32_16x16x32_bf16 v[14:17], v[134:137], v[212:215], v[14:17]
	v_mfma_f32_16x16x32_bf16 v[30:33], v[134:137], v[204:207], v[30:33]
	v_mfma_f32_16x16x32_bf16 v[46:49], v[134:137], v[196:199], v[46:49]
	v_mfma_f32_16x16x32_bf16 v[62:65], v[134:137], v[188:191], v[62:65]
	v_mfma_f32_16x16x32_bf16 v[58:61], v[138:141], v[184:187], v[58:61]
	v_mfma_f32_16x16x32_bf16 v[42:45], v[138:141], v[192:195], v[42:45]
	v_mfma_f32_16x16x32_bf16 v[26:29], v[138:141], v[200:203], v[26:29]
	v_mfma_f32_16x16x32_bf16 v[10:13], v[138:141], v[208:211], v[10:13]
	v_mfma_f32_16x16x32_bf16 v[10:13], v[142:145], v[212:215], v[10:13]
	v_mfma_f32_16x16x32_bf16 v[26:29], v[142:145], v[204:207], v[26:29]
	v_mfma_f32_16x16x32_bf16 v[42:45], v[142:145], v[196:199], v[42:45]
	v_mfma_f32_16x16x32_bf16 v[58:61], v[142:145], v[188:191], v[58:61]
	v_mfma_f32_16x16x32_bf16 v[54:57], v[146:149], v[184:187], v[54:57]
	v_mfma_f32_16x16x32_bf16 v[38:41], v[146:149], v[192:195], v[38:41]
	v_mfma_f32_16x16x32_bf16 v[22:25], v[146:149], v[200:203], v[22:25]
	v_mfma_f32_16x16x32_bf16 v[6:9], v[146:149], v[208:211], v[6:9]
	v_mfma_f32_16x16x32_bf16 v[6:9], v[150:153], v[212:215], v[6:9]
	v_mfma_f32_16x16x32_bf16 v[22:25], v[150:153], v[204:207], v[22:25]
	v_mfma_f32_16x16x32_bf16 v[38:41], v[150:153], v[196:199], v[38:41]
	v_mfma_f32_16x16x32_bf16 v[54:57], v[150:153], v[188:191], v[54:57]
	v_mfma_f32_16x16x32_bf16 v[50:53], v[154:157], v[184:187], v[50:53]
	v_mfma_f32_16x16x32_bf16 v[34:37], v[154:157], v[192:195], v[34:37]
	v_mfma_f32_16x16x32_bf16 v[18:21], v[154:157], v[200:203], v[18:21]
	v_mfma_f32_16x16x32_bf16 v[2:5], v[154:157], v[208:211], v[2:5]
	s_barrier
	s_setprio 2
	v_mfma_f32_16x16x32_bf16 v[2:5], v[158:161], v[212:215], v[2:5]
	v_mfma_f32_16x16x32_bf16 v[18:21], v[158:161], v[204:207], v[18:21]
	v_mfma_f32_16x16x32_bf16 v[34:37], v[158:161], v[196:199], v[34:37]
	v_mfma_f32_16x16x32_bf16 v[50:53], v[158:161], v[188:191], v[50:53]
	s_setprio 0
	s_add_u32 s62, s62, 0x1000
	s_addc_u32 s63, s63, 0
	s_add_u32 s11, s11, 0x1000
	s_addc_u32 s49, s49, 0
	s_cmp_ge_i32 s55, s89
	s_mov_b32 s53, s55
	s_cbranch_scc0 .LBB0_2399
	s_and_b64 vcc, exec, s[34:35]
	s_cbranch_vccnz .LBB0_2404
	s_lshl_b32 s11, s2, 8
	s_cmp_gt_i32 s2, 63
	s_mov_b64 s[62:63], -1
	s_cbranch_scc1 .LBB0_2405
